# load-segment waves raise s_setprio while they issue their LDS-DMA loads
# baseline (speedup 1.0000x reference)
; #define PG8_STAGE(bufoff, gbase, voff) do { _Pragma("unroll") for (int _i = 0; _i < 2; ++_i) \
;         __builtin_amdgcn_global_load_lds((const unsigned*)((const char*)(gbase) + (voff)[_i]), (LAS unsigned*)(lds + (bufoff) + ldsw + _i * 8192), 16, 0, 0); } while (0)
; #define PG8_LDA(dst, b, h) do { _Pragma("unroll") for (int m = 0; m < 4; ++m) _Pragma("unroll") for (int k = 0; k < 2; ++k) dst[m][k] = *(const LAS bf16x8*)(lds + PG8_SA(b, h) + aoff + m * 2048 + k * 1024); } while (0)
; #define PG8_LDB(dst, b, h) do { _Pragma("unroll") for (int n = 0; n < 2; ++n) _Pragma("unroll") for (int k = 0; k < 2; ++k) dst[n][k] = *(const LAS bf16x8*)(lds + PG8_SB(b, h) + boff + n * 2048 + k * 1024); } while (0)
; #define PG8_MMA(ai, bj, At, Bt) do { __builtin_amdgcn_s_setprio(1); _Pragma("unroll") for (int m = 0; m < 4; ++m) _Pragma("unroll") for (int n = 0; n < 2; ++n) _Pragma("unroll") for (int k = 0; k < 2; ++k) \
;         acc[ai][bj][m][n] = __builtin_amdgcn_mfma_f32_16x16x32_bf16(Bt[n][k], At[m][k], acc[ai][bj][m][n], 0, 0, 0); __builtin_amdgcn_s_setprio(0); } while (0)
; template <class Epi, class Sched>
; __device__ __forceinline__ void gemm_phase(LAS unsigned char* lds, const Gemm g, const Sched& S, const Epi& E) {
;     ...
;         const bool has_next = S.next(ui + 1, nxt);
;         const char* nA = has_next ? (const char*)g.A + (size_t)nxt.pm * tstepA + (size_t)nxt.pn * g.a_pn_off * 2 : cA; const char* nB = has_next ? (const char*)g.Bt + (size_t)nxt.pn * tstepB : cB;
;         for (int t = 0; t < nt; t += 2) {
;             const bool last = (t == nt - 2);
;             const char* a1 = cA + (size_t)(t + 1) * kstep;
;             const char* a2 = last ? nA : cA + (size_t)(t + 2) * kstep; const char* b2 = last ? nB : cB + (size_t)(t + 2) * kstep;
;             const char* a3 = a2 + kstep; const char* b3 = b2 + kstep;
;             PG8_LDB(B0, 0, 0); PG8_LDB(B1, 0, 1); PG8_SCHED; PG8_LDA(At, 0, 0); PG8_STAGE(PG8_SA(1, 1), a1 + hstepA, voffA);
;             PG8_WAIT_V(8); PG8_WAIT_L(0); PG8_BAR; PG8_MMA(0, 0, At, B0); PG8_MMA(0, 1, At, B1); PG8_BAR; PG8_SCHED;
;             PG8_LDA(At, 0, 1); PG8_STAGE(PG8_SB(0, 0), b2, voffB); PG8_STAGE(PG8_SB(0, 1), b2 + hstepB, voffB); PG8_STAGE(PG8_SA(0, 0), a2, voffA);
;             PG8_WAIT_V(8); PG8_WAIT_L(0); PG8_BAR; PG8_MMA(1, 0, At, B0); PG8_MMA(1, 1, At, B1); PG8_BAR; PG8_SCHED;
.LBB0_231:
	s_ashr_i32 s83, s82, 31
	s_lshl_b64 s[36:37], s[82:83], 19
	s_add_u32 s84, s4, s36
	s_addc_u32 s85, s5, s37
	s_and_b64 s[36:37], s[70:71], exec
	s_cselect_b32 s43, s85, s19
	s_cselect_b32 s48, s84, s18
	s_ashr_i32 s81, s80, 31
	s_lshl_b64 s[36:37], s[80:81], 19
	v_readlane_b32 s12, v248, 5
	s_add_u32 s36, s12, s36
	v_readlane_b32 s12, v248, 6
	s_addc_u32 s37, s12, s37
	s_and_b64 s[86:87], s[70:71], exec
	s_cselect_b32 s49, s37, s21
	s_cselect_b32 s53, s36, s20
	s_add_u32 s18, s18, 0x40080
	s_addc_u32 s19, s19, 0
	s_add_u32 s54, s20, 0x100
	s_addc_u32 s81, s21, 0
	s_mov_b32 s83, -2
	s_add_u32 s20, s18, 0xfffc0080
	s_addc_u32 s21, s19, -1
	s_add_i32 s88, 0, 0x10000
	s_cmp_eq_u32 s83, 12
	s_cselect_b32 s21, s43, s21
	s_cselect_b32 s20, s48, s20
	s_cselect_b32 s87, s49, s81
	s_cselect_b32 s86, s53, s54
	s_add_i32 s90, 0, 0x14000
	s_add_u32 s100, s20, 0x80
	s_addc_u32 s101, s21, 0
	s_add_i32 m0, s9, 0xc000
	s_nop 0
	s_setprio 2
	global_load_lds_dwordx4 v170, s[18:19]
	s_add_i32 m0, s9, 0xe000
	s_nop 0
	global_load_lds_dwordx4 v190, s[18:19]
	s_setprio 0
	ds_read_b128 v[130:133], v246
	ds_read_b128 v[134:137], v246 offset:1024
	ds_read_b128 v[138:141], v246 offset:2048
	ds_read_b128 v[142:145], v246 offset:3072
	ds_read_b128 v[146:149], v246 offset:16384
	ds_read_b128 v[150:153], v246 offset:17408
	ds_read_b128 v[154:157], v246 offset:18432
	ds_read_b128 v[158:161], v246 offset:19456
	ds_read_b128 v[162:165], v222
	ds_read_b128 v[166:169], v222 offset:1024
	ds_read_b128 v[194:197], v222 offset:2048
	ds_read_b128 v[198:201], v222 offset:3072
	ds_read_b128 v[202:205], v222 offset:4096
	ds_read_b128 v[224:227], v222 offset:5120
	ds_read_b128 v[228:231], v222 offset:6144
	ds_read_b128 v[232:235], v222 offset:7168
	s_waitcnt vmcnt(8)
	s_waitcnt lgkmcnt(0)
	s_barrier
	s_waitcnt lgkmcnt(0)
	v_mfma_f32_16x16x32_bf16 v[126:129], v[130:133], v[162:165], 0
	v_mfma_f32_16x16x32_bf16 v[118:121], v[138:141], v[162:165], 0
	v_mfma_f32_16x16x32_bf16 v[110:113], v[130:133], v[194:197], 0
	v_mfma_f32_16x16x32_bf16 v[102:105], v[138:141], v[194:197], 0
	v_mfma_f32_16x16x32_bf16 v[94:97], v[130:133], v[202:205], 0
	v_mfma_f32_16x16x32_bf16 v[86:89], v[138:141], v[202:205], 0
	v_mfma_f32_16x16x32_bf16 v[78:81], v[130:133], v[228:231], 0
	v_mfma_f32_16x16x32_bf16 v[70:73], v[138:141], v[228:231], 0
	v_mfma_f32_16x16x32_bf16 v[126:129], v[134:137], v[166:169], v[126:129]
	v_mfma_f32_16x16x32_bf16 v[118:121], v[142:145], v[166:169], v[118:121]
	v_mfma_f32_16x16x32_bf16 v[110:113], v[134:137], v[198:201], v[110:113]
	v_mfma_f32_16x16x32_bf16 v[102:105], v[142:145], v[198:201], v[102:105]
	v_mfma_f32_16x16x32_bf16 v[94:97], v[134:137], v[224:227], v[94:97]
	v_mfma_f32_16x16x32_bf16 v[86:89], v[142:145], v[224:227], v[86:89]
	v_mfma_f32_16x16x32_bf16 v[78:81], v[134:137], v[232:235], v[78:81]
	v_mfma_f32_16x16x32_bf16 v[70:73], v[142:145], v[232:235], v[70:73]
	v_mfma_f32_16x16x32_bf16 v[122:125], v[146:149], v[162:165], 0
	v_mfma_f32_16x16x32_bf16 v[114:117], v[154:157], v[162:165], 0
	v_mfma_f32_16x16x32_bf16 v[106:109], v[146:149], v[194:197], 0
	v_mfma_f32_16x16x32_bf16 v[98:101], v[154:157], v[194:197], 0
	v_mfma_f32_16x16x32_bf16 v[90:93], v[146:149], v[202:205], 0
	v_mfma_f32_16x16x32_bf16 v[82:85], v[154:157], v[202:205], 0
	v_mfma_f32_16x16x32_bf16 v[74:77], v[146:149], v[228:231], 0
	v_mfma_f32_16x16x32_bf16 v[66:69], v[154:157], v[228:231], 0
	v_mfma_f32_16x16x32_bf16 v[122:125], v[150:153], v[166:169], v[122:125]
	v_mfma_f32_16x16x32_bf16 v[114:117], v[158:161], v[166:169], v[114:117]
	v_mfma_f32_16x16x32_bf16 v[106:109], v[150:153], v[198:201], v[106:109]
	v_mfma_f32_16x16x32_bf16 v[98:101], v[158:161], v[198:201], v[98:101]
	v_mfma_f32_16x16x32_bf16 v[90:93], v[150:153], v[224:227], v[90:93]
	v_mfma_f32_16x16x32_bf16 v[82:85], v[158:161], v[224:227], v[82:85]
	v_mfma_f32_16x16x32_bf16 v[74:77], v[150:153], v[232:235], v[74:77]
	v_mfma_f32_16x16x32_bf16 v[66:69], v[158:161], v[232:235], v[66:69]
	s_barrier
	s_add_i32 s88, s88, s8
	s_mov_b32 m0, s88
	s_nop 0
	s_setprio 2
	global_load_lds_dwordx4 v172, s[86:87]
	s_add_i32 m0, s88, 0x2000
	s_add_u32 s88, s86, 0x40000
	s_addc_u32 s89, s87, 0
	s_add_i32 s90, s90, s8
	global_load_lds_dwordx4 v192, s[86:87]
	s_mov_b32 m0, s90
	s_nop 0
	global_load_lds_dwordx4 v172, s[88:89]
	s_add_i32 m0, s90, 0x2000
	s_nop 0
	global_load_lds_dwordx4 v192, s[88:89]
	s_mov_b32 m0, s9
	s_nop 0
	global_load_lds_dwordx4 v170, s[20:21]
	s_mov_b32 m0, s28
	s_nop 0
	global_load_lds_dwordx4 v190, s[20:21]
	s_setprio 0
	ds_read_b128 v[162:165], v222 offset:16384
	ds_read_b128 v[166:169], v222 offset:17408
	ds_read_b128 v[194:197], v222 offset:18432
	ds_read_b128 v[198:201], v222 offset:19456
	ds_read_b128 v[202:205], v222 offset:20480
	ds_read_b128 v[224:227], v222 offset:21504
	ds_read_b128 v[228:231], v222 offset:22528
	ds_read_b128 v[232:235], v222 offset:23552
	s_waitcnt vmcnt(8)
	s_waitcnt lgkmcnt(0)
	s_barrier
; #define PG8_STAGE(bufoff, gbase, voff) do { _Pragma("unroll") for (int _i = 0; _i < 2; ++_i) \
;         __builtin_amdgcn_global_load_lds((const unsigned*)((const char*)(gbase) + (voff)[_i]), (LAS unsigned*)(lds + (bufoff) + ldsw + _i * 8192), 16, 0, 0); } while (0)
; #define PG8_LDA(dst, b, h) do { _Pragma("unroll") for (int m = 0; m < 4; ++m) _Pragma("unroll") for (int k = 0; k < 2; ++k) dst[m][k] = *(const LAS bf16x8*)(lds + PG8_SA(b, h) + aoff + m * 2048 + k * 1024); } while (0)
; #define PG8_LDB(dst, b, h) do { _Pragma("unroll") for (int n = 0; n < 2; ++n) _Pragma("unroll") for (int k = 0; k < 2; ++k) dst[n][k] = *(const LAS bf16x8*)(lds + PG8_SB(b, h) + boff + n * 2048 + k * 1024); } while (0)
; #define PG8_MMA(ai, bj, At, Bt) do { __builtin_amdgcn_s_setprio(1); _Pragma("unroll") for (int m = 0; m < 4; ++m) _Pragma("unroll") for (int n = 0; n < 2; ++n) _Pragma("unroll") for (int k = 0; k < 2; ++k) \
;         acc[ai][bj][m][n] = __builtin_amdgcn_mfma_f32_16x16x32_bf16(Bt[n][k], At[m][k], acc[ai][bj][m][n], 0, 0, 0); __builtin_amdgcn_s_setprio(0); } while (0)
; #define PG8_WAIT_V(n) asm volatile("s_waitcnt vmcnt(" #n ")" ::: "memory")
; #define PG8_WAIT_L(n) asm volatile("s_waitcnt lgkmcnt(" #n ")" ::: "memory")
; #define PG8_BAR __builtin_amdgcn_s_barrier()
; #define PG8_SCHED __builtin_amdgcn_sched_barrier(0)
; template <class Epi, class Sched>
; __device__ __forceinline__ void gemm_phase(LAS unsigned char* lds, const Gemm g, const Sched& S, const Epi& E) {
;     ...
;             PG8_WAIT_V(8); PG8_WAIT_L(0); PG8_BAR; PG8_MMA(1, 0, At, B0); PG8_MMA(1, 1, At, B1); PG8_BAR; PG8_SCHED;
;             PG8_LDB(B0, 1, 0); PG8_LDB(B1, 1, 1); PG8_SCHED; PG8_LDA(At, 1, 0); PG8_STAGE(PG8_SA(0, 1), a2 + hstepA, voffA);
;             PG8_WAIT_V(8); PG8_WAIT_L(0); PG8_BAR; PG8_MMA(0, 0, At, B0); PG8_MMA(0, 1, At, B1); PG8_BAR; PG8_SCHED;
	s_waitcnt lgkmcnt(0)
	v_mfma_f32_16x16x32_bf16 v[62:65], v[130:133], v[162:165], 0
	v_mfma_f32_16x16x32_bf16 v[54:57], v[138:141], v[162:165], 0
	v_mfma_f32_16x16x32_bf16 v[46:49], v[130:133], v[194:197], 0
	v_mfma_f32_16x16x32_bf16 v[38:41], v[138:141], v[194:197], 0
	v_mfma_f32_16x16x32_bf16 v[30:33], v[130:133], v[202:205], 0
	v_mfma_f32_16x16x32_bf16 v[22:25], v[138:141], v[202:205], 0
	v_mfma_f32_16x16x32_bf16 v[14:17], v[130:133], v[228:231], 0
	v_mfma_f32_16x16x32_bf16 v[6:9], v[138:141], v[228:231], 0
	v_mfma_f32_16x16x32_bf16 v[62:65], v[134:137], v[166:169], v[62:65]
	v_mfma_f32_16x16x32_bf16 v[54:57], v[142:145], v[166:169], v[54:57]
	v_mfma_f32_16x16x32_bf16 v[46:49], v[134:137], v[198:201], v[46:49]
	v_mfma_f32_16x16x32_bf16 v[38:41], v[142:145], v[198:201], v[38:41]
	v_mfma_f32_16x16x32_bf16 v[30:33], v[134:137], v[224:227], v[30:33]
	v_mfma_f32_16x16x32_bf16 v[22:25], v[142:145], v[224:227], v[22:25]
	v_mfma_f32_16x16x32_bf16 v[14:17], v[134:137], v[232:235], v[14:17]
	v_mfma_f32_16x16x32_bf16 v[6:9], v[142:145], v[232:235], v[6:9]
	v_mfma_f32_16x16x32_bf16 v[58:61], v[146:149], v[162:165], 0
	v_mfma_f32_16x16x32_bf16 v[50:53], v[154:157], v[162:165], 0
	v_mfma_f32_16x16x32_bf16 v[42:45], v[146:149], v[194:197], 0
	v_mfma_f32_16x16x32_bf16 v[34:37], v[154:157], v[194:197], 0
	v_mfma_f32_16x16x32_bf16 v[26:29], v[146:149], v[202:205], 0
	v_mfma_f32_16x16x32_bf16 v[18:21], v[154:157], v[202:205], 0
	v_mfma_f32_16x16x32_bf16 v[10:13], v[146:149], v[228:231], 0
	v_mfma_f32_16x16x32_bf16 v[2:5], v[154:157], v[228:231], 0
	v_mfma_f32_16x16x32_bf16 v[58:61], v[150:153], v[166:169], v[58:61]
	v_mfma_f32_16x16x32_bf16 v[50:53], v[158:161], v[166:169], v[50:53]
	v_mfma_f32_16x16x32_bf16 v[42:45], v[150:153], v[198:201], v[42:45]
	v_mfma_f32_16x16x32_bf16 v[34:37], v[158:161], v[198:201], v[34:37]
	v_mfma_f32_16x16x32_bf16 v[26:29], v[150:153], v[224:227], v[26:29]
	v_mfma_f32_16x16x32_bf16 v[18:21], v[158:161], v[224:227], v[18:21]
	v_mfma_f32_16x16x32_bf16 v[10:13], v[150:153], v[232:235], v[10:13]
	v_mfma_f32_16x16x32_bf16 v[2:5], v[158:161], v[232:235], v[2:5]
	s_barrier
	s_add_i32 s88, 0, 0x18000
	s_add_i32 s89, 0, 0x1c000
	s_add_u32 s20, s20, 0x40000
	s_addc_u32 s21, s21, 0
	s_mov_b32 m0, s29
	s_nop 0
	s_setprio 2
	global_load_lds_dwordx4 v170, s[20:21]
	s_mov_b32 m0, s30
	s_nop 0
	global_load_lds_dwordx4 v190, s[20:21]
	s_setprio 0
	ds_read_b128 v[130:133], v246 offset:32768
	ds_read_b128 v[134:137], v246 offset:33792
	ds_read_b128 v[138:141], v246 offset:34816
	ds_read_b128 v[142:145], v246 offset:35840
	ds_read_b128 v[146:149], v246 offset:49152
	ds_read_b128 v[150:153], v246 offset:50176
	ds_read_b128 v[154:157], v246 offset:51200
	ds_read_b128 v[158:161], v246 offset:52224
	ds_read_b128 v[162:165], v222 offset:32768
	ds_read_b128 v[166:169], v222 offset:33792
	ds_read_b128 v[194:197], v222 offset:34816
	ds_read_b128 v[198:201], v222 offset:35840
	ds_read_b128 v[202:205], v222 offset:36864
	ds_read_b128 v[224:227], v222 offset:37888
	ds_read_b128 v[228:231], v222 offset:38912
	ds_read_b128 v[232:235], v222 offset:39936
	s_waitcnt vmcnt(8)
	s_waitcnt lgkmcnt(0)
	s_barrier
	s_waitcnt lgkmcnt(0)
	v_mfma_f32_16x16x32_bf16 v[126:129], v[130:133], v[162:165], v[126:129]
	v_mfma_f32_16x16x32_bf16 v[118:121], v[138:141], v[162:165], v[118:121]
	v_mfma_f32_16x16x32_bf16 v[110:113], v[130:133], v[194:197], v[110:113]
	v_mfma_f32_16x16x32_bf16 v[102:105], v[138:141], v[194:197], v[102:105]
	v_mfma_f32_16x16x32_bf16 v[94:97], v[130:133], v[202:205], v[94:97]
	v_mfma_f32_16x16x32_bf16 v[86:89], v[138:141], v[202:205], v[86:89]
	v_mfma_f32_16x16x32_bf16 v[78:81], v[130:133], v[228:231], v[78:81]
	v_mfma_f32_16x16x32_bf16 v[70:73], v[138:141], v[228:231], v[70:73]
	v_mfma_f32_16x16x32_bf16 v[126:129], v[134:137], v[166:169], v[126:129]
	v_mfma_f32_16x16x32_bf16 v[118:121], v[142:145], v[166:169], v[118:121]
	v_mfma_f32_16x16x32_bf16 v[110:113], v[134:137], v[198:201], v[110:113]
	v_mfma_f32_16x16x32_bf16 v[102:105], v[142:145], v[198:201], v[102:105]
	v_mfma_f32_16x16x32_bf16 v[94:97], v[134:137], v[224:227], v[94:97]
	v_mfma_f32_16x16x32_bf16 v[86:89], v[142:145], v[224:227], v[86:89]
	v_mfma_f32_16x16x32_bf16 v[78:81], v[134:137], v[232:235], v[78:81]
	v_mfma_f32_16x16x32_bf16 v[70:73], v[142:145], v[232:235], v[70:73]
	v_mfma_f32_16x16x32_bf16 v[122:125], v[146:149], v[162:165], v[122:125]
	v_mfma_f32_16x16x32_bf16 v[114:117], v[154:157], v[162:165], v[114:117]
	v_mfma_f32_16x16x32_bf16 v[106:109], v[146:149], v[194:197], v[106:109]
	v_mfma_f32_16x16x32_bf16 v[98:101], v[154:157], v[194:197], v[98:101]
	v_mfma_f32_16x16x32_bf16 v[90:93], v[146:149], v[202:205], v[90:93]
	v_mfma_f32_16x16x32_bf16 v[82:85], v[154:157], v[202:205], v[82:85]
	v_mfma_f32_16x16x32_bf16 v[74:77], v[146:149], v[228:231], v[74:77]
	v_mfma_f32_16x16x32_bf16 v[66:69], v[154:157], v[228:231], v[66:69]
	v_mfma_f32_16x16x32_bf16 v[122:125], v[150:153], v[166:169], v[122:125]
	v_mfma_f32_16x16x32_bf16 v[114:117], v[158:161], v[166:169], v[114:117]
	v_mfma_f32_16x16x32_bf16 v[106:109], v[150:153], v[198:201], v[106:109]
	v_mfma_f32_16x16x32_bf16 v[98:101], v[158:161], v[198:201], v[98:101]
	v_mfma_f32_16x16x32_bf16 v[90:93], v[150:153], v[224:227], v[90:93]
	v_mfma_f32_16x16x32_bf16 v[82:85], v[158:161], v[224:227], v[82:85]
	v_mfma_f32_16x16x32_bf16 v[74:77], v[150:153], v[232:235], v[74:77]
	v_mfma_f32_16x16x32_bf16 v[66:69], v[158:161], v[232:235], v[66:69]
	s_barrier
; #define PG8_STAGE(bufoff, gbase, voff) do { _Pragma("unroll") for (int _i = 0; _i < 2; ++_i) \
;         __builtin_amdgcn_global_load_lds((const unsigned*)((const char*)(gbase) + (voff)[_i]), (LAS unsigned*)(lds + (bufoff) + ldsw + _i * 8192), 16, 0, 0); } while (0)
; #define PG8_LDA(dst, b, h) do { _Pragma("unroll") for (int m = 0; m < 4; ++m) _Pragma("unroll") for (int k = 0; k < 2; ++k) dst[m][k] = *(const LAS bf16x8*)(lds + PG8_SA(b, h) + aoff + m * 2048 + k * 1024); } while (0)
; #define PG8_LDB(dst, b, h) do { _Pragma("unroll") for (int n = 0; n < 2; ++n) _Pragma("unroll") for (int k = 0; k < 2; ++k) dst[n][k] = *(const LAS bf16x8*)(lds + PG8_SB(b, h) + boff + n * 2048 + k * 1024); } while (0)
; #define PG8_MMA(ai, bj, At, Bt) do { __builtin_amdgcn_s_setprio(1); _Pragma("unroll") for (int m = 0; m < 4; ++m) _Pragma("unroll") for (int n = 0; n < 2; ++n) _Pragma("unroll") for (int k = 0; k < 2; ++k) \
;         acc[ai][bj][m][n] = __builtin_amdgcn_mfma_f32_16x16x32_bf16(Bt[n][k], At[m][k], acc[ai][bj][m][n], 0, 0, 0); __builtin_amdgcn_s_setprio(0); } while (0)
; #define PG8_WAIT_V(n) asm volatile("s_waitcnt vmcnt(" #n ")" ::: "memory")
; #define PG8_WAIT_L(n) asm volatile("s_waitcnt lgkmcnt(" #n ")" ::: "memory")
; #define PG8_BAR __builtin_amdgcn_s_barrier()
; #define PG8_SCHED __builtin_amdgcn_sched_barrier(0)
; template <class Epi, class Sched>
; __device__ __forceinline__ void gemm_phase(LAS unsigned char* lds, const Gemm g, const Sched& S, const Epi& E) {
;     ...
;         for (int t = 0; t < nt; t += 2) {
;             const bool last = (t == nt - 2);
;             const char* a1 = cA + (size_t)(t + 1) * kstep;
;             const char* a2 = last ? nA : cA + (size_t)(t + 2) * kstep; const char* b2 = last ? nB : cB + (size_t)(t + 2) * kstep;
;             const char* a3 = a2 + kstep; const char* b3 = b2 + kstep;
;             PG8_LDB(B0, 0, 0); PG8_LDB(B1, 0, 1); PG8_SCHED; PG8_LDA(At, 0, 0); PG8_STAGE(PG8_SA(1, 1), a1 + hstepA, voffA);
;             PG8_WAIT_V(8); PG8_WAIT_L(0); PG8_BAR; PG8_MMA(0, 0, At, B0); PG8_MMA(0, 1, At, B1); PG8_BAR; PG8_SCHED;
;     ...
;             PG8_LDA(At, 1, 1); PG8_STAGE(PG8_SB(1, 0), b3, voffB); PG8_STAGE(PG8_SB(1, 1), b3 + hstepB, voffB); PG8_STAGE(PG8_SA(1, 0), a3, voffA);
;             PG8_WAIT_V(8); PG8_WAIT_L(0); PG8_BAR; PG8_MMA(1, 0, At, B0); PG8_MMA(1, 1, At, B1); PG8_BAR; PG8_SCHED;
	s_add_i32 s20, s8, 0x18000
	s_add_u32 s88, s86, 0x80
	s_addc_u32 s89, s87, 0
	s_mov_b32 m0, s20
	s_nop 0
	s_setprio 2
	global_load_lds_dwordx4 v172, s[88:89]
	s_add_i32 m0, s20, 0x2000
	s_add_u32 s20, s86, 0x40080
	s_addc_u32 s21, s87, 0
	s_add_i32 s12, s8, 0x1c000
	global_load_lds_dwordx4 v192, s[88:89]
	s_mov_b32 m0, s12
	s_nop 0
	global_load_lds_dwordx4 v172, s[20:21]
	s_add_i32 m0, s12, 0x2000
	s_nop 0
	global_load_lds_dwordx4 v192, s[20:21]
	s_mov_b32 m0, s31
	s_nop 0
	global_load_lds_dwordx4 v170, s[100:101]
	s_mov_b32 m0, s34
	s_nop 0
	global_load_lds_dwordx4 v190, s[100:101]
	s_setprio 0
	ds_read_b128 v[162:165], v222 offset:49152
	ds_read_b128 v[166:169], v222 offset:50176
	ds_read_b128 v[194:197], v222 offset:51200
	ds_read_b128 v[198:201], v222 offset:52224
	ds_read_b128 v[202:205], v222 offset:53248
	ds_read_b128 v[224:227], v222 offset:54272
	ds_read_b128 v[228:231], v222 offset:55296
	ds_read_b128 v[232:235], v222 offset:56320
	s_waitcnt vmcnt(8)
	s_waitcnt lgkmcnt(0)
	s_barrier
	s_waitcnt lgkmcnt(0)
	v_mfma_f32_16x16x32_bf16 v[62:65], v[130:133], v[162:165], v[62:65]
	v_mfma_f32_16x16x32_bf16 v[54:57], v[138:141], v[162:165], v[54:57]
	v_mfma_f32_16x16x32_bf16 v[46:49], v[130:133], v[194:197], v[46:49]
	v_mfma_f32_16x16x32_bf16 v[38:41], v[138:141], v[194:197], v[38:41]
	v_mfma_f32_16x16x32_bf16 v[30:33], v[130:133], v[202:205], v[30:33]
	v_mfma_f32_16x16x32_bf16 v[22:25], v[138:141], v[202:205], v[22:25]
	v_mfma_f32_16x16x32_bf16 v[14:17], v[130:133], v[228:231], v[14:17]
	v_mfma_f32_16x16x32_bf16 v[6:9], v[138:141], v[228:231], v[6:9]
	v_mfma_f32_16x16x32_bf16 v[62:65], v[134:137], v[166:169], v[62:65]
	v_mfma_f32_16x16x32_bf16 v[54:57], v[142:145], v[166:169], v[54:57]
	v_mfma_f32_16x16x32_bf16 v[46:49], v[134:137], v[198:201], v[46:49]
	v_mfma_f32_16x16x32_bf16 v[38:41], v[142:145], v[198:201], v[38:41]
	v_mfma_f32_16x16x32_bf16 v[30:33], v[134:137], v[224:227], v[30:33]
	v_mfma_f32_16x16x32_bf16 v[22:25], v[142:145], v[224:227], v[22:25]
	v_mfma_f32_16x16x32_bf16 v[14:17], v[134:137], v[232:235], v[14:17]
	v_mfma_f32_16x16x32_bf16 v[6:9], v[142:145], v[232:235], v[6:9]
	v_mfma_f32_16x16x32_bf16 v[58:61], v[146:149], v[162:165], v[58:61]
	v_mfma_f32_16x16x32_bf16 v[50:53], v[154:157], v[162:165], v[50:53]
	v_mfma_f32_16x16x32_bf16 v[42:45], v[146:149], v[194:197], v[42:45]
	v_mfma_f32_16x16x32_bf16 v[34:37], v[154:157], v[194:197], v[34:37]
	v_mfma_f32_16x16x32_bf16 v[26:29], v[146:149], v[202:205], v[26:29]
	v_mfma_f32_16x16x32_bf16 v[18:21], v[154:157], v[202:205], v[18:21]
	v_mfma_f32_16x16x32_bf16 v[10:13], v[146:149], v[228:231], v[10:13]
	v_mfma_f32_16x16x32_bf16 v[2:5], v[154:157], v[228:231], v[2:5]
	v_mfma_f32_16x16x32_bf16 v[58:61], v[150:153], v[166:169], v[58:61]
	v_mfma_f32_16x16x32_bf16 v[50:53], v[158:161], v[166:169], v[50:53]
	v_mfma_f32_16x16x32_bf16 v[42:45], v[150:153], v[198:201], v[42:45]
	v_mfma_f32_16x16x32_bf16 v[34:37], v[158:161], v[198:201], v[34:37]
	v_mfma_f32_16x16x32_bf16 v[26:29], v[150:153], v[224:227], v[26:29]
	v_mfma_f32_16x16x32_bf16 v[18:21], v[158:161], v[224:227], v[18:21]
	v_mfma_f32_16x16x32_bf16 v[10:13], v[150:153], v[232:235], v[10:13]
	v_mfma_f32_16x16x32_bf16 v[2:5], v[158:161], v[232:235], v[2:5]
	s_barrier
	s_add_i32 s83, s83, 2
	s_add_u32 s18, s18, 0x100
	s_addc_u32 s19, s19, 0
	s_add_u32 s54, s54, 0x100
	s_addc_u32 s81, s81, 0
	s_cmp_gt_u32 s83, 13
.LBB0_232:
	s_add_u32 s20, s18, 0xfffc0080
	s_addc_u32 s21, s19, -1
	s_add_i32 s88, 0, 0x10000
	s_cmp_eq_u32 s83, 12
	s_cselect_b32 s21, s43, s21
	s_cselect_b32 s20, s48, s20
	s_cselect_b32 s87, s49, s81
	s_cselect_b32 s86, s53, s54
	s_add_i32 s90, 0, 0x14000
	s_add_u32 s100, s20, 0x80
	s_addc_u32 s101, s21, 0
	s_add_i32 m0, s9, 0xc000
	s_nop 0
	s_setprio 2
	global_load_lds_dwordx4 v170, s[18:19]
	s_add_i32 m0, s9, 0xe000
	s_nop 0
	global_load_lds_dwordx4 v190, s[18:19]
	s_setprio 0
	ds_read_b128 v[130:133], v246
	ds_read_b128 v[134:137], v246 offset:1024
	ds_read_b128 v[138:141], v246 offset:2048
	ds_read_b128 v[142:145], v246 offset:3072
	ds_read_b128 v[146:149], v246 offset:16384
	ds_read_b128 v[150:153], v246 offset:17408
	ds_read_b128 v[154:157], v246 offset:18432
	ds_read_b128 v[158:161], v246 offset:19456
	ds_read_b128 v[162:165], v222
	ds_read_b128 v[166:169], v222 offset:1024
	ds_read_b128 v[194:197], v222 offset:2048
	ds_read_b128 v[198:201], v222 offset:3072
	ds_read_b128 v[202:205], v222 offset:4096
	ds_read_b128 v[224:227], v222 offset:5120
	ds_read_b128 v[228:231], v222 offset:6144
	ds_read_b128 v[232:235], v222 offset:7168
	s_waitcnt vmcnt(8)
	s_waitcnt lgkmcnt(0)
	s_barrier
; #define PG8_STAGE(bufoff, gbase, voff) do { _Pragma("unroll") for (int _i = 0; _i < 2; ++_i) \
;         __builtin_amdgcn_global_load_lds((const unsigned*)((const char*)(gbase) + (voff)[_i]), (LAS unsigned*)(lds + (bufoff) + ldsw + _i * 8192), 16, 0, 0); } while (0)
; #define PG8_LDA(dst, b, h) do { _Pragma("unroll") for (int m = 0; m < 4; ++m) _Pragma("unroll") for (int k = 0; k < 2; ++k) dst[m][k] = *(const LAS bf16x8*)(lds + PG8_SA(b, h) + aoff + m * 2048 + k * 1024); } while (0)
; #define PG8_MMA(ai, bj, At, Bt) do { __builtin_amdgcn_s_setprio(1); _Pragma("unroll") for (int m = 0; m < 4; ++m) _Pragma("unroll") for (int n = 0; n < 2; ++n) _Pragma("unroll") for (int k = 0; k < 2; ++k) \
;         acc[ai][bj][m][n] = __builtin_amdgcn_mfma_f32_16x16x32_bf16(Bt[n][k], At[m][k], acc[ai][bj][m][n], 0, 0, 0); __builtin_amdgcn_s_setprio(0); } while (0)
; #define PG8_WAIT_V(n) asm volatile("s_waitcnt vmcnt(" #n ")" ::: "memory")
; #define PG8_WAIT_L(n) asm volatile("s_waitcnt lgkmcnt(" #n ")" ::: "memory")
; #define PG8_BAR __builtin_amdgcn_s_barrier()
; #define PG8_SCHED __builtin_amdgcn_sched_barrier(0)
; template <class Epi, class Sched>
; __device__ __forceinline__ void gemm_phase(LAS unsigned char* lds, const Gemm g, const Sched& S, const Epi& E) {
;     ...
;             PG8_WAIT_V(8); PG8_WAIT_L(0); PG8_BAR; PG8_MMA(0, 0, At, B0); PG8_MMA(0, 1, At, B1); PG8_BAR; PG8_SCHED;
;             PG8_LDA(At, 0, 1); PG8_STAGE(PG8_SB(0, 0), b2, voffB); PG8_STAGE(PG8_SB(0, 1), b2 + hstepB, voffB); PG8_STAGE(PG8_SA(0, 0), a2, voffA);
;             PG8_WAIT_V(8); PG8_WAIT_L(0); PG8_BAR; PG8_MMA(1, 0, At, B0); PG8_MMA(1, 1, At, B1); PG8_BAR; PG8_SCHED;
	s_waitcnt lgkmcnt(0)
	v_mfma_f32_16x16x32_bf16 v[126:129], v[130:133], v[162:165], v[126:129]
	v_mfma_f32_16x16x32_bf16 v[118:121], v[138:141], v[162:165], v[118:121]
	v_mfma_f32_16x16x32_bf16 v[110:113], v[130:133], v[194:197], v[110:113]
	v_mfma_f32_16x16x32_bf16 v[102:105], v[138:141], v[194:197], v[102:105]
	v_mfma_f32_16x16x32_bf16 v[94:97], v[130:133], v[202:205], v[94:97]
	v_mfma_f32_16x16x32_bf16 v[86:89], v[138:141], v[202:205], v[86:89]
	v_mfma_f32_16x16x32_bf16 v[78:81], v[130:133], v[228:231], v[78:81]
	v_mfma_f32_16x16x32_bf16 v[70:73], v[138:141], v[228:231], v[70:73]
	v_mfma_f32_16x16x32_bf16 v[126:129], v[134:137], v[166:169], v[126:129]
	v_mfma_f32_16x16x32_bf16 v[118:121], v[142:145], v[166:169], v[118:121]
	v_mfma_f32_16x16x32_bf16 v[110:113], v[134:137], v[198:201], v[110:113]
	v_mfma_f32_16x16x32_bf16 v[102:105], v[142:145], v[198:201], v[102:105]
	v_mfma_f32_16x16x32_bf16 v[94:97], v[134:137], v[224:227], v[94:97]
	v_mfma_f32_16x16x32_bf16 v[86:89], v[142:145], v[224:227], v[86:89]
	v_mfma_f32_16x16x32_bf16 v[78:81], v[134:137], v[232:235], v[78:81]
	v_mfma_f32_16x16x32_bf16 v[70:73], v[142:145], v[232:235], v[70:73]
	v_mfma_f32_16x16x32_bf16 v[122:125], v[146:149], v[162:165], v[122:125]
	v_mfma_f32_16x16x32_bf16 v[114:117], v[154:157], v[162:165], v[114:117]
	v_mfma_f32_16x16x32_bf16 v[106:109], v[146:149], v[194:197], v[106:109]
	v_mfma_f32_16x16x32_bf16 v[98:101], v[154:157], v[194:197], v[98:101]
	v_mfma_f32_16x16x32_bf16 v[90:93], v[146:149], v[202:205], v[90:93]
	v_mfma_f32_16x16x32_bf16 v[82:85], v[154:157], v[202:205], v[82:85]
	v_mfma_f32_16x16x32_bf16 v[74:77], v[146:149], v[228:231], v[74:77]
	v_mfma_f32_16x16x32_bf16 v[66:69], v[154:157], v[228:231], v[66:69]
	v_mfma_f32_16x16x32_bf16 v[122:125], v[150:153], v[166:169], v[122:125]
	v_mfma_f32_16x16x32_bf16 v[114:117], v[158:161], v[166:169], v[114:117]
	v_mfma_f32_16x16x32_bf16 v[106:109], v[150:153], v[198:201], v[106:109]
	v_mfma_f32_16x16x32_bf16 v[98:101], v[158:161], v[198:201], v[98:101]
	v_mfma_f32_16x16x32_bf16 v[90:93], v[150:153], v[224:227], v[90:93]
	v_mfma_f32_16x16x32_bf16 v[82:85], v[158:161], v[224:227], v[82:85]
	v_mfma_f32_16x16x32_bf16 v[74:77], v[150:153], v[232:235], v[74:77]
	v_mfma_f32_16x16x32_bf16 v[66:69], v[158:161], v[232:235], v[66:69]
	s_barrier
	s_add_i32 s88, s88, s8
	s_mov_b32 m0, s88
	s_nop 0
	s_setprio 2
	global_load_lds_dwordx4 v172, s[86:87]
	s_add_i32 m0, s88, 0x2000
	s_add_u32 s88, s86, 0x40000
	s_addc_u32 s89, s87, 0
	s_add_i32 s90, s90, s8
	global_load_lds_dwordx4 v192, s[86:87]
	s_mov_b32 m0, s90
	s_nop 0
	global_load_lds_dwordx4 v172, s[88:89]
	s_add_i32 m0, s90, 0x2000
	s_nop 0
	global_load_lds_dwordx4 v192, s[88:89]
	s_mov_b32 m0, s9
	s_nop 0
	global_load_lds_dwordx4 v170, s[20:21]
	s_mov_b32 m0, s28
	s_nop 0
	global_load_lds_dwordx4 v190, s[20:21]
	s_setprio 0
	ds_read_b128 v[162:165], v222 offset:16384
	ds_read_b128 v[166:169], v222 offset:17408
	ds_read_b128 v[194:197], v222 offset:18432
	ds_read_b128 v[198:201], v222 offset:19456
	ds_read_b128 v[202:205], v222 offset:20480
	ds_read_b128 v[224:227], v222 offset:21504
	ds_read_b128 v[228:231], v222 offset:22528
	ds_read_b128 v[232:235], v222 offset:23552
	s_waitcnt vmcnt(8)
	s_waitcnt lgkmcnt(0)
	s_barrier
	s_waitcnt lgkmcnt(0)
	v_mfma_f32_16x16x32_bf16 v[62:65], v[130:133], v[162:165], v[62:65]
	v_mfma_f32_16x16x32_bf16 v[54:57], v[138:141], v[162:165], v[54:57]
	v_mfma_f32_16x16x32_bf16 v[46:49], v[130:133], v[194:197], v[46:49]
	v_mfma_f32_16x16x32_bf16 v[38:41], v[138:141], v[194:197], v[38:41]
	v_mfma_f32_16x16x32_bf16 v[30:33], v[130:133], v[202:205], v[30:33]
	v_mfma_f32_16x16x32_bf16 v[22:25], v[138:141], v[202:205], v[22:25]
	v_mfma_f32_16x16x32_bf16 v[14:17], v[130:133], v[228:231], v[14:17]
	v_mfma_f32_16x16x32_bf16 v[6:9], v[138:141], v[228:231], v[6:9]
	v_mfma_f32_16x16x32_bf16 v[62:65], v[134:137], v[166:169], v[62:65]
	v_mfma_f32_16x16x32_bf16 v[54:57], v[142:145], v[166:169], v[54:57]
	v_mfma_f32_16x16x32_bf16 v[46:49], v[134:137], v[198:201], v[46:49]
	v_mfma_f32_16x16x32_bf16 v[38:41], v[142:145], v[198:201], v[38:41]
	v_mfma_f32_16x16x32_bf16 v[30:33], v[134:137], v[224:227], v[30:33]
	v_mfma_f32_16x16x32_bf16 v[22:25], v[142:145], v[224:227], v[22:25]
	v_mfma_f32_16x16x32_bf16 v[14:17], v[134:137], v[232:235], v[14:17]
	v_mfma_f32_16x16x32_bf16 v[6:9], v[142:145], v[232:235], v[6:9]
	v_mfma_f32_16x16x32_bf16 v[58:61], v[146:149], v[162:165], v[58:61]
	v_mfma_f32_16x16x32_bf16 v[50:53], v[154:157], v[162:165], v[50:53]
	v_mfma_f32_16x16x32_bf16 v[42:45], v[146:149], v[194:197], v[42:45]
	v_mfma_f32_16x16x32_bf16 v[34:37], v[154:157], v[194:197], v[34:37]
	v_mfma_f32_16x16x32_bf16 v[26:29], v[146:149], v[202:205], v[26:29]
	v_mfma_f32_16x16x32_bf16 v[18:21], v[154:157], v[202:205], v[18:21]
	v_mfma_f32_16x16x32_bf16 v[10:13], v[146:149], v[228:231], v[10:13]
	v_mfma_f32_16x16x32_bf16 v[2:5], v[154:157], v[228:231], v[2:5]
	v_mfma_f32_16x16x32_bf16 v[58:61], v[150:153], v[166:169], v[58:61]
	v_mfma_f32_16x16x32_bf16 v[50:53], v[158:161], v[166:169], v[50:53]
	v_mfma_f32_16x16x32_bf16 v[42:45], v[150:153], v[198:201], v[42:45]
	v_mfma_f32_16x16x32_bf16 v[34:37], v[158:161], v[198:201], v[34:37]
	v_mfma_f32_16x16x32_bf16 v[26:29], v[150:153], v[224:227], v[26:29]
	v_mfma_f32_16x16x32_bf16 v[18:21], v[158:161], v[224:227], v[18:21]
	v_mfma_f32_16x16x32_bf16 v[10:13], v[150:153], v[232:235], v[10:13]
	v_mfma_f32_16x16x32_bf16 v[2:5], v[158:161], v[232:235], v[2:5]
	s_barrier
; #define PG8_STAGE(bufoff, gbase, voff) do { _Pragma("unroll") for (int _i = 0; _i < 2; ++_i) \
;         __builtin_amdgcn_global_load_lds((const unsigned*)((const char*)(gbase) + (voff)[_i]), (LAS unsigned*)(lds + (bufoff) + ldsw + _i * 8192), 16, 0, 0); } while (0)
; #define PG8_LDA(dst, b, h) do { _Pragma("unroll") for (int m = 0; m < 4; ++m) _Pragma("unroll") for (int k = 0; k < 2; ++k) dst[m][k] = *(const LAS bf16x8*)(lds + PG8_SA(b, h) + aoff + m * 2048 + k * 1024); } while (0)
; #define PG8_LDB(dst, b, h) do { _Pragma("unroll") for (int n = 0; n < 2; ++n) _Pragma("unroll") for (int k = 0; k < 2; ++k) dst[n][k] = *(const LAS bf16x8*)(lds + PG8_SB(b, h) + boff + n * 2048 + k * 1024); } while (0)
; #define PG8_MMA(ai, bj, At, Bt) do { __builtin_amdgcn_s_setprio(1); _Pragma("unroll") for (int m = 0; m < 4; ++m) _Pragma("unroll") for (int n = 0; n < 2; ++n) _Pragma("unroll") for (int k = 0; k < 2; ++k) \
;         acc[ai][bj][m][n] = __builtin_amdgcn_mfma_f32_16x16x32_bf16(Bt[n][k], At[m][k], acc[ai][bj][m][n], 0, 0, 0); __builtin_amdgcn_s_setprio(0); } while (0)
; #define PG8_WAIT_V(n) asm volatile("s_waitcnt vmcnt(" #n ")" ::: "memory")
; #define PG8_WAIT_L(n) asm volatile("s_waitcnt lgkmcnt(" #n ")" ::: "memory")
; #define PG8_BAR __builtin_amdgcn_s_barrier()
; #define PG8_SCHED __builtin_amdgcn_sched_barrier(0)
; template <class Epi, class Sched>
; __device__ __forceinline__ void gemm_phase(LAS unsigned char* lds, const Gemm g, const Sched& S, const Epi& E) {
;     ...
;             PG8_LDB(B0, 1, 0); PG8_LDB(B1, 1, 1); PG8_SCHED; PG8_LDA(At, 1, 0); PG8_STAGE(PG8_SA(0, 1), a2 + hstepA, voffA);
;             PG8_WAIT_V(8); PG8_WAIT_L(0); PG8_BAR; PG8_MMA(0, 0, At, B0); PG8_MMA(0, 1, At, B1); PG8_BAR; PG8_SCHED;
;             PG8_LDA(At, 1, 1); PG8_STAGE(PG8_SB(1, 0), b3, voffB); PG8_STAGE(PG8_SB(1, 1), b3 + hstepB, voffB); PG8_STAGE(PG8_SA(1, 0), a3, voffA);
;             PG8_WAIT_V(8); PG8_WAIT_L(0); PG8_BAR; PG8_MMA(1, 0, At, B0); PG8_MMA(1, 1, At, B1); PG8_BAR; PG8_SCHED;
;         }
;         if (wr == 0) PG8_BAR;
	s_add_i32 s88, 0, 0x18000
	s_add_i32 s89, 0, 0x1c000
	s_add_u32 s20, s20, 0x40000
	s_addc_u32 s21, s21, 0
	s_mov_b32 m0, s29
	s_nop 0
	s_setprio 2
	global_load_lds_dwordx4 v170, s[20:21]
	s_mov_b32 m0, s30
	s_nop 0
	global_load_lds_dwordx4 v190, s[20:21]
	s_setprio 0
	ds_read_b128 v[130:133], v246 offset:32768
	ds_read_b128 v[134:137], v246 offset:33792
	ds_read_b128 v[138:141], v246 offset:34816
	ds_read_b128 v[142:145], v246 offset:35840
	ds_read_b128 v[146:149], v246 offset:49152
	ds_read_b128 v[150:153], v246 offset:50176
	ds_read_b128 v[154:157], v246 offset:51200
	ds_read_b128 v[158:161], v246 offset:52224
	ds_read_b128 v[162:165], v222 offset:32768
	ds_read_b128 v[166:169], v222 offset:33792
	ds_read_b128 v[194:197], v222 offset:34816
	ds_read_b128 v[198:201], v222 offset:35840
	ds_read_b128 v[202:205], v222 offset:36864
	ds_read_b128 v[224:227], v222 offset:37888
	ds_read_b128 v[228:231], v222 offset:38912
	ds_read_b128 v[232:235], v222 offset:39936
	s_waitcnt vmcnt(8)
	s_waitcnt lgkmcnt(0)
	s_barrier
	s_waitcnt lgkmcnt(0)
	v_mfma_f32_16x16x32_bf16 v[126:129], v[130:133], v[162:165], v[126:129]
	v_mfma_f32_16x16x32_bf16 v[118:121], v[138:141], v[162:165], v[118:121]
	v_mfma_f32_16x16x32_bf16 v[110:113], v[130:133], v[194:197], v[110:113]
	v_mfma_f32_16x16x32_bf16 v[102:105], v[138:141], v[194:197], v[102:105]
	v_mfma_f32_16x16x32_bf16 v[94:97], v[130:133], v[202:205], v[94:97]
	v_mfma_f32_16x16x32_bf16 v[86:89], v[138:141], v[202:205], v[86:89]
	v_mfma_f32_16x16x32_bf16 v[78:81], v[130:133], v[228:231], v[78:81]
	v_mfma_f32_16x16x32_bf16 v[70:73], v[138:141], v[228:231], v[70:73]
	v_mfma_f32_16x16x32_bf16 v[126:129], v[134:137], v[166:169], v[126:129]
	v_mfma_f32_16x16x32_bf16 v[118:121], v[142:145], v[166:169], v[118:121]
	v_mfma_f32_16x16x32_bf16 v[110:113], v[134:137], v[198:201], v[110:113]
	v_mfma_f32_16x16x32_bf16 v[102:105], v[142:145], v[198:201], v[102:105]
	v_mfma_f32_16x16x32_bf16 v[94:97], v[134:137], v[224:227], v[94:97]
	v_mfma_f32_16x16x32_bf16 v[86:89], v[142:145], v[224:227], v[86:89]
	v_mfma_f32_16x16x32_bf16 v[78:81], v[134:137], v[232:235], v[78:81]
	v_mfma_f32_16x16x32_bf16 v[70:73], v[142:145], v[232:235], v[70:73]
	v_mfma_f32_16x16x32_bf16 v[122:125], v[146:149], v[162:165], v[122:125]
	v_mfma_f32_16x16x32_bf16 v[114:117], v[154:157], v[162:165], v[114:117]
	v_mfma_f32_16x16x32_bf16 v[106:109], v[146:149], v[194:197], v[106:109]
	v_mfma_f32_16x16x32_bf16 v[98:101], v[154:157], v[194:197], v[98:101]
	v_mfma_f32_16x16x32_bf16 v[90:93], v[146:149], v[202:205], v[90:93]
	v_mfma_f32_16x16x32_bf16 v[82:85], v[154:157], v[202:205], v[82:85]
	v_mfma_f32_16x16x32_bf16 v[74:77], v[146:149], v[228:231], v[74:77]
	v_mfma_f32_16x16x32_bf16 v[66:69], v[154:157], v[228:231], v[66:69]
	v_mfma_f32_16x16x32_bf16 v[122:125], v[150:153], v[166:169], v[122:125]
	v_mfma_f32_16x16x32_bf16 v[114:117], v[158:161], v[166:169], v[114:117]
	v_mfma_f32_16x16x32_bf16 v[106:109], v[150:153], v[198:201], v[106:109]
	v_mfma_f32_16x16x32_bf16 v[98:101], v[158:161], v[198:201], v[98:101]
	v_mfma_f32_16x16x32_bf16 v[90:93], v[150:153], v[224:227], v[90:93]
	v_mfma_f32_16x16x32_bf16 v[82:85], v[158:161], v[224:227], v[82:85]
	v_mfma_f32_16x16x32_bf16 v[74:77], v[150:153], v[232:235], v[74:77]
	v_mfma_f32_16x16x32_bf16 v[66:69], v[158:161], v[232:235], v[66:69]
	s_barrier
	s_add_i32 s20, s8, 0x18000
	s_add_u32 s88, s86, 0x80
	s_addc_u32 s89, s87, 0
	s_mov_b32 m0, s20
	s_nop 0
	s_setprio 2
	global_load_lds_dwordx4 v172, s[88:89]
	s_add_i32 m0, s20, 0x2000
	s_add_u32 s20, s86, 0x40080
	s_addc_u32 s21, s87, 0
	s_add_i32 s12, s8, 0x1c000
	global_load_lds_dwordx4 v192, s[88:89]
	s_mov_b32 m0, s12
	s_nop 0
	global_load_lds_dwordx4 v172, s[20:21]
	s_add_i32 m0, s12, 0x2000
	s_nop 0
	global_load_lds_dwordx4 v192, s[20:21]
	s_mov_b32 m0, s31
	s_nop 0
	global_load_lds_dwordx4 v170, s[100:101]
	s_mov_b32 m0, s34
	s_nop 0
	global_load_lds_dwordx4 v190, s[100:101]
	s_setprio 0
	ds_read_b128 v[162:165], v222 offset:49152
	ds_read_b128 v[166:169], v222 offset:50176
	ds_read_b128 v[194:197], v222 offset:51200
	ds_read_b128 v[198:201], v222 offset:52224
	ds_read_b128 v[202:205], v222 offset:53248
	ds_read_b128 v[224:227], v222 offset:54272
	ds_read_b128 v[228:231], v222 offset:55296
	ds_read_b128 v[232:235], v222 offset:56320
	s_waitcnt vmcnt(8)
	s_waitcnt lgkmcnt(0)
	s_barrier
	s_waitcnt lgkmcnt(0)
	v_mfma_f32_16x16x32_bf16 v[62:65], v[130:133], v[162:165], v[62:65]
	v_mfma_f32_16x16x32_bf16 v[54:57], v[138:141], v[162:165], v[54:57]
	v_mfma_f32_16x16x32_bf16 v[46:49], v[130:133], v[194:197], v[46:49]
	v_mfma_f32_16x16x32_bf16 v[38:41], v[138:141], v[194:197], v[38:41]
	v_mfma_f32_16x16x32_bf16 v[30:33], v[130:133], v[202:205], v[30:33]
	v_mfma_f32_16x16x32_bf16 v[22:25], v[138:141], v[202:205], v[22:25]
	v_mfma_f32_16x16x32_bf16 v[14:17], v[130:133], v[228:231], v[14:17]
	v_mfma_f32_16x16x32_bf16 v[6:9], v[138:141], v[228:231], v[6:9]
	v_mfma_f32_16x16x32_bf16 v[62:65], v[134:137], v[166:169], v[62:65]
	v_mfma_f32_16x16x32_bf16 v[54:57], v[142:145], v[166:169], v[54:57]
	v_mfma_f32_16x16x32_bf16 v[46:49], v[134:137], v[198:201], v[46:49]
	v_mfma_f32_16x16x32_bf16 v[38:41], v[142:145], v[198:201], v[38:41]
	v_mfma_f32_16x16x32_bf16 v[30:33], v[134:137], v[224:227], v[30:33]
	v_mfma_f32_16x16x32_bf16 v[22:25], v[142:145], v[224:227], v[22:25]
	v_mfma_f32_16x16x32_bf16 v[14:17], v[134:137], v[232:235], v[14:17]
	v_mfma_f32_16x16x32_bf16 v[6:9], v[142:145], v[232:235], v[6:9]
	v_mfma_f32_16x16x32_bf16 v[58:61], v[146:149], v[162:165], v[58:61]
	v_mfma_f32_16x16x32_bf16 v[50:53], v[154:157], v[162:165], v[50:53]
	v_mfma_f32_16x16x32_bf16 v[42:45], v[146:149], v[194:197], v[42:45]
	v_mfma_f32_16x16x32_bf16 v[34:37], v[154:157], v[194:197], v[34:37]
	v_mfma_f32_16x16x32_bf16 v[26:29], v[146:149], v[202:205], v[26:29]
	v_mfma_f32_16x16x32_bf16 v[18:21], v[154:157], v[202:205], v[18:21]
	v_mfma_f32_16x16x32_bf16 v[10:13], v[146:149], v[228:231], v[10:13]
	v_mfma_f32_16x16x32_bf16 v[2:5], v[154:157], v[228:231], v[2:5]
	v_mfma_f32_16x16x32_bf16 v[58:61], v[150:153], v[166:169], v[58:61]
	v_mfma_f32_16x16x32_bf16 v[50:53], v[158:161], v[166:169], v[50:53]
	v_mfma_f32_16x16x32_bf16 v[42:45], v[150:153], v[198:201], v[42:45]
	v_mfma_f32_16x16x32_bf16 v[34:37], v[158:161], v[198:201], v[34:37]
	v_mfma_f32_16x16x32_bf16 v[26:29], v[150:153], v[224:227], v[26:29]
	v_mfma_f32_16x16x32_bf16 v[18:21], v[158:161], v[224:227], v[18:21]
	v_mfma_f32_16x16x32_bf16 v[10:13], v[150:153], v[232:235], v[10:13]
	v_mfma_f32_16x16x32_bf16 v[2:5], v[158:161], v[232:235], v[2:5]
	s_barrier
	s_add_i32 s83, s83, 2
	s_add_u32 s18, s18, 0x100
	s_addc_u32 s19, s19, 0
	s_add_u32 s54, s54, 0x100
	s_addc_u32 s81, s81, 0
	s_cmp_gt_u32 s83, 13
	s_cbranch_scc0 .LBB0_232
	s_and_b64 vcc, exec, s[72:73]
	s_cbranch_vccz .LBB0_235
	s_barrier

; #define PG8_STAGE(bufoff, gbase, voff) do { _Pragma("unroll") for (int _i = 0; _i < 2; ++_i) \
;         __builtin_amdgcn_global_load_lds((const unsigned*)((const char*)(gbase) + (voff)[_i]), (LAS unsigned*)(lds + (bufoff) + ldsw + _i * 8192), 16, 0, 0); } while (0)
; #define PG8_LDA(dst, b, h) do { _Pragma("unroll") for (int m = 0; m < 4; ++m) _Pragma("unroll") for (int k = 0; k < 2; ++k) dst[m][k] = *(const LAS bf16x8*)(lds + PG8_SA(b, h) + aoff + m * 2048 + k * 1024); } while (0)
; #define PG8_LDB(dst, b, h) do { _Pragma("unroll") for (int n = 0; n < 2; ++n) _Pragma("unroll") for (int k = 0; k < 2; ++k) dst[n][k] = *(const LAS bf16x8*)(lds + PG8_SB(b, h) + boff + n * 2048 + k * 1024); } while (0)
; #define PG8_MMA(ai, bj, At, Bt) do { __builtin_amdgcn_s_setprio(1); _Pragma("unroll") for (int m = 0; m < 4; ++m) _Pragma("unroll") for (int n = 0; n < 2; ++n) _Pragma("unroll") for (int k = 0; k < 2; ++k) \
;         acc[ai][bj][m][n] = __builtin_amdgcn_mfma_f32_16x16x32_bf16(Bt[n][k], At[m][k], acc[ai][bj][m][n], 0, 0, 0); __builtin_amdgcn_s_setprio(0); } while (0)
; template <class Epi, class Sched>
; __device__ __forceinline__ void gemm_phase(LAS unsigned char* lds, const Gemm g, const Sched& S, const Epi& E) {
;     ...
;         const bool has_next = S.next(ui + 1, nxt);
;         const char* nA = has_next ? (const char*)g.A + (size_t)nxt.pm * tstepA + (size_t)nxt.pn * g.a_pn_off * 2 : cA; const char* nB = has_next ? (const char*)g.Bt + (size_t)nxt.pn * tstepB : cB;
;         for (int t = 0; t < nt; t += 2) {
;             const bool last = (t == nt - 2);
;             const char* a1 = cA + (size_t)(t + 1) * kstep;
;             const char* a2 = last ? nA : cA + (size_t)(t + 2) * kstep; const char* b2 = last ? nB : cB + (size_t)(t + 2) * kstep;
;             const char* a3 = a2 + kstep; const char* b3 = b2 + kstep;
;             PG8_LDB(B0, 0, 0); PG8_LDB(B1, 0, 1); PG8_SCHED; PG8_LDA(At, 0, 0); PG8_STAGE(PG8_SA(1, 1), a1 + hstepA, voffA);
;             PG8_WAIT_V(8); PG8_WAIT_L(0); PG8_BAR; PG8_MMA(0, 0, At, B0); PG8_MMA(0, 1, At, B1); PG8_BAR; PG8_SCHED;
;             PG8_LDA(At, 0, 1); PG8_STAGE(PG8_SB(0, 0), b2, voffB); PG8_STAGE(PG8_SB(0, 1), b2 + hstepB, voffB); PG8_STAGE(PG8_SA(0, 0), a2, voffA);
;             PG8_WAIT_V(8); PG8_WAIT_L(0); PG8_BAR; PG8_MMA(1, 0, At, B0); PG8_MMA(1, 1, At, B1); PG8_BAR; PG8_SCHED;
.LBB0_348:
	s_ashr_i32 s71, s70, 31
	s_lshl_b64 s[48:49], s[70:71], 19
	s_add_u32 s72, s4, s48
	s_addc_u32 s73, s5, s49
	s_and_b64 s[48:49], s[66:67], exec
	s_cselect_b32 s48, s73, s19
	s_cselect_b32 s49, s72, s18
	s_ashr_i32 s69, s68, 31
	s_lshl_b64 s[74:75], s[68:69], 19
	v_readlane_b32 s12, v248, 13
	s_add_u32 s74, s12, s74
	v_readlane_b32 s12, v248, 14
	s_addc_u32 s75, s12, s75
	s_and_b64 s[76:77], s[66:67], exec
	s_cselect_b32 s53, s75, s21
	s_cselect_b32 s54, s74, s20
	s_add_u32 s18, s18, 0x40080
	s_addc_u32 s19, s19, 0
	s_add_u32 s69, s20, 0x100
	s_addc_u32 s71, s21, 0
	s_mov_b32 s78, -2
	s_waitcnt vmcnt(0)
	v_add_u32_e32 v255, 0x10000, v139
	s_add_u32 s20, s18, 0xfffc0080
	s_addc_u32 s21, s19, -1
	s_add_i32 s79, 0, 0x10000
	s_cmp_eq_u32 s78, 12
	s_cselect_b32 s21, s48, s21
	s_cselect_b32 s20, s49, s20
	s_cselect_b32 s77, s53, s71
	s_cselect_b32 s76, s54, s69
	s_add_u32 s100, s20, 0x80
	s_addc_u32 s101, s21, 0
	s_add_i32 s82, 0, 0x14000
	s_add_i32 m0, s9, 0xc000
	s_nop 0
	s_setprio 2
	global_load_lds_dwordx4 v130, s[18:19]
	s_add_i32 m0, s9, 0xe000
	s_nop 0
	global_load_lds_dwordx4 v134, s[18:19]
	s_setprio 0
	ds_read_b128 v[150:153], v255
	ds_read_b128 v[154:157], v255 offset:1024
	ds_read_b128 v[158:161], v255 offset:2048
	ds_read_b128 v[162:165], v255 offset:3072
	ds_read_b128 v[166:169], v255 offset:16384
	ds_read_b128 v[170:173], v255 offset:17408
	ds_read_b128 v[190:193], v255 offset:18432
	ds_read_b128 v[194:197], v255 offset:19456
	ds_read_b128 v[198:201], v148
	ds_read_b128 v[202:205], v148 offset:1024
	ds_read_b128 v[206:209], v148 offset:2048
	ds_read_b128 v[218:221], v148 offset:3072
	ds_read_b128 v[222:225], v148 offset:4096
	ds_read_b128 v[226:229], v148 offset:5120
	ds_read_b128 v[230:233], v148 offset:6144
	ds_read_b128 v[234:237], v148 offset:7168
	s_waitcnt vmcnt(8)
	s_waitcnt lgkmcnt(0)
	s_barrier
	s_waitcnt lgkmcnt(0)
	v_mfma_f32_16x16x32_bf16 v[126:129], v[150:153], v[198:201], 0
	v_mfma_f32_16x16x32_bf16 v[122:125], v[158:161], v[198:201], 0
	v_mfma_f32_16x16x32_bf16 v[110:113], v[150:153], v[206:209], 0
	v_mfma_f32_16x16x32_bf16 v[106:109], v[158:161], v[206:209], 0
	v_mfma_f32_16x16x32_bf16 v[94:97], v[150:153], v[222:225], 0
	v_mfma_f32_16x16x32_bf16 v[90:93], v[158:161], v[222:225], 0
	v_mfma_f32_16x16x32_bf16 v[82:85], v[150:153], v[230:233], 0
	v_mfma_f32_16x16x32_bf16 v[74:77], v[158:161], v[230:233], 0
	v_mfma_f32_16x16x32_bf16 v[126:129], v[154:157], v[202:205], v[126:129]
	v_mfma_f32_16x16x32_bf16 v[122:125], v[162:165], v[202:205], v[122:125]
	v_mfma_f32_16x16x32_bf16 v[110:113], v[154:157], v[218:221], v[110:113]
	v_mfma_f32_16x16x32_bf16 v[106:109], v[162:165], v[218:221], v[106:109]
	v_mfma_f32_16x16x32_bf16 v[94:97], v[154:157], v[226:229], v[94:97]
	v_mfma_f32_16x16x32_bf16 v[90:93], v[162:165], v[226:229], v[90:93]
	v_mfma_f32_16x16x32_bf16 v[82:85], v[154:157], v[234:237], v[82:85]
	v_mfma_f32_16x16x32_bf16 v[74:77], v[162:165], v[234:237], v[74:77]
	v_mfma_f32_16x16x32_bf16 v[118:121], v[166:169], v[198:201], 0
	v_mfma_f32_16x16x32_bf16 v[114:117], v[190:193], v[198:201], 0
	v_mfma_f32_16x16x32_bf16 v[102:105], v[166:169], v[206:209], 0
	v_mfma_f32_16x16x32_bf16 v[98:101], v[190:193], v[206:209], 0
	v_mfma_f32_16x16x32_bf16 v[86:89], v[166:169], v[222:225], 0
	v_mfma_f32_16x16x32_bf16 v[78:81], v[190:193], v[222:225], 0
	v_mfma_f32_16x16x32_bf16 v[70:73], v[166:169], v[230:233], 0
	v_mfma_f32_16x16x32_bf16 v[66:69], v[190:193], v[230:233], 0
	v_mfma_f32_16x16x32_bf16 v[118:121], v[170:173], v[202:205], v[118:121]
	v_mfma_f32_16x16x32_bf16 v[114:117], v[194:197], v[202:205], v[114:117]
	v_mfma_f32_16x16x32_bf16 v[102:105], v[170:173], v[218:221], v[102:105]
	v_mfma_f32_16x16x32_bf16 v[98:101], v[194:197], v[218:221], v[98:101]
	v_mfma_f32_16x16x32_bf16 v[86:89], v[170:173], v[226:229], v[86:89]
	v_mfma_f32_16x16x32_bf16 v[78:81], v[194:197], v[226:229], v[78:81]
	v_mfma_f32_16x16x32_bf16 v[70:73], v[170:173], v[234:237], v[70:73]
	v_mfma_f32_16x16x32_bf16 v[66:69], v[194:197], v[234:237], v[66:69]
	s_barrier
	s_add_i32 s79, s79, s8
	s_mov_b32 m0, s79
	s_nop 0
	s_setprio 2
	global_load_lds_dwordx4 v132, s[76:77]
	s_add_i32 m0, s79, 0x2000
	s_add_u32 s80, s76, 0x40000
	s_addc_u32 s81, s77, 0
	s_add_i32 s79, s82, s8
	global_load_lds_dwordx4 v136, s[76:77]
	s_mov_b32 m0, s79
	s_nop 0
	global_load_lds_dwordx4 v132, s[80:81]
	s_add_i32 m0, s79, 0x2000
	s_nop 0
	global_load_lds_dwordx4 v136, s[80:81]
	s_mov_b32 m0, s9
	s_nop 0
	global_load_lds_dwordx4 v130, s[20:21]
	s_mov_b32 m0, s28
	s_nop 0
	global_load_lds_dwordx4 v134, s[20:21]
	s_setprio 0
	ds_read_b128 v[198:201], v148 offset:16384
	ds_read_b128 v[202:205], v148 offset:17408
	ds_read_b128 v[206:209], v148 offset:18432
	ds_read_b128 v[218:221], v148 offset:19456
	ds_read_b128 v[222:225], v148 offset:20480
	ds_read_b128 v[226:229], v148 offset:21504
	ds_read_b128 v[230:233], v148 offset:22528
	ds_read_b128 v[234:237], v148 offset:23552
	s_waitcnt vmcnt(8)
	s_waitcnt lgkmcnt(0)
	s_barrier
; #define PG8_STAGE(bufoff, gbase, voff) do { _Pragma("unroll") for (int _i = 0; _i < 2; ++_i) \
;         __builtin_amdgcn_global_load_lds((const unsigned*)((const char*)(gbase) + (voff)[_i]), (LAS unsigned*)(lds + (bufoff) + ldsw + _i * 8192), 16, 0, 0); } while (0)
; #define PG8_LDA(dst, b, h) do { _Pragma("unroll") for (int m = 0; m < 4; ++m) _Pragma("unroll") for (int k = 0; k < 2; ++k) dst[m][k] = *(const LAS bf16x8*)(lds + PG8_SA(b, h) + aoff + m * 2048 + k * 1024); } while (0)
; #define PG8_LDB(dst, b, h) do { _Pragma("unroll") for (int n = 0; n < 2; ++n) _Pragma("unroll") for (int k = 0; k < 2; ++k) dst[n][k] = *(const LAS bf16x8*)(lds + PG8_SB(b, h) + boff + n * 2048 + k * 1024); } while (0)
; #define PG8_MMA(ai, bj, At, Bt) do { __builtin_amdgcn_s_setprio(1); _Pragma("unroll") for (int m = 0; m < 4; ++m) _Pragma("unroll") for (int n = 0; n < 2; ++n) _Pragma("unroll") for (int k = 0; k < 2; ++k) \
;         acc[ai][bj][m][n] = __builtin_amdgcn_mfma_f32_16x16x32_bf16(Bt[n][k], At[m][k], acc[ai][bj][m][n], 0, 0, 0); __builtin_amdgcn_s_setprio(0); } while (0)
; #define PG8_WAIT_V(n) asm volatile("s_waitcnt vmcnt(" #n ")" ::: "memory")
; #define PG8_WAIT_L(n) asm volatile("s_waitcnt lgkmcnt(" #n ")" ::: "memory")
; #define PG8_BAR __builtin_amdgcn_s_barrier()
; #define PG8_SCHED __builtin_amdgcn_sched_barrier(0)
; template <class Epi, class Sched>
; __device__ __forceinline__ void gemm_phase(LAS unsigned char* lds, const Gemm g, const Sched& S, const Epi& E) {
;     ...
;             PG8_WAIT_V(8); PG8_WAIT_L(0); PG8_BAR; PG8_MMA(1, 0, At, B0); PG8_MMA(1, 1, At, B1); PG8_BAR; PG8_SCHED;
;             PG8_LDB(B0, 1, 0); PG8_LDB(B1, 1, 1); PG8_SCHED; PG8_LDA(At, 1, 0); PG8_STAGE(PG8_SA(0, 1), a2 + hstepA, voffA);
;             PG8_WAIT_V(8); PG8_WAIT_L(0); PG8_BAR; PG8_MMA(0, 0, At, B0); PG8_MMA(0, 1, At, B1); PG8_BAR; PG8_SCHED;
	s_waitcnt lgkmcnt(0)
	v_mfma_f32_16x16x32_bf16 v[62:65], v[150:153], v[198:201], 0
	v_mfma_f32_16x16x32_bf16 v[58:61], v[158:161], v[198:201], 0
	v_mfma_f32_16x16x32_bf16 v[50:53], v[150:153], v[206:209], 0
	v_mfma_f32_16x16x32_bf16 v[42:45], v[158:161], v[206:209], 0
	v_mfma_f32_16x16x32_bf16 v[30:33], v[150:153], v[222:225], 0
	v_mfma_f32_16x16x32_bf16 v[26:29], v[158:161], v[222:225], 0
	v_mfma_f32_16x16x32_bf16 v[18:21], v[150:153], v[230:233], 0
	v_mfma_f32_16x16x32_bf16 v[10:13], v[158:161], v[230:233], 0
	v_mfma_f32_16x16x32_bf16 v[62:65], v[154:157], v[202:205], v[62:65]
	v_mfma_f32_16x16x32_bf16 v[58:61], v[162:165], v[202:205], v[58:61]
	v_mfma_f32_16x16x32_bf16 v[50:53], v[154:157], v[218:221], v[50:53]
	v_mfma_f32_16x16x32_bf16 v[42:45], v[162:165], v[218:221], v[42:45]
	v_mfma_f32_16x16x32_bf16 v[30:33], v[154:157], v[226:229], v[30:33]
	v_mfma_f32_16x16x32_bf16 v[26:29], v[162:165], v[226:229], v[26:29]
	v_mfma_f32_16x16x32_bf16 v[18:21], v[154:157], v[234:237], v[18:21]
	v_mfma_f32_16x16x32_bf16 v[10:13], v[162:165], v[234:237], v[10:13]
	v_mfma_f32_16x16x32_bf16 v[54:57], v[166:169], v[198:201], 0
	v_mfma_f32_16x16x32_bf16 v[46:49], v[190:193], v[198:201], 0
	v_mfma_f32_16x16x32_bf16 v[38:41], v[166:169], v[206:209], 0
	v_mfma_f32_16x16x32_bf16 v[34:37], v[190:193], v[206:209], 0
	v_mfma_f32_16x16x32_bf16 v[22:25], v[166:169], v[222:225], 0
	v_mfma_f32_16x16x32_bf16 v[14:17], v[190:193], v[222:225], 0
	v_mfma_f32_16x16x32_bf16 v[6:9], v[166:169], v[230:233], 0
	v_mfma_f32_16x16x32_bf16 v[2:5], v[190:193], v[230:233], 0
	v_mfma_f32_16x16x32_bf16 v[54:57], v[170:173], v[202:205], v[54:57]
	v_mfma_f32_16x16x32_bf16 v[46:49], v[194:197], v[202:205], v[46:49]
	v_mfma_f32_16x16x32_bf16 v[38:41], v[170:173], v[218:221], v[38:41]
	v_mfma_f32_16x16x32_bf16 v[34:37], v[194:197], v[218:221], v[34:37]
	v_mfma_f32_16x16x32_bf16 v[22:25], v[170:173], v[226:229], v[22:25]
	v_mfma_f32_16x16x32_bf16 v[14:17], v[194:197], v[226:229], v[14:17]
	v_mfma_f32_16x16x32_bf16 v[6:9], v[170:173], v[234:237], v[6:9]
	v_mfma_f32_16x16x32_bf16 v[2:5], v[194:197], v[234:237], v[2:5]
	s_barrier
	s_add_i32 s79, 0, 0x18000
	s_add_i32 s80, 0, 0x1c000
	s_add_u32 s20, s20, 0x40000
	s_addc_u32 s21, s21, 0
	s_mov_b32 m0, s29
	s_nop 0
	s_setprio 2
	global_load_lds_dwordx4 v130, s[20:21]
	s_mov_b32 m0, s30
	s_nop 0
	global_load_lds_dwordx4 v134, s[20:21]
	s_setprio 0
	ds_read_b128 v[150:153], v255 offset:32768
	ds_read_b128 v[154:157], v255 offset:33792
	ds_read_b128 v[158:161], v255 offset:34816
	ds_read_b128 v[162:165], v255 offset:35840
	ds_read_b128 v[166:169], v255 offset:49152
	ds_read_b128 v[170:173], v255 offset:50176
	ds_read_b128 v[190:193], v255 offset:51200
	ds_read_b128 v[194:197], v255 offset:52224
	ds_read_b128 v[198:201], v148 offset:32768
	ds_read_b128 v[202:205], v148 offset:33792
	ds_read_b128 v[206:209], v148 offset:34816
	ds_read_b128 v[218:221], v148 offset:35840
	ds_read_b128 v[222:225], v148 offset:36864
	ds_read_b128 v[226:229], v148 offset:37888
	ds_read_b128 v[230:233], v148 offset:38912
	ds_read_b128 v[234:237], v148 offset:39936
	s_waitcnt vmcnt(8)
	s_waitcnt lgkmcnt(0)
	s_barrier
	s_waitcnt lgkmcnt(0)
	v_mfma_f32_16x16x32_bf16 v[126:129], v[150:153], v[198:201], v[126:129]
	v_mfma_f32_16x16x32_bf16 v[122:125], v[158:161], v[198:201], v[122:125]
	v_mfma_f32_16x16x32_bf16 v[110:113], v[150:153], v[206:209], v[110:113]
	v_mfma_f32_16x16x32_bf16 v[106:109], v[158:161], v[206:209], v[106:109]
	v_mfma_f32_16x16x32_bf16 v[94:97], v[150:153], v[222:225], v[94:97]
	v_mfma_f32_16x16x32_bf16 v[90:93], v[158:161], v[222:225], v[90:93]
	v_mfma_f32_16x16x32_bf16 v[82:85], v[150:153], v[230:233], v[82:85]
	v_mfma_f32_16x16x32_bf16 v[74:77], v[158:161], v[230:233], v[74:77]
	v_mfma_f32_16x16x32_bf16 v[126:129], v[154:157], v[202:205], v[126:129]
	v_mfma_f32_16x16x32_bf16 v[122:125], v[162:165], v[202:205], v[122:125]
	v_mfma_f32_16x16x32_bf16 v[110:113], v[154:157], v[218:221], v[110:113]
	v_mfma_f32_16x16x32_bf16 v[106:109], v[162:165], v[218:221], v[106:109]
	v_mfma_f32_16x16x32_bf16 v[94:97], v[154:157], v[226:229], v[94:97]
	v_mfma_f32_16x16x32_bf16 v[90:93], v[162:165], v[226:229], v[90:93]
	v_mfma_f32_16x16x32_bf16 v[82:85], v[154:157], v[234:237], v[82:85]
	v_mfma_f32_16x16x32_bf16 v[74:77], v[162:165], v[234:237], v[74:77]
	v_mfma_f32_16x16x32_bf16 v[118:121], v[166:169], v[198:201], v[118:121]
	v_mfma_f32_16x16x32_bf16 v[114:117], v[190:193], v[198:201], v[114:117]
	v_mfma_f32_16x16x32_bf16 v[102:105], v[166:169], v[206:209], v[102:105]
	v_mfma_f32_16x16x32_bf16 v[98:101], v[190:193], v[206:209], v[98:101]
	v_mfma_f32_16x16x32_bf16 v[86:89], v[166:169], v[222:225], v[86:89]
	v_mfma_f32_16x16x32_bf16 v[78:81], v[190:193], v[222:225], v[78:81]
	v_mfma_f32_16x16x32_bf16 v[70:73], v[166:169], v[230:233], v[70:73]
	v_mfma_f32_16x16x32_bf16 v[66:69], v[190:193], v[230:233], v[66:69]
	v_mfma_f32_16x16x32_bf16 v[118:121], v[170:173], v[202:205], v[118:121]
	v_mfma_f32_16x16x32_bf16 v[114:117], v[194:197], v[202:205], v[114:117]
	v_mfma_f32_16x16x32_bf16 v[102:105], v[170:173], v[218:221], v[102:105]
	v_mfma_f32_16x16x32_bf16 v[98:101], v[194:197], v[218:221], v[98:101]
	v_mfma_f32_16x16x32_bf16 v[86:89], v[170:173], v[226:229], v[86:89]
	v_mfma_f32_16x16x32_bf16 v[78:81], v[194:197], v[226:229], v[78:81]
	v_mfma_f32_16x16x32_bf16 v[70:73], v[170:173], v[234:237], v[70:73]
	v_mfma_f32_16x16x32_bf16 v[66:69], v[194:197], v[234:237], v[66:69]
	s_barrier
; #define PG8_STAGE(bufoff, gbase, voff) do { _Pragma("unroll") for (int _i = 0; _i < 2; ++_i) \
;         __builtin_amdgcn_global_load_lds((const unsigned*)((const char*)(gbase) + (voff)[_i]), (LAS unsigned*)(lds + (bufoff) + ldsw + _i * 8192), 16, 0, 0); } while (0)
; #define PG8_LDA(dst, b, h) do { _Pragma("unroll") for (int m = 0; m < 4; ++m) _Pragma("unroll") for (int k = 0; k < 2; ++k) dst[m][k] = *(const LAS bf16x8*)(lds + PG8_SA(b, h) + aoff + m * 2048 + k * 1024); } while (0)
; #define PG8_LDB(dst, b, h) do { _Pragma("unroll") for (int n = 0; n < 2; ++n) _Pragma("unroll") for (int k = 0; k < 2; ++k) dst[n][k] = *(const LAS bf16x8*)(lds + PG8_SB(b, h) + boff + n * 2048 + k * 1024); } while (0)
; #define PG8_MMA(ai, bj, At, Bt) do { __builtin_amdgcn_s_setprio(1); _Pragma("unroll") for (int m = 0; m < 4; ++m) _Pragma("unroll") for (int n = 0; n < 2; ++n) _Pragma("unroll") for (int k = 0; k < 2; ++k) \
;         acc[ai][bj][m][n] = __builtin_amdgcn_mfma_f32_16x16x32_bf16(Bt[n][k], At[m][k], acc[ai][bj][m][n], 0, 0, 0); __builtin_amdgcn_s_setprio(0); } while (0)
; #define PG8_WAIT_V(n) asm volatile("s_waitcnt vmcnt(" #n ")" ::: "memory")
; #define PG8_WAIT_L(n) asm volatile("s_waitcnt lgkmcnt(" #n ")" ::: "memory")
; #define PG8_BAR __builtin_amdgcn_s_barrier()
; #define PG8_SCHED __builtin_amdgcn_sched_barrier(0)
; template <class Epi, class Sched>
; __device__ __forceinline__ void gemm_phase(LAS unsigned char* lds, const Gemm g, const Sched& S, const Epi& E) {
;     ...
;         for (int t = 0; t < nt; t += 2) {
;             const bool last = (t == nt - 2);
;             const char* a1 = cA + (size_t)(t + 1) * kstep;
;             const char* a2 = last ? nA : cA + (size_t)(t + 2) * kstep; const char* b2 = last ? nB : cB + (size_t)(t + 2) * kstep;
;             const char* a3 = a2 + kstep; const char* b3 = b2 + kstep;
;             PG8_LDB(B0, 0, 0); PG8_LDB(B1, 0, 1); PG8_SCHED; PG8_LDA(At, 0, 0); PG8_STAGE(PG8_SA(1, 1), a1 + hstepA, voffA);
;             PG8_WAIT_V(8); PG8_WAIT_L(0); PG8_BAR; PG8_MMA(0, 0, At, B0); PG8_MMA(0, 1, At, B1); PG8_BAR; PG8_SCHED;
;     ...
;             PG8_LDA(At, 1, 1); PG8_STAGE(PG8_SB(1, 0), b3, voffB); PG8_STAGE(PG8_SB(1, 1), b3 + hstepB, voffB); PG8_STAGE(PG8_SA(1, 0), a3, voffA);
;             PG8_WAIT_V(8); PG8_WAIT_L(0); PG8_BAR; PG8_MMA(1, 0, At, B0); PG8_MMA(1, 1, At, B1); PG8_BAR; PG8_SCHED;
	s_add_i32 s20, s8, 0x18000
	s_add_u32 s80, s76, 0x80
	s_addc_u32 s81, s77, 0
	s_mov_b32 m0, s20
	s_nop 0
	s_setprio 2
	global_load_lds_dwordx4 v132, s[80:81]
	s_add_i32 m0, s20, 0x2000
	s_add_u32 s20, s76, 0x40080
	s_addc_u32 s21, s77, 0
	s_add_i32 s12, s8, 0x1c000
	global_load_lds_dwordx4 v136, s[80:81]
	s_mov_b32 m0, s12
	s_nop 0
	global_load_lds_dwordx4 v132, s[20:21]
	s_add_i32 m0, s12, 0x2000
	s_nop 0
	global_load_lds_dwordx4 v136, s[20:21]
	s_mov_b32 m0, s31
	s_nop 0
	global_load_lds_dwordx4 v130, s[100:101]
	s_mov_b32 m0, s34
	s_nop 0
	global_load_lds_dwordx4 v134, s[100:101]
	s_setprio 0
	ds_read_b128 v[198:201], v148 offset:49152
	ds_read_b128 v[202:205], v148 offset:50176
	ds_read_b128 v[206:209], v148 offset:51200
	ds_read_b128 v[218:221], v148 offset:52224
	ds_read_b128 v[222:225], v148 offset:53248
	ds_read_b128 v[226:229], v148 offset:54272
	ds_read_b128 v[230:233], v148 offset:55296
	ds_read_b128 v[234:237], v148 offset:56320
	s_waitcnt vmcnt(8)
	s_waitcnt lgkmcnt(0)
	s_barrier
	s_waitcnt lgkmcnt(0)
	v_mfma_f32_16x16x32_bf16 v[62:65], v[150:153], v[198:201], v[62:65]
	v_mfma_f32_16x16x32_bf16 v[58:61], v[158:161], v[198:201], v[58:61]
	v_mfma_f32_16x16x32_bf16 v[50:53], v[150:153], v[206:209], v[50:53]
	v_mfma_f32_16x16x32_bf16 v[42:45], v[158:161], v[206:209], v[42:45]
	v_mfma_f32_16x16x32_bf16 v[30:33], v[150:153], v[222:225], v[30:33]
	v_mfma_f32_16x16x32_bf16 v[26:29], v[158:161], v[222:225], v[26:29]
	v_mfma_f32_16x16x32_bf16 v[18:21], v[150:153], v[230:233], v[18:21]
	v_mfma_f32_16x16x32_bf16 v[10:13], v[158:161], v[230:233], v[10:13]
	v_mfma_f32_16x16x32_bf16 v[62:65], v[154:157], v[202:205], v[62:65]
	v_mfma_f32_16x16x32_bf16 v[58:61], v[162:165], v[202:205], v[58:61]
	v_mfma_f32_16x16x32_bf16 v[50:53], v[154:157], v[218:221], v[50:53]
	v_mfma_f32_16x16x32_bf16 v[42:45], v[162:165], v[218:221], v[42:45]
	v_mfma_f32_16x16x32_bf16 v[30:33], v[154:157], v[226:229], v[30:33]
	v_mfma_f32_16x16x32_bf16 v[26:29], v[162:165], v[226:229], v[26:29]
	v_mfma_f32_16x16x32_bf16 v[18:21], v[154:157], v[234:237], v[18:21]
	v_mfma_f32_16x16x32_bf16 v[10:13], v[162:165], v[234:237], v[10:13]
	v_mfma_f32_16x16x32_bf16 v[54:57], v[166:169], v[198:201], v[54:57]
	v_mfma_f32_16x16x32_bf16 v[46:49], v[190:193], v[198:201], v[46:49]
	v_mfma_f32_16x16x32_bf16 v[38:41], v[166:169], v[206:209], v[38:41]
	v_mfma_f32_16x16x32_bf16 v[34:37], v[190:193], v[206:209], v[34:37]
	v_mfma_f32_16x16x32_bf16 v[22:25], v[166:169], v[222:225], v[22:25]
	v_mfma_f32_16x16x32_bf16 v[14:17], v[190:193], v[222:225], v[14:17]
	v_mfma_f32_16x16x32_bf16 v[6:9], v[166:169], v[230:233], v[6:9]
	v_mfma_f32_16x16x32_bf16 v[2:5], v[190:193], v[230:233], v[2:5]
	v_mfma_f32_16x16x32_bf16 v[54:57], v[170:173], v[202:205], v[54:57]
	v_mfma_f32_16x16x32_bf16 v[46:49], v[194:197], v[202:205], v[46:49]
	v_mfma_f32_16x16x32_bf16 v[38:41], v[170:173], v[218:221], v[38:41]
	v_mfma_f32_16x16x32_bf16 v[34:37], v[194:197], v[218:221], v[34:37]
	v_mfma_f32_16x16x32_bf16 v[22:25], v[170:173], v[226:229], v[22:25]
	v_mfma_f32_16x16x32_bf16 v[14:17], v[194:197], v[226:229], v[14:17]
	v_mfma_f32_16x16x32_bf16 v[6:9], v[170:173], v[234:237], v[6:9]
	v_mfma_f32_16x16x32_bf16 v[2:5], v[194:197], v[234:237], v[2:5]
	s_barrier
	s_add_i32 s78, s78, 2
	s_add_u32 s18, s18, 0x100
	s_addc_u32 s19, s19, 0
	s_add_u32 s69, s69, 0x100
	s_addc_u32 s71, s71, 0
	s_cmp_gt_u32 s78, 13
.LBB0_349:
	s_add_u32 s20, s18, 0xfffc0080
	s_addc_u32 s21, s19, -1
	s_add_i32 s79, 0, 0x10000
	s_cmp_eq_u32 s78, 12
	s_cselect_b32 s21, s48, s21
	s_cselect_b32 s20, s49, s20
	s_cselect_b32 s77, s53, s71
	s_cselect_b32 s76, s54, s69
	s_add_u32 s100, s20, 0x80
	s_addc_u32 s101, s21, 0
	s_add_i32 s82, 0, 0x14000
	s_add_i32 m0, s9, 0xc000
	s_nop 0
	s_setprio 2
	global_load_lds_dwordx4 v130, s[18:19]
	s_add_i32 m0, s9, 0xe000
	s_nop 0
	global_load_lds_dwordx4 v134, s[18:19]
	s_setprio 0
	ds_read_b128 v[150:153], v255
	ds_read_b128 v[154:157], v255 offset:1024
	ds_read_b128 v[158:161], v255 offset:2048
	ds_read_b128 v[162:165], v255 offset:3072
	ds_read_b128 v[166:169], v255 offset:16384
	ds_read_b128 v[170:173], v255 offset:17408
	ds_read_b128 v[190:193], v255 offset:18432
	ds_read_b128 v[194:197], v255 offset:19456
	ds_read_b128 v[198:201], v148
	ds_read_b128 v[202:205], v148 offset:1024
	ds_read_b128 v[206:209], v148 offset:2048
	ds_read_b128 v[218:221], v148 offset:3072
	ds_read_b128 v[222:225], v148 offset:4096
	ds_read_b128 v[226:229], v148 offset:5120
	ds_read_b128 v[230:233], v148 offset:6144
	ds_read_b128 v[234:237], v148 offset:7168
	s_waitcnt vmcnt(8)
	s_waitcnt lgkmcnt(0)
	s_barrier
; #define PG8_STAGE(bufoff, gbase, voff) do { _Pragma("unroll") for (int _i = 0; _i < 2; ++_i) \
;         __builtin_amdgcn_global_load_lds((const unsigned*)((const char*)(gbase) + (voff)[_i]), (LAS unsigned*)(lds + (bufoff) + ldsw + _i * 8192), 16, 0, 0); } while (0)
; #define PG8_LDA(dst, b, h) do { _Pragma("unroll") for (int m = 0; m < 4; ++m) _Pragma("unroll") for (int k = 0; k < 2; ++k) dst[m][k] = *(const LAS bf16x8*)(lds + PG8_SA(b, h) + aoff + m * 2048 + k * 1024); } while (0)
; #define PG8_MMA(ai, bj, At, Bt) do { __builtin_amdgcn_s_setprio(1); _Pragma("unroll") for (int m = 0; m < 4; ++m) _Pragma("unroll") for (int n = 0; n < 2; ++n) _Pragma("unroll") for (int k = 0; k < 2; ++k) \
;         acc[ai][bj][m][n] = __builtin_amdgcn_mfma_f32_16x16x32_bf16(Bt[n][k], At[m][k], acc[ai][bj][m][n], 0, 0, 0); __builtin_amdgcn_s_setprio(0); } while (0)
; #define PG8_WAIT_V(n) asm volatile("s_waitcnt vmcnt(" #n ")" ::: "memory")
; #define PG8_WAIT_L(n) asm volatile("s_waitcnt lgkmcnt(" #n ")" ::: "memory")
; #define PG8_BAR __builtin_amdgcn_s_barrier()
; #define PG8_SCHED __builtin_amdgcn_sched_barrier(0)
; template <class Epi, class Sched>
; __device__ __forceinline__ void gemm_phase(LAS unsigned char* lds, const Gemm g, const Sched& S, const Epi& E) {
;     ...
;             PG8_WAIT_V(8); PG8_WAIT_L(0); PG8_BAR; PG8_MMA(0, 0, At, B0); PG8_MMA(0, 1, At, B1); PG8_BAR; PG8_SCHED;
;             PG8_LDA(At, 0, 1); PG8_STAGE(PG8_SB(0, 0), b2, voffB); PG8_STAGE(PG8_SB(0, 1), b2 + hstepB, voffB); PG8_STAGE(PG8_SA(0, 0), a2, voffA);
;             PG8_WAIT_V(8); PG8_WAIT_L(0); PG8_BAR; PG8_MMA(1, 0, At, B0); PG8_MMA(1, 1, At, B1); PG8_BAR; PG8_SCHED;
	s_waitcnt lgkmcnt(0)
	v_mfma_f32_16x16x32_bf16 v[126:129], v[150:153], v[198:201], v[126:129]
	v_mfma_f32_16x16x32_bf16 v[122:125], v[158:161], v[198:201], v[122:125]
	v_mfma_f32_16x16x32_bf16 v[110:113], v[150:153], v[206:209], v[110:113]
	v_mfma_f32_16x16x32_bf16 v[106:109], v[158:161], v[206:209], v[106:109]
	v_mfma_f32_16x16x32_bf16 v[94:97], v[150:153], v[222:225], v[94:97]
	v_mfma_f32_16x16x32_bf16 v[90:93], v[158:161], v[222:225], v[90:93]
	v_mfma_f32_16x16x32_bf16 v[82:85], v[150:153], v[230:233], v[82:85]
	v_mfma_f32_16x16x32_bf16 v[74:77], v[158:161], v[230:233], v[74:77]
	v_mfma_f32_16x16x32_bf16 v[126:129], v[154:157], v[202:205], v[126:129]
	v_mfma_f32_16x16x32_bf16 v[122:125], v[162:165], v[202:205], v[122:125]
	v_mfma_f32_16x16x32_bf16 v[110:113], v[154:157], v[218:221], v[110:113]
	v_mfma_f32_16x16x32_bf16 v[106:109], v[162:165], v[218:221], v[106:109]
	v_mfma_f32_16x16x32_bf16 v[94:97], v[154:157], v[226:229], v[94:97]
	v_mfma_f32_16x16x32_bf16 v[90:93], v[162:165], v[226:229], v[90:93]
	v_mfma_f32_16x16x32_bf16 v[82:85], v[154:157], v[234:237], v[82:85]
	v_mfma_f32_16x16x32_bf16 v[74:77], v[162:165], v[234:237], v[74:77]
	v_mfma_f32_16x16x32_bf16 v[118:121], v[166:169], v[198:201], v[118:121]
	v_mfma_f32_16x16x32_bf16 v[114:117], v[190:193], v[198:201], v[114:117]
	v_mfma_f32_16x16x32_bf16 v[102:105], v[166:169], v[206:209], v[102:105]
	v_mfma_f32_16x16x32_bf16 v[98:101], v[190:193], v[206:209], v[98:101]
	v_mfma_f32_16x16x32_bf16 v[86:89], v[166:169], v[222:225], v[86:89]
	v_mfma_f32_16x16x32_bf16 v[78:81], v[190:193], v[222:225], v[78:81]
	v_mfma_f32_16x16x32_bf16 v[70:73], v[166:169], v[230:233], v[70:73]
	v_mfma_f32_16x16x32_bf16 v[66:69], v[190:193], v[230:233], v[66:69]
	v_mfma_f32_16x16x32_bf16 v[118:121], v[170:173], v[202:205], v[118:121]
	v_mfma_f32_16x16x32_bf16 v[114:117], v[194:197], v[202:205], v[114:117]
	v_mfma_f32_16x16x32_bf16 v[102:105], v[170:173], v[218:221], v[102:105]
	v_mfma_f32_16x16x32_bf16 v[98:101], v[194:197], v[218:221], v[98:101]
	v_mfma_f32_16x16x32_bf16 v[86:89], v[170:173], v[226:229], v[86:89]
	v_mfma_f32_16x16x32_bf16 v[78:81], v[194:197], v[226:229], v[78:81]
	v_mfma_f32_16x16x32_bf16 v[70:73], v[170:173], v[234:237], v[70:73]
	v_mfma_f32_16x16x32_bf16 v[66:69], v[194:197], v[234:237], v[66:69]
	s_barrier
	s_add_i32 s79, s79, s8
	s_mov_b32 m0, s79
	s_nop 0
	s_setprio 2
	global_load_lds_dwordx4 v132, s[76:77]
	s_add_i32 m0, s79, 0x2000
	s_add_u32 s80, s76, 0x40000
	s_addc_u32 s81, s77, 0
	s_add_i32 s79, s82, s8
	global_load_lds_dwordx4 v136, s[76:77]
	s_mov_b32 m0, s79
	s_nop 0
	global_load_lds_dwordx4 v132, s[80:81]
	s_add_i32 m0, s79, 0x2000
	s_nop 0
	global_load_lds_dwordx4 v136, s[80:81]
	s_mov_b32 m0, s9
	s_nop 0
	global_load_lds_dwordx4 v130, s[20:21]
	s_mov_b32 m0, s28
	s_nop 0
	global_load_lds_dwordx4 v134, s[20:21]
	s_setprio 0
	ds_read_b128 v[198:201], v148 offset:16384
	ds_read_b128 v[202:205], v148 offset:17408
	ds_read_b128 v[206:209], v148 offset:18432
	ds_read_b128 v[218:221], v148 offset:19456
	ds_read_b128 v[222:225], v148 offset:20480
	ds_read_b128 v[226:229], v148 offset:21504
	ds_read_b128 v[230:233], v148 offset:22528
	ds_read_b128 v[234:237], v148 offset:23552
	s_waitcnt vmcnt(8)
	s_waitcnt lgkmcnt(0)
	s_barrier
	s_waitcnt lgkmcnt(0)
	v_mfma_f32_16x16x32_bf16 v[62:65], v[150:153], v[198:201], v[62:65]
	v_mfma_f32_16x16x32_bf16 v[58:61], v[158:161], v[198:201], v[58:61]
	v_mfma_f32_16x16x32_bf16 v[50:53], v[150:153], v[206:209], v[50:53]
	v_mfma_f32_16x16x32_bf16 v[42:45], v[158:161], v[206:209], v[42:45]
	v_mfma_f32_16x16x32_bf16 v[30:33], v[150:153], v[222:225], v[30:33]
	v_mfma_f32_16x16x32_bf16 v[26:29], v[158:161], v[222:225], v[26:29]
	v_mfma_f32_16x16x32_bf16 v[18:21], v[150:153], v[230:233], v[18:21]
	v_mfma_f32_16x16x32_bf16 v[10:13], v[158:161], v[230:233], v[10:13]
	v_mfma_f32_16x16x32_bf16 v[62:65], v[154:157], v[202:205], v[62:65]
	v_mfma_f32_16x16x32_bf16 v[58:61], v[162:165], v[202:205], v[58:61]
	v_mfma_f32_16x16x32_bf16 v[50:53], v[154:157], v[218:221], v[50:53]
	v_mfma_f32_16x16x32_bf16 v[42:45], v[162:165], v[218:221], v[42:45]
	v_mfma_f32_16x16x32_bf16 v[30:33], v[154:157], v[226:229], v[30:33]
	v_mfma_f32_16x16x32_bf16 v[26:29], v[162:165], v[226:229], v[26:29]
	v_mfma_f32_16x16x32_bf16 v[18:21], v[154:157], v[234:237], v[18:21]
	v_mfma_f32_16x16x32_bf16 v[10:13], v[162:165], v[234:237], v[10:13]
	v_mfma_f32_16x16x32_bf16 v[54:57], v[166:169], v[198:201], v[54:57]
	v_mfma_f32_16x16x32_bf16 v[46:49], v[190:193], v[198:201], v[46:49]
	v_mfma_f32_16x16x32_bf16 v[38:41], v[166:169], v[206:209], v[38:41]
	v_mfma_f32_16x16x32_bf16 v[34:37], v[190:193], v[206:209], v[34:37]
	v_mfma_f32_16x16x32_bf16 v[22:25], v[166:169], v[222:225], v[22:25]
	v_mfma_f32_16x16x32_bf16 v[14:17], v[190:193], v[222:225], v[14:17]
	v_mfma_f32_16x16x32_bf16 v[6:9], v[166:169], v[230:233], v[6:9]
	v_mfma_f32_16x16x32_bf16 v[2:5], v[190:193], v[230:233], v[2:5]
	v_mfma_f32_16x16x32_bf16 v[54:57], v[170:173], v[202:205], v[54:57]
	v_mfma_f32_16x16x32_bf16 v[46:49], v[194:197], v[202:205], v[46:49]
	v_mfma_f32_16x16x32_bf16 v[38:41], v[170:173], v[218:221], v[38:41]
	v_mfma_f32_16x16x32_bf16 v[34:37], v[194:197], v[218:221], v[34:37]
	v_mfma_f32_16x16x32_bf16 v[22:25], v[170:173], v[226:229], v[22:25]
	v_mfma_f32_16x16x32_bf16 v[14:17], v[194:197], v[226:229], v[14:17]
	v_mfma_f32_16x16x32_bf16 v[6:9], v[170:173], v[234:237], v[6:9]
	v_mfma_f32_16x16x32_bf16 v[2:5], v[194:197], v[234:237], v[2:5]
	s_barrier
; #define PG8_STAGE(bufoff, gbase, voff) do { _Pragma("unroll") for (int _i = 0; _i < 2; ++_i) \
;         __builtin_amdgcn_global_load_lds((const unsigned*)((const char*)(gbase) + (voff)[_i]), (LAS unsigned*)(lds + (bufoff) + ldsw + _i * 8192), 16, 0, 0); } while (0)
; #define PG8_LDA(dst, b, h) do { _Pragma("unroll") for (int m = 0; m < 4; ++m) _Pragma("unroll") for (int k = 0; k < 2; ++k) dst[m][k] = *(const LAS bf16x8*)(lds + PG8_SA(b, h) + aoff + m * 2048 + k * 1024); } while (0)
; #define PG8_LDB(dst, b, h) do { _Pragma("unroll") for (int n = 0; n < 2; ++n) _Pragma("unroll") for (int k = 0; k < 2; ++k) dst[n][k] = *(const LAS bf16x8*)(lds + PG8_SB(b, h) + boff + n * 2048 + k * 1024); } while (0)
; #define PG8_MMA(ai, bj, At, Bt) do { __builtin_amdgcn_s_setprio(1); _Pragma("unroll") for (int m = 0; m < 4; ++m) _Pragma("unroll") for (int n = 0; n < 2; ++n) _Pragma("unroll") for (int k = 0; k < 2; ++k) \
;         acc[ai][bj][m][n] = __builtin_amdgcn_mfma_f32_16x16x32_bf16(Bt[n][k], At[m][k], acc[ai][bj][m][n], 0, 0, 0); __builtin_amdgcn_s_setprio(0); } while (0)
; #define PG8_WAIT_V(n) asm volatile("s_waitcnt vmcnt(" #n ")" ::: "memory")
; #define PG8_WAIT_L(n) asm volatile("s_waitcnt lgkmcnt(" #n ")" ::: "memory")
; #define PG8_BAR __builtin_amdgcn_s_barrier()
; #define PG8_SCHED __builtin_amdgcn_sched_barrier(0)
; template <class Epi, class Sched>
; __device__ __forceinline__ void gemm_phase(LAS unsigned char* lds, const Gemm g, const Sched& S, const Epi& E) {
;     ...
;             PG8_LDB(B0, 1, 0); PG8_LDB(B1, 1, 1); PG8_SCHED; PG8_LDA(At, 1, 0); PG8_STAGE(PG8_SA(0, 1), a2 + hstepA, voffA);
;             PG8_WAIT_V(8); PG8_WAIT_L(0); PG8_BAR; PG8_MMA(0, 0, At, B0); PG8_MMA(0, 1, At, B1); PG8_BAR; PG8_SCHED;
;             PG8_LDA(At, 1, 1); PG8_STAGE(PG8_SB(1, 0), b3, voffB); PG8_STAGE(PG8_SB(1, 1), b3 + hstepB, voffB); PG8_STAGE(PG8_SA(1, 0), a3, voffA);
;             PG8_WAIT_V(8); PG8_WAIT_L(0); PG8_BAR; PG8_MMA(1, 0, At, B0); PG8_MMA(1, 1, At, B1); PG8_BAR; PG8_SCHED;
;         }
;         if (wr == 0) PG8_BAR;
	s_add_i32 s79, 0, 0x18000
	s_add_i32 s80, 0, 0x1c000
	s_add_u32 s20, s20, 0x40000
	s_addc_u32 s21, s21, 0
	s_mov_b32 m0, s29
	s_nop 0
	s_setprio 2
	global_load_lds_dwordx4 v130, s[20:21]
	s_mov_b32 m0, s30
	s_nop 0
	global_load_lds_dwordx4 v134, s[20:21]
	s_setprio 0
	ds_read_b128 v[150:153], v255 offset:32768
	ds_read_b128 v[154:157], v255 offset:33792
	ds_read_b128 v[158:161], v255 offset:34816
	ds_read_b128 v[162:165], v255 offset:35840
	ds_read_b128 v[166:169], v255 offset:49152
	ds_read_b128 v[170:173], v255 offset:50176
	ds_read_b128 v[190:193], v255 offset:51200
	ds_read_b128 v[194:197], v255 offset:52224
	ds_read_b128 v[198:201], v148 offset:32768
	ds_read_b128 v[202:205], v148 offset:33792
	ds_read_b128 v[206:209], v148 offset:34816
	ds_read_b128 v[218:221], v148 offset:35840
	ds_read_b128 v[222:225], v148 offset:36864
	ds_read_b128 v[226:229], v148 offset:37888
	ds_read_b128 v[230:233], v148 offset:38912
	ds_read_b128 v[234:237], v148 offset:39936
	s_waitcnt vmcnt(8)
	s_waitcnt lgkmcnt(0)
	s_barrier
	s_waitcnt lgkmcnt(0)
	v_mfma_f32_16x16x32_bf16 v[126:129], v[150:153], v[198:201], v[126:129]
	v_mfma_f32_16x16x32_bf16 v[122:125], v[158:161], v[198:201], v[122:125]
	v_mfma_f32_16x16x32_bf16 v[110:113], v[150:153], v[206:209], v[110:113]
	v_mfma_f32_16x16x32_bf16 v[106:109], v[158:161], v[206:209], v[106:109]
	v_mfma_f32_16x16x32_bf16 v[94:97], v[150:153], v[222:225], v[94:97]
	v_mfma_f32_16x16x32_bf16 v[90:93], v[158:161], v[222:225], v[90:93]
	v_mfma_f32_16x16x32_bf16 v[82:85], v[150:153], v[230:233], v[82:85]
	v_mfma_f32_16x16x32_bf16 v[74:77], v[158:161], v[230:233], v[74:77]
	v_mfma_f32_16x16x32_bf16 v[126:129], v[154:157], v[202:205], v[126:129]
	v_mfma_f32_16x16x32_bf16 v[122:125], v[162:165], v[202:205], v[122:125]
	v_mfma_f32_16x16x32_bf16 v[110:113], v[154:157], v[218:221], v[110:113]
	v_mfma_f32_16x16x32_bf16 v[106:109], v[162:165], v[218:221], v[106:109]
	v_mfma_f32_16x16x32_bf16 v[94:97], v[154:157], v[226:229], v[94:97]
	v_mfma_f32_16x16x32_bf16 v[90:93], v[162:165], v[226:229], v[90:93]
	v_mfma_f32_16x16x32_bf16 v[82:85], v[154:157], v[234:237], v[82:85]
	v_mfma_f32_16x16x32_bf16 v[74:77], v[162:165], v[234:237], v[74:77]
	v_mfma_f32_16x16x32_bf16 v[118:121], v[166:169], v[198:201], v[118:121]
	v_mfma_f32_16x16x32_bf16 v[114:117], v[190:193], v[198:201], v[114:117]
	v_mfma_f32_16x16x32_bf16 v[102:105], v[166:169], v[206:209], v[102:105]
	v_mfma_f32_16x16x32_bf16 v[98:101], v[190:193], v[206:209], v[98:101]
	v_mfma_f32_16x16x32_bf16 v[86:89], v[166:169], v[222:225], v[86:89]
	v_mfma_f32_16x16x32_bf16 v[78:81], v[190:193], v[222:225], v[78:81]
	v_mfma_f32_16x16x32_bf16 v[70:73], v[166:169], v[230:233], v[70:73]
	v_mfma_f32_16x16x32_bf16 v[66:69], v[190:193], v[230:233], v[66:69]
	v_mfma_f32_16x16x32_bf16 v[118:121], v[170:173], v[202:205], v[118:121]
	v_mfma_f32_16x16x32_bf16 v[114:117], v[194:197], v[202:205], v[114:117]
	v_mfma_f32_16x16x32_bf16 v[102:105], v[170:173], v[218:221], v[102:105]
	v_mfma_f32_16x16x32_bf16 v[98:101], v[194:197], v[218:221], v[98:101]
	v_mfma_f32_16x16x32_bf16 v[86:89], v[170:173], v[226:229], v[86:89]
	v_mfma_f32_16x16x32_bf16 v[78:81], v[194:197], v[226:229], v[78:81]
	v_mfma_f32_16x16x32_bf16 v[70:73], v[170:173], v[234:237], v[70:73]
	v_mfma_f32_16x16x32_bf16 v[66:69], v[194:197], v[234:237], v[66:69]
	s_barrier
	s_add_i32 s20, s8, 0x18000
	s_add_u32 s80, s76, 0x80
	s_addc_u32 s81, s77, 0
	s_mov_b32 m0, s20
	s_nop 0
	s_setprio 2
	global_load_lds_dwordx4 v132, s[80:81]
	s_add_i32 m0, s20, 0x2000
	s_add_u32 s20, s76, 0x40080
	s_addc_u32 s21, s77, 0
	s_add_i32 s12, s8, 0x1c000
	global_load_lds_dwordx4 v136, s[80:81]
	s_mov_b32 m0, s12
	s_nop 0
	global_load_lds_dwordx4 v132, s[20:21]
	s_add_i32 m0, s12, 0x2000
	s_nop 0
	global_load_lds_dwordx4 v136, s[20:21]
	s_mov_b32 m0, s31
	s_nop 0
	global_load_lds_dwordx4 v130, s[100:101]
	s_mov_b32 m0, s34
	s_nop 0
	global_load_lds_dwordx4 v134, s[100:101]
	s_setprio 0
	ds_read_b128 v[198:201], v148 offset:49152
	ds_read_b128 v[202:205], v148 offset:50176
	ds_read_b128 v[206:209], v148 offset:51200
	ds_read_b128 v[218:221], v148 offset:52224
	ds_read_b128 v[222:225], v148 offset:53248
	ds_read_b128 v[226:229], v148 offset:54272
	ds_read_b128 v[230:233], v148 offset:55296
	ds_read_b128 v[234:237], v148 offset:56320
	s_waitcnt vmcnt(8)
	s_waitcnt lgkmcnt(0)
	s_barrier
	s_waitcnt lgkmcnt(0)
	v_mfma_f32_16x16x32_bf16 v[62:65], v[150:153], v[198:201], v[62:65]
	v_mfma_f32_16x16x32_bf16 v[58:61], v[158:161], v[198:201], v[58:61]
	v_mfma_f32_16x16x32_bf16 v[50:53], v[150:153], v[206:209], v[50:53]
	v_mfma_f32_16x16x32_bf16 v[42:45], v[158:161], v[206:209], v[42:45]
	v_mfma_f32_16x16x32_bf16 v[30:33], v[150:153], v[222:225], v[30:33]
	v_mfma_f32_16x16x32_bf16 v[26:29], v[158:161], v[222:225], v[26:29]
	v_mfma_f32_16x16x32_bf16 v[18:21], v[150:153], v[230:233], v[18:21]
	v_mfma_f32_16x16x32_bf16 v[10:13], v[158:161], v[230:233], v[10:13]
	v_mfma_f32_16x16x32_bf16 v[62:65], v[154:157], v[202:205], v[62:65]
	v_mfma_f32_16x16x32_bf16 v[58:61], v[162:165], v[202:205], v[58:61]
	v_mfma_f32_16x16x32_bf16 v[50:53], v[154:157], v[218:221], v[50:53]
	v_mfma_f32_16x16x32_bf16 v[42:45], v[162:165], v[218:221], v[42:45]
	v_mfma_f32_16x16x32_bf16 v[30:33], v[154:157], v[226:229], v[30:33]
	v_mfma_f32_16x16x32_bf16 v[26:29], v[162:165], v[226:229], v[26:29]
	v_mfma_f32_16x16x32_bf16 v[18:21], v[154:157], v[234:237], v[18:21]
	v_mfma_f32_16x16x32_bf16 v[10:13], v[162:165], v[234:237], v[10:13]
	v_mfma_f32_16x16x32_bf16 v[54:57], v[166:169], v[198:201], v[54:57]
	v_mfma_f32_16x16x32_bf16 v[46:49], v[190:193], v[198:201], v[46:49]
	v_mfma_f32_16x16x32_bf16 v[38:41], v[166:169], v[206:209], v[38:41]
	v_mfma_f32_16x16x32_bf16 v[34:37], v[190:193], v[206:209], v[34:37]
	v_mfma_f32_16x16x32_bf16 v[22:25], v[166:169], v[222:225], v[22:25]
	v_mfma_f32_16x16x32_bf16 v[14:17], v[190:193], v[222:225], v[14:17]
	v_mfma_f32_16x16x32_bf16 v[6:9], v[166:169], v[230:233], v[6:9]
	v_mfma_f32_16x16x32_bf16 v[2:5], v[190:193], v[230:233], v[2:5]
	v_mfma_f32_16x16x32_bf16 v[54:57], v[170:173], v[202:205], v[54:57]
	v_mfma_f32_16x16x32_bf16 v[46:49], v[194:197], v[202:205], v[46:49]
	v_mfma_f32_16x16x32_bf16 v[38:41], v[170:173], v[218:221], v[38:41]
	v_mfma_f32_16x16x32_bf16 v[34:37], v[194:197], v[218:221], v[34:37]
	v_mfma_f32_16x16x32_bf16 v[22:25], v[170:173], v[226:229], v[22:25]
	v_mfma_f32_16x16x32_bf16 v[14:17], v[194:197], v[226:229], v[14:17]
	v_mfma_f32_16x16x32_bf16 v[6:9], v[170:173], v[234:237], v[6:9]
	v_mfma_f32_16x16x32_bf16 v[2:5], v[194:197], v[234:237], v[2:5]
	s_barrier
	s_add_i32 s78, s78, 2
	s_add_u32 s18, s18, 0x100
	s_addc_u32 s19, s19, 0
	s_add_u32 s69, s69, 0x100
	s_addc_u32 s71, s71, 0
	s_cmp_gt_u32 s78, 13
	s_cbranch_scc0 .LBB0_349
	s_and_b64 vcc, exec, s[36:37]
	s_cbranch_vccz .LBB0_352
	s_barrier

; #define PG8_STAGE(bufoff, gbase, voff) do { _Pragma("unroll") for (int _i = 0; _i < 2; ++_i) \
;         __builtin_amdgcn_global_load_lds((const unsigned*)((const char*)(gbase) + (voff)[_i]), (LAS unsigned*)(lds + (bufoff) + ldsw + _i * 8192), 16, 0, 0); } while (0)
; #define PG8_LDA(dst, b, h) do { _Pragma("unroll") for (int m = 0; m < 4; ++m) _Pragma("unroll") for (int k = 0; k < 2; ++k) dst[m][k] = *(const LAS bf16x8*)(lds + PG8_SA(b, h) + aoff + m * 2048 + k * 1024); } while (0)
; #define PG8_LDB(dst, b, h) do { _Pragma("unroll") for (int n = 0; n < 2; ++n) _Pragma("unroll") for (int k = 0; k < 2; ++k) dst[n][k] = *(const LAS bf16x8*)(lds + PG8_SB(b, h) + boff + n * 2048 + k * 1024); } while (0)
; #define PG8_MMA(ai, bj, At, Bt) do { __builtin_amdgcn_s_setprio(1); _Pragma("unroll") for (int m = 0; m < 4; ++m) _Pragma("unroll") for (int n = 0; n < 2; ++n) _Pragma("unroll") for (int k = 0; k < 2; ++k) \
;         acc[ai][bj][m][n] = __builtin_amdgcn_mfma_f32_16x16x32_bf16(Bt[n][k], At[m][k], acc[ai][bj][m][n], 0, 0, 0); __builtin_amdgcn_s_setprio(0); } while (0)
; template <class Epi, class Sched>
; __device__ __forceinline__ void gemm_phase(LAS unsigned char* lds, const Gemm g, const Sched& S, const Epi& E) {
;     ...
;         const bool has_next = S.next(ui + 1, nxt);
;         const char* nA = has_next ? (const char*)g.A + (size_t)nxt.pm * tstepA + (size_t)nxt.pn * g.a_pn_off * 2 : cA; const char* nB = has_next ? (const char*)g.Bt + (size_t)nxt.pn * tstepB : cB;
;         for (int t = 0; t < nt; t += 2) {
;             const bool last = (t == nt - 2);
;             const char* a1 = cA + (size_t)(t + 1) * kstep;
;             const char* a2 = last ? nA : cA + (size_t)(t + 2) * kstep; const char* b2 = last ? nB : cB + (size_t)(t + 2) * kstep;
;             const char* a3 = a2 + kstep; const char* b3 = b2 + kstep;
;             PG8_LDB(B0, 0, 0); PG8_LDB(B1, 0, 1); PG8_SCHED; PG8_LDA(At, 0, 0); PG8_STAGE(PG8_SA(1, 1), a1 + hstepA, voffA);
;             PG8_WAIT_V(8); PG8_WAIT_L(0); PG8_BAR; PG8_MMA(0, 0, At, B0); PG8_MMA(0, 1, At, B1); PG8_BAR; PG8_SCHED;
;             PG8_LDA(At, 0, 1); PG8_STAGE(PG8_SB(0, 0), b2, voffB); PG8_STAGE(PG8_SB(0, 1), b2 + hstepB, voffB); PG8_STAGE(PG8_SA(0, 0), a2, voffA);
;             PG8_WAIT_V(8); PG8_WAIT_L(0); PG8_BAR; PG8_MMA(1, 0, At, B0); PG8_MMA(1, 1, At, B1); PG8_BAR; PG8_SCHED;
.LBB0_377:
	s_ashr_i32 s71, s70, 31
	s_lshl_b64 s[48:49], s[70:71], 19
	v_readlane_b32 s12, v248, 21
	s_add_u32 s72, s12, s48
	v_readlane_b32 s12, v248, 22
	s_addc_u32 s73, s12, s49
	s_and_b64 s[48:49], s[66:67], exec
	s_cselect_b32 s43, s73, s19
	s_cselect_b32 s48, s72, s18
	s_ashr_i32 s69, s68, 31
	s_lshl_b64 s[74:75], s[68:69], 19
	s_add_u32 s74, s4, s74
	s_addc_u32 s75, s5, s75
	s_and_b64 s[76:77], s[66:67], exec
	s_cselect_b32 s49, s75, s21
	s_cselect_b32 s53, s74, s20
	s_add_u32 s18, s18, 0x40080
	s_addc_u32 s19, s19, 0
	s_add_u32 s69, s20, 0x100
	s_addc_u32 s71, s21, 0
	s_mov_b32 s78, -2
	v_add_u32_e32 v255, 0x10000, v158
	s_add_u32 s20, s18, 0xfffc0080
	s_addc_u32 s21, s19, -1
	s_add_i32 s79, 0, 0x10000
	s_cmp_eq_u32 s78, 12
	s_cselect_b32 s21, s43, s21
	s_cselect_b32 s20, s48, s20
	s_cselect_b32 s77, s49, s71
	s_cselect_b32 s76, s53, s69
	s_add_u32 s100, s20, 0x80
	s_addc_u32 s101, s21, 0
	s_add_i32 s82, 0, 0x14000
	s_add_i32 m0, s9, 0xc000
	s_nop 0
	s_setprio 2
	global_load_lds_dwordx4 v146, s[18:19]
	s_add_i32 m0, s9, 0xe000
	s_nop 0
	global_load_lds_dwordx4 v150, s[18:19]
	s_setprio 0
	ds_read_b128 v[130:133], v255
	ds_read_b128 v[134:137], v255 offset:1024
	ds_read_b128 v[138:141], v255 offset:2048
	ds_read_b128 v[142:145], v255 offset:3072
	ds_read_b128 v[162:165], v255 offset:16384
	ds_read_b128 v[166:169], v255 offset:17408
	ds_read_b128 v[170:173], v255 offset:18432
	ds_read_b128 v[190:193], v255 offset:19456
	ds_read_b128 v[194:197], v160
	ds_read_b128 v[198:201], v160 offset:1024
	ds_read_b128 v[202:205], v160 offset:2048
	ds_read_b128 v[206:209], v160 offset:3072
	ds_read_b128 v[218:221], v160 offset:4096
	ds_read_b128 v[222:225], v160 offset:5120
	ds_read_b128 v[226:229], v160 offset:6144
	ds_read_b128 v[230:233], v160 offset:7168
	s_waitcnt vmcnt(8)
	s_waitcnt lgkmcnt(0)
	s_barrier
	s_waitcnt lgkmcnt(0)
	v_mfma_f32_16x16x32_bf16 v[126:129], v[130:133], v[194:197], 0
	v_mfma_f32_16x16x32_bf16 v[122:125], v[138:141], v[194:197], 0
	v_mfma_f32_16x16x32_bf16 v[118:121], v[130:133], v[202:205], 0
	v_mfma_f32_16x16x32_bf16 v[110:113], v[138:141], v[202:205], 0
	v_mfma_f32_16x16x32_bf16 v[102:105], v[130:133], v[218:221], 0
	v_mfma_f32_16x16x32_bf16 v[94:97], v[138:141], v[218:221], 0
	v_mfma_f32_16x16x32_bf16 v[86:89], v[130:133], v[226:229], 0
	v_mfma_f32_16x16x32_bf16 v[78:81], v[138:141], v[226:229], 0
	v_mfma_f32_16x16x32_bf16 v[126:129], v[134:137], v[198:201], v[126:129]
	v_mfma_f32_16x16x32_bf16 v[122:125], v[142:145], v[198:201], v[122:125]
	v_mfma_f32_16x16x32_bf16 v[118:121], v[134:137], v[206:209], v[118:121]
	v_mfma_f32_16x16x32_bf16 v[110:113], v[142:145], v[206:209], v[110:113]
	v_mfma_f32_16x16x32_bf16 v[102:105], v[134:137], v[222:225], v[102:105]
	v_mfma_f32_16x16x32_bf16 v[94:97], v[142:145], v[222:225], v[94:97]
	v_mfma_f32_16x16x32_bf16 v[86:89], v[134:137], v[230:233], v[86:89]
	v_mfma_f32_16x16x32_bf16 v[78:81], v[142:145], v[230:233], v[78:81]
	v_mfma_f32_16x16x32_bf16 v[114:117], v[162:165], v[194:197], 0
	v_mfma_f32_16x16x32_bf16 v[106:109], v[170:173], v[194:197], 0
	v_mfma_f32_16x16x32_bf16 v[98:101], v[162:165], v[202:205], 0
	v_mfma_f32_16x16x32_bf16 v[90:93], v[170:173], v[202:205], 0
	v_mfma_f32_16x16x32_bf16 v[82:85], v[162:165], v[218:221], 0
	v_mfma_f32_16x16x32_bf16 v[74:77], v[170:173], v[218:221], 0
	v_mfma_f32_16x16x32_bf16 v[70:73], v[162:165], v[226:229], 0
	v_mfma_f32_16x16x32_bf16 v[66:69], v[170:173], v[226:229], 0
	v_mfma_f32_16x16x32_bf16 v[114:117], v[166:169], v[198:201], v[114:117]
	v_mfma_f32_16x16x32_bf16 v[106:109], v[190:193], v[198:201], v[106:109]
	v_mfma_f32_16x16x32_bf16 v[98:101], v[166:169], v[206:209], v[98:101]
	v_mfma_f32_16x16x32_bf16 v[90:93], v[190:193], v[206:209], v[90:93]
	v_mfma_f32_16x16x32_bf16 v[82:85], v[166:169], v[222:225], v[82:85]
	v_mfma_f32_16x16x32_bf16 v[74:77], v[190:193], v[222:225], v[74:77]
	v_mfma_f32_16x16x32_bf16 v[70:73], v[166:169], v[230:233], v[70:73]
	v_mfma_f32_16x16x32_bf16 v[66:69], v[190:193], v[230:233], v[66:69]
	s_barrier
	s_add_i32 s79, s79, s8
	s_mov_b32 m0, s79
	s_nop 0
	s_setprio 2
	global_load_lds_dwordx4 v148, s[76:77]
	s_add_i32 m0, s79, 0x2000
	s_add_u32 s80, s76, 0x40000
	s_addc_u32 s81, s77, 0
	s_add_i32 s79, s82, s8
	global_load_lds_dwordx4 v152, s[76:77]
	s_mov_b32 m0, s79
	s_nop 0
	global_load_lds_dwordx4 v148, s[80:81]
	s_add_i32 m0, s79, 0x2000
	s_nop 0
	global_load_lds_dwordx4 v152, s[80:81]
	s_mov_b32 m0, s9
	s_nop 0
	global_load_lds_dwordx4 v146, s[20:21]
	s_mov_b32 m0, s28
	s_nop 0
	global_load_lds_dwordx4 v150, s[20:21]
	s_setprio 0
	ds_read_b128 v[194:197], v160 offset:16384
	ds_read_b128 v[198:201], v160 offset:17408
	ds_read_b128 v[202:205], v160 offset:18432
	ds_read_b128 v[206:209], v160 offset:19456
	ds_read_b128 v[218:221], v160 offset:20480
	ds_read_b128 v[222:225], v160 offset:21504
	ds_read_b128 v[226:229], v160 offset:22528
	ds_read_b128 v[230:233], v160 offset:23552
	s_waitcnt vmcnt(8)
	s_waitcnt lgkmcnt(0)
	s_barrier
; #define PG8_STAGE(bufoff, gbase, voff) do { _Pragma("unroll") for (int _i = 0; _i < 2; ++_i) \
;         __builtin_amdgcn_global_load_lds((const unsigned*)((const char*)(gbase) + (voff)[_i]), (LAS unsigned*)(lds + (bufoff) + ldsw + _i * 8192), 16, 0, 0); } while (0)
; #define PG8_LDA(dst, b, h) do { _Pragma("unroll") for (int m = 0; m < 4; ++m) _Pragma("unroll") for (int k = 0; k < 2; ++k) dst[m][k] = *(const LAS bf16x8*)(lds + PG8_SA(b, h) + aoff + m * 2048 + k * 1024); } while (0)
; #define PG8_LDB(dst, b, h) do { _Pragma("unroll") for (int n = 0; n < 2; ++n) _Pragma("unroll") for (int k = 0; k < 2; ++k) dst[n][k] = *(const LAS bf16x8*)(lds + PG8_SB(b, h) + boff + n * 2048 + k * 1024); } while (0)
; #define PG8_MMA(ai, bj, At, Bt) do { __builtin_amdgcn_s_setprio(1); _Pragma("unroll") for (int m = 0; m < 4; ++m) _Pragma("unroll") for (int n = 0; n < 2; ++n) _Pragma("unroll") for (int k = 0; k < 2; ++k) \
;         acc[ai][bj][m][n] = __builtin_amdgcn_mfma_f32_16x16x32_bf16(Bt[n][k], At[m][k], acc[ai][bj][m][n], 0, 0, 0); __builtin_amdgcn_s_setprio(0); } while (0)
; #define PG8_WAIT_V(n) asm volatile("s_waitcnt vmcnt(" #n ")" ::: "memory")
; #define PG8_WAIT_L(n) asm volatile("s_waitcnt lgkmcnt(" #n ")" ::: "memory")
; #define PG8_BAR __builtin_amdgcn_s_barrier()
; #define PG8_SCHED __builtin_amdgcn_sched_barrier(0)
; template <class Epi, class Sched>
; __device__ __forceinline__ void gemm_phase(LAS unsigned char* lds, const Gemm g, const Sched& S, const Epi& E) {
;     ...
;             PG8_WAIT_V(8); PG8_WAIT_L(0); PG8_BAR; PG8_MMA(1, 0, At, B0); PG8_MMA(1, 1, At, B1); PG8_BAR; PG8_SCHED;
;             PG8_LDB(B0, 1, 0); PG8_LDB(B1, 1, 1); PG8_SCHED; PG8_LDA(At, 1, 0); PG8_STAGE(PG8_SA(0, 1), a2 + hstepA, voffA);
;             PG8_WAIT_V(8); PG8_WAIT_L(0); PG8_BAR; PG8_MMA(0, 0, At, B0); PG8_MMA(0, 1, At, B1); PG8_BAR; PG8_SCHED;
	s_waitcnt lgkmcnt(0)
	v_mfma_f32_16x16x32_bf16 v[62:65], v[130:133], v[194:197], 0
	v_mfma_f32_16x16x32_bf16 v[58:61], v[138:141], v[194:197], 0
	v_mfma_f32_16x16x32_bf16 v[54:57], v[130:133], v[202:205], 0
	v_mfma_f32_16x16x32_bf16 v[46:49], v[138:141], v[202:205], 0
	v_mfma_f32_16x16x32_bf16 v[38:41], v[130:133], v[218:221], 0
	v_mfma_f32_16x16x32_bf16 v[30:33], v[138:141], v[218:221], 0
	v_mfma_f32_16x16x32_bf16 v[22:25], v[130:133], v[226:229], 0
	v_mfma_f32_16x16x32_bf16 v[14:17], v[138:141], v[226:229], 0
	v_mfma_f32_16x16x32_bf16 v[62:65], v[134:137], v[198:201], v[62:65]
	v_mfma_f32_16x16x32_bf16 v[58:61], v[142:145], v[198:201], v[58:61]
	v_mfma_f32_16x16x32_bf16 v[54:57], v[134:137], v[206:209], v[54:57]
	v_mfma_f32_16x16x32_bf16 v[46:49], v[142:145], v[206:209], v[46:49]
	v_mfma_f32_16x16x32_bf16 v[38:41], v[134:137], v[222:225], v[38:41]
	v_mfma_f32_16x16x32_bf16 v[30:33], v[142:145], v[222:225], v[30:33]
	v_mfma_f32_16x16x32_bf16 v[22:25], v[134:137], v[230:233], v[22:25]
	v_mfma_f32_16x16x32_bf16 v[14:17], v[142:145], v[230:233], v[14:17]
	v_mfma_f32_16x16x32_bf16 v[50:53], v[162:165], v[194:197], 0
	v_mfma_f32_16x16x32_bf16 v[42:45], v[170:173], v[194:197], 0
	v_mfma_f32_16x16x32_bf16 v[34:37], v[162:165], v[202:205], 0
	v_mfma_f32_16x16x32_bf16 v[26:29], v[170:173], v[202:205], 0
	v_mfma_f32_16x16x32_bf16 v[18:21], v[162:165], v[218:221], 0
	v_mfma_f32_16x16x32_bf16 v[10:13], v[170:173], v[218:221], 0
	v_mfma_f32_16x16x32_bf16 v[6:9], v[162:165], v[226:229], 0
	v_mfma_f32_16x16x32_bf16 v[2:5], v[170:173], v[226:229], 0
	v_mfma_f32_16x16x32_bf16 v[50:53], v[166:169], v[198:201], v[50:53]
	v_mfma_f32_16x16x32_bf16 v[42:45], v[190:193], v[198:201], v[42:45]
	v_mfma_f32_16x16x32_bf16 v[34:37], v[166:169], v[206:209], v[34:37]
	v_mfma_f32_16x16x32_bf16 v[26:29], v[190:193], v[206:209], v[26:29]
	v_mfma_f32_16x16x32_bf16 v[18:21], v[166:169], v[222:225], v[18:21]
	v_mfma_f32_16x16x32_bf16 v[10:13], v[190:193], v[222:225], v[10:13]
	v_mfma_f32_16x16x32_bf16 v[6:9], v[166:169], v[230:233], v[6:9]
	v_mfma_f32_16x16x32_bf16 v[2:5], v[190:193], v[230:233], v[2:5]
	s_barrier
	s_add_i32 s79, 0, 0x18000
	s_add_i32 s80, 0, 0x1c000
	s_add_u32 s20, s20, 0x40000
	s_addc_u32 s21, s21, 0
	s_mov_b32 m0, s29
	s_nop 0
	s_setprio 2
	global_load_lds_dwordx4 v146, s[20:21]
	s_mov_b32 m0, s30
	s_nop 0
	global_load_lds_dwordx4 v150, s[20:21]
	s_setprio 0
	ds_read_b128 v[130:133], v255 offset:32768
	ds_read_b128 v[134:137], v255 offset:33792
	ds_read_b128 v[138:141], v255 offset:34816
	ds_read_b128 v[142:145], v255 offset:35840
	ds_read_b128 v[162:165], v255 offset:49152
	ds_read_b128 v[166:169], v255 offset:50176
	ds_read_b128 v[170:173], v255 offset:51200
	ds_read_b128 v[190:193], v255 offset:52224
	ds_read_b128 v[194:197], v160 offset:32768
	ds_read_b128 v[198:201], v160 offset:33792
	ds_read_b128 v[202:205], v160 offset:34816
	ds_read_b128 v[206:209], v160 offset:35840
	ds_read_b128 v[218:221], v160 offset:36864
	ds_read_b128 v[222:225], v160 offset:37888
	ds_read_b128 v[226:229], v160 offset:38912
	ds_read_b128 v[230:233], v160 offset:39936
	s_waitcnt vmcnt(8)
	s_waitcnt lgkmcnt(0)
	s_barrier
	s_waitcnt lgkmcnt(0)
	v_mfma_f32_16x16x32_bf16 v[126:129], v[130:133], v[194:197], v[126:129]
	v_mfma_f32_16x16x32_bf16 v[122:125], v[138:141], v[194:197], v[122:125]
	v_mfma_f32_16x16x32_bf16 v[118:121], v[130:133], v[202:205], v[118:121]
	v_mfma_f32_16x16x32_bf16 v[110:113], v[138:141], v[202:205], v[110:113]
	v_mfma_f32_16x16x32_bf16 v[102:105], v[130:133], v[218:221], v[102:105]
	v_mfma_f32_16x16x32_bf16 v[94:97], v[138:141], v[218:221], v[94:97]
	v_mfma_f32_16x16x32_bf16 v[86:89], v[130:133], v[226:229], v[86:89]
	v_mfma_f32_16x16x32_bf16 v[78:81], v[138:141], v[226:229], v[78:81]
	v_mfma_f32_16x16x32_bf16 v[126:129], v[134:137], v[198:201], v[126:129]
	v_mfma_f32_16x16x32_bf16 v[122:125], v[142:145], v[198:201], v[122:125]
	v_mfma_f32_16x16x32_bf16 v[118:121], v[134:137], v[206:209], v[118:121]
	v_mfma_f32_16x16x32_bf16 v[110:113], v[142:145], v[206:209], v[110:113]
	v_mfma_f32_16x16x32_bf16 v[102:105], v[134:137], v[222:225], v[102:105]
	v_mfma_f32_16x16x32_bf16 v[94:97], v[142:145], v[222:225], v[94:97]
	v_mfma_f32_16x16x32_bf16 v[86:89], v[134:137], v[230:233], v[86:89]
	v_mfma_f32_16x16x32_bf16 v[78:81], v[142:145], v[230:233], v[78:81]
	v_mfma_f32_16x16x32_bf16 v[114:117], v[162:165], v[194:197], v[114:117]
	v_mfma_f32_16x16x32_bf16 v[106:109], v[170:173], v[194:197], v[106:109]
	v_mfma_f32_16x16x32_bf16 v[98:101], v[162:165], v[202:205], v[98:101]
	v_mfma_f32_16x16x32_bf16 v[90:93], v[170:173], v[202:205], v[90:93]
	v_mfma_f32_16x16x32_bf16 v[82:85], v[162:165], v[218:221], v[82:85]
	v_mfma_f32_16x16x32_bf16 v[74:77], v[170:173], v[218:221], v[74:77]
	v_mfma_f32_16x16x32_bf16 v[70:73], v[162:165], v[226:229], v[70:73]
	v_mfma_f32_16x16x32_bf16 v[66:69], v[170:173], v[226:229], v[66:69]
	v_mfma_f32_16x16x32_bf16 v[114:117], v[166:169], v[198:201], v[114:117]
	v_mfma_f32_16x16x32_bf16 v[106:109], v[190:193], v[198:201], v[106:109]
	v_mfma_f32_16x16x32_bf16 v[98:101], v[166:169], v[206:209], v[98:101]
	v_mfma_f32_16x16x32_bf16 v[90:93], v[190:193], v[206:209], v[90:93]
	v_mfma_f32_16x16x32_bf16 v[82:85], v[166:169], v[222:225], v[82:85]
	v_mfma_f32_16x16x32_bf16 v[74:77], v[190:193], v[222:225], v[74:77]
	v_mfma_f32_16x16x32_bf16 v[70:73], v[166:169], v[230:233], v[70:73]
	v_mfma_f32_16x16x32_bf16 v[66:69], v[190:193], v[230:233], v[66:69]
	s_barrier
; #define PG8_STAGE(bufoff, gbase, voff) do { _Pragma("unroll") for (int _i = 0; _i < 2; ++_i) \
;         __builtin_amdgcn_global_load_lds((const unsigned*)((const char*)(gbase) + (voff)[_i]), (LAS unsigned*)(lds + (bufoff) + ldsw + _i * 8192), 16, 0, 0); } while (0)
; #define PG8_LDA(dst, b, h) do { _Pragma("unroll") for (int m = 0; m < 4; ++m) _Pragma("unroll") for (int k = 0; k < 2; ++k) dst[m][k] = *(const LAS bf16x8*)(lds + PG8_SA(b, h) + aoff + m * 2048 + k * 1024); } while (0)
; #define PG8_LDB(dst, b, h) do { _Pragma("unroll") for (int n = 0; n < 2; ++n) _Pragma("unroll") for (int k = 0; k < 2; ++k) dst[n][k] = *(const LAS bf16x8*)(lds + PG8_SB(b, h) + boff + n * 2048 + k * 1024); } while (0)
; #define PG8_MMA(ai, bj, At, Bt) do { __builtin_amdgcn_s_setprio(1); _Pragma("unroll") for (int m = 0; m < 4; ++m) _Pragma("unroll") for (int n = 0; n < 2; ++n) _Pragma("unroll") for (int k = 0; k < 2; ++k) \
;         acc[ai][bj][m][n] = __builtin_amdgcn_mfma_f32_16x16x32_bf16(Bt[n][k], At[m][k], acc[ai][bj][m][n], 0, 0, 0); __builtin_amdgcn_s_setprio(0); } while (0)
; #define PG8_WAIT_V(n) asm volatile("s_waitcnt vmcnt(" #n ")" ::: "memory")
; #define PG8_WAIT_L(n) asm volatile("s_waitcnt lgkmcnt(" #n ")" ::: "memory")
; #define PG8_BAR __builtin_amdgcn_s_barrier()
; #define PG8_SCHED __builtin_amdgcn_sched_barrier(0)
; template <class Epi, class Sched>
; __device__ __forceinline__ void gemm_phase(LAS unsigned char* lds, const Gemm g, const Sched& S, const Epi& E) {
;     ...
;         for (int t = 0; t < nt; t += 2) {
;             const bool last = (t == nt - 2);
;             const char* a1 = cA + (size_t)(t + 1) * kstep;
;             const char* a2 = last ? nA : cA + (size_t)(t + 2) * kstep; const char* b2 = last ? nB : cB + (size_t)(t + 2) * kstep;
;             const char* a3 = a2 + kstep; const char* b3 = b2 + kstep;
;             PG8_LDB(B0, 0, 0); PG8_LDB(B1, 0, 1); PG8_SCHED; PG8_LDA(At, 0, 0); PG8_STAGE(PG8_SA(1, 1), a1 + hstepA, voffA);
;             PG8_WAIT_V(8); PG8_WAIT_L(0); PG8_BAR; PG8_MMA(0, 0, At, B0); PG8_MMA(0, 1, At, B1); PG8_BAR; PG8_SCHED;
;     ...
;             PG8_LDA(At, 1, 1); PG8_STAGE(PG8_SB(1, 0), b3, voffB); PG8_STAGE(PG8_SB(1, 1), b3 + hstepB, voffB); PG8_STAGE(PG8_SA(1, 0), a3, voffA);
;             PG8_WAIT_V(8); PG8_WAIT_L(0); PG8_BAR; PG8_MMA(1, 0, At, B0); PG8_MMA(1, 1, At, B1); PG8_BAR; PG8_SCHED;
	s_add_i32 s20, s8, 0x18000
	s_add_u32 s80, s76, 0x80
	s_addc_u32 s81, s77, 0
	s_mov_b32 m0, s20
	s_nop 0
	s_setprio 2
	global_load_lds_dwordx4 v148, s[80:81]
	s_add_i32 m0, s20, 0x2000
	s_add_u32 s20, s76, 0x40080
	s_addc_u32 s21, s77, 0
	s_add_i32 s12, s8, 0x1c000
	global_load_lds_dwordx4 v152, s[80:81]
	s_mov_b32 m0, s12
	s_nop 0
	global_load_lds_dwordx4 v148, s[20:21]
	s_add_i32 m0, s12, 0x2000
	s_nop 0
	global_load_lds_dwordx4 v152, s[20:21]
	s_mov_b32 m0, s31
	s_nop 0
	global_load_lds_dwordx4 v146, s[100:101]
	s_mov_b32 m0, s34
	s_nop 0
	global_load_lds_dwordx4 v150, s[100:101]
	s_setprio 0
	ds_read_b128 v[194:197], v160 offset:49152
	ds_read_b128 v[198:201], v160 offset:50176
	ds_read_b128 v[202:205], v160 offset:51200
	ds_read_b128 v[206:209], v160 offset:52224
	ds_read_b128 v[218:221], v160 offset:53248
	ds_read_b128 v[222:225], v160 offset:54272
	ds_read_b128 v[226:229], v160 offset:55296
	ds_read_b128 v[230:233], v160 offset:56320
	s_waitcnt vmcnt(8)
	s_waitcnt lgkmcnt(0)
	s_barrier
	s_waitcnt lgkmcnt(0)
	v_mfma_f32_16x16x32_bf16 v[62:65], v[130:133], v[194:197], v[62:65]
	v_mfma_f32_16x16x32_bf16 v[58:61], v[138:141], v[194:197], v[58:61]
	v_mfma_f32_16x16x32_bf16 v[54:57], v[130:133], v[202:205], v[54:57]
	v_mfma_f32_16x16x32_bf16 v[46:49], v[138:141], v[202:205], v[46:49]
	v_mfma_f32_16x16x32_bf16 v[38:41], v[130:133], v[218:221], v[38:41]
	v_mfma_f32_16x16x32_bf16 v[30:33], v[138:141], v[218:221], v[30:33]
	v_mfma_f32_16x16x32_bf16 v[22:25], v[130:133], v[226:229], v[22:25]
	v_mfma_f32_16x16x32_bf16 v[14:17], v[138:141], v[226:229], v[14:17]
	v_mfma_f32_16x16x32_bf16 v[62:65], v[134:137], v[198:201], v[62:65]
	v_mfma_f32_16x16x32_bf16 v[58:61], v[142:145], v[198:201], v[58:61]
	v_mfma_f32_16x16x32_bf16 v[54:57], v[134:137], v[206:209], v[54:57]
	v_mfma_f32_16x16x32_bf16 v[46:49], v[142:145], v[206:209], v[46:49]
	v_mfma_f32_16x16x32_bf16 v[38:41], v[134:137], v[222:225], v[38:41]
	v_mfma_f32_16x16x32_bf16 v[30:33], v[142:145], v[222:225], v[30:33]
	v_mfma_f32_16x16x32_bf16 v[22:25], v[134:137], v[230:233], v[22:25]
	v_mfma_f32_16x16x32_bf16 v[14:17], v[142:145], v[230:233], v[14:17]
	v_mfma_f32_16x16x32_bf16 v[50:53], v[162:165], v[194:197], v[50:53]
	v_mfma_f32_16x16x32_bf16 v[42:45], v[170:173], v[194:197], v[42:45]
	v_mfma_f32_16x16x32_bf16 v[34:37], v[162:165], v[202:205], v[34:37]
	v_mfma_f32_16x16x32_bf16 v[26:29], v[170:173], v[202:205], v[26:29]
	v_mfma_f32_16x16x32_bf16 v[18:21], v[162:165], v[218:221], v[18:21]
	v_mfma_f32_16x16x32_bf16 v[10:13], v[170:173], v[218:221], v[10:13]
	v_mfma_f32_16x16x32_bf16 v[6:9], v[162:165], v[226:229], v[6:9]
	v_mfma_f32_16x16x32_bf16 v[2:5], v[170:173], v[226:229], v[2:5]
	v_mfma_f32_16x16x32_bf16 v[50:53], v[166:169], v[198:201], v[50:53]
	v_mfma_f32_16x16x32_bf16 v[42:45], v[190:193], v[198:201], v[42:45]
	v_mfma_f32_16x16x32_bf16 v[34:37], v[166:169], v[206:209], v[34:37]
	v_mfma_f32_16x16x32_bf16 v[26:29], v[190:193], v[206:209], v[26:29]
	v_mfma_f32_16x16x32_bf16 v[18:21], v[166:169], v[222:225], v[18:21]
	v_mfma_f32_16x16x32_bf16 v[10:13], v[190:193], v[222:225], v[10:13]
	v_mfma_f32_16x16x32_bf16 v[6:9], v[166:169], v[230:233], v[6:9]
	v_mfma_f32_16x16x32_bf16 v[2:5], v[190:193], v[230:233], v[2:5]
	s_barrier
	s_add_i32 s78, s78, 2
	s_add_u32 s18, s18, 0x100
	s_addc_u32 s19, s19, 0
	s_add_u32 s69, s69, 0x100
	s_addc_u32 s71, s71, 0
	s_cmp_gt_u32 s78, 13
.LBB0_378:
	s_add_u32 s20, s18, 0xfffc0080
	s_addc_u32 s21, s19, -1
	s_add_i32 s79, 0, 0x10000
	s_cmp_eq_u32 s78, 12
	s_cselect_b32 s21, s43, s21
	s_cselect_b32 s20, s48, s20
	s_cselect_b32 s77, s49, s71
	s_cselect_b32 s76, s53, s69
	s_add_u32 s100, s20, 0x80
	s_addc_u32 s101, s21, 0
	s_add_i32 s82, 0, 0x14000
	s_add_i32 m0, s9, 0xc000
	s_nop 0
	s_setprio 2
	global_load_lds_dwordx4 v146, s[18:19]
	s_add_i32 m0, s9, 0xe000
	s_nop 0
	global_load_lds_dwordx4 v150, s[18:19]
	s_setprio 0
	ds_read_b128 v[130:133], v255
	ds_read_b128 v[134:137], v255 offset:1024
	ds_read_b128 v[138:141], v255 offset:2048
	ds_read_b128 v[142:145], v255 offset:3072
	ds_read_b128 v[162:165], v255 offset:16384
	ds_read_b128 v[166:169], v255 offset:17408
	ds_read_b128 v[170:173], v255 offset:18432
	ds_read_b128 v[190:193], v255 offset:19456
	ds_read_b128 v[194:197], v160
	ds_read_b128 v[198:201], v160 offset:1024
	ds_read_b128 v[202:205], v160 offset:2048
	ds_read_b128 v[206:209], v160 offset:3072
	ds_read_b128 v[218:221], v160 offset:4096
	ds_read_b128 v[222:225], v160 offset:5120
	ds_read_b128 v[226:229], v160 offset:6144
	ds_read_b128 v[230:233], v160 offset:7168
	s_waitcnt vmcnt(8)
	s_waitcnt lgkmcnt(0)
	s_barrier
; #define PG8_STAGE(bufoff, gbase, voff) do { _Pragma("unroll") for (int _i = 0; _i < 2; ++_i) \
;         __builtin_amdgcn_global_load_lds((const unsigned*)((const char*)(gbase) + (voff)[_i]), (LAS unsigned*)(lds + (bufoff) + ldsw + _i * 8192), 16, 0, 0); } while (0)
; #define PG8_LDA(dst, b, h) do { _Pragma("unroll") for (int m = 0; m < 4; ++m) _Pragma("unroll") for (int k = 0; k < 2; ++k) dst[m][k] = *(const LAS bf16x8*)(lds + PG8_SA(b, h) + aoff + m * 2048 + k * 1024); } while (0)
; #define PG8_MMA(ai, bj, At, Bt) do { __builtin_amdgcn_s_setprio(1); _Pragma("unroll") for (int m = 0; m < 4; ++m) _Pragma("unroll") for (int n = 0; n < 2; ++n) _Pragma("unroll") for (int k = 0; k < 2; ++k) \
;         acc[ai][bj][m][n] = __builtin_amdgcn_mfma_f32_16x16x32_bf16(Bt[n][k], At[m][k], acc[ai][bj][m][n], 0, 0, 0); __builtin_amdgcn_s_setprio(0); } while (0)
; #define PG8_WAIT_V(n) asm volatile("s_waitcnt vmcnt(" #n ")" ::: "memory")
; #define PG8_WAIT_L(n) asm volatile("s_waitcnt lgkmcnt(" #n ")" ::: "memory")
; #define PG8_BAR __builtin_amdgcn_s_barrier()
; #define PG8_SCHED __builtin_amdgcn_sched_barrier(0)
; template <class Epi, class Sched>
; __device__ __forceinline__ void gemm_phase(LAS unsigned char* lds, const Gemm g, const Sched& S, const Epi& E) {
;     ...
;             PG8_WAIT_V(8); PG8_WAIT_L(0); PG8_BAR; PG8_MMA(0, 0, At, B0); PG8_MMA(0, 1, At, B1); PG8_BAR; PG8_SCHED;
;             PG8_LDA(At, 0, 1); PG8_STAGE(PG8_SB(0, 0), b2, voffB); PG8_STAGE(PG8_SB(0, 1), b2 + hstepB, voffB); PG8_STAGE(PG8_SA(0, 0), a2, voffA);
;             PG8_WAIT_V(8); PG8_WAIT_L(0); PG8_BAR; PG8_MMA(1, 0, At, B0); PG8_MMA(1, 1, At, B1); PG8_BAR; PG8_SCHED;
	s_waitcnt lgkmcnt(0)
	v_mfma_f32_16x16x32_bf16 v[126:129], v[130:133], v[194:197], v[126:129]
	v_mfma_f32_16x16x32_bf16 v[122:125], v[138:141], v[194:197], v[122:125]
	v_mfma_f32_16x16x32_bf16 v[118:121], v[130:133], v[202:205], v[118:121]
	v_mfma_f32_16x16x32_bf16 v[110:113], v[138:141], v[202:205], v[110:113]
	v_mfma_f32_16x16x32_bf16 v[102:105], v[130:133], v[218:221], v[102:105]
	v_mfma_f32_16x16x32_bf16 v[94:97], v[138:141], v[218:221], v[94:97]
	v_mfma_f32_16x16x32_bf16 v[86:89], v[130:133], v[226:229], v[86:89]
	v_mfma_f32_16x16x32_bf16 v[78:81], v[138:141], v[226:229], v[78:81]
	v_mfma_f32_16x16x32_bf16 v[126:129], v[134:137], v[198:201], v[126:129]
	v_mfma_f32_16x16x32_bf16 v[122:125], v[142:145], v[198:201], v[122:125]
	v_mfma_f32_16x16x32_bf16 v[118:121], v[134:137], v[206:209], v[118:121]
	v_mfma_f32_16x16x32_bf16 v[110:113], v[142:145], v[206:209], v[110:113]
	v_mfma_f32_16x16x32_bf16 v[102:105], v[134:137], v[222:225], v[102:105]
	v_mfma_f32_16x16x32_bf16 v[94:97], v[142:145], v[222:225], v[94:97]
	v_mfma_f32_16x16x32_bf16 v[86:89], v[134:137], v[230:233], v[86:89]
	v_mfma_f32_16x16x32_bf16 v[78:81], v[142:145], v[230:233], v[78:81]
	v_mfma_f32_16x16x32_bf16 v[114:117], v[162:165], v[194:197], v[114:117]
	v_mfma_f32_16x16x32_bf16 v[106:109], v[170:173], v[194:197], v[106:109]
	v_mfma_f32_16x16x32_bf16 v[98:101], v[162:165], v[202:205], v[98:101]
	v_mfma_f32_16x16x32_bf16 v[90:93], v[170:173], v[202:205], v[90:93]
	v_mfma_f32_16x16x32_bf16 v[82:85], v[162:165], v[218:221], v[82:85]
	v_mfma_f32_16x16x32_bf16 v[74:77], v[170:173], v[218:221], v[74:77]
	v_mfma_f32_16x16x32_bf16 v[70:73], v[162:165], v[226:229], v[70:73]
	v_mfma_f32_16x16x32_bf16 v[66:69], v[170:173], v[226:229], v[66:69]
	v_mfma_f32_16x16x32_bf16 v[114:117], v[166:169], v[198:201], v[114:117]
	v_mfma_f32_16x16x32_bf16 v[106:109], v[190:193], v[198:201], v[106:109]
	v_mfma_f32_16x16x32_bf16 v[98:101], v[166:169], v[206:209], v[98:101]
	v_mfma_f32_16x16x32_bf16 v[90:93], v[190:193], v[206:209], v[90:93]
	v_mfma_f32_16x16x32_bf16 v[82:85], v[166:169], v[222:225], v[82:85]
	v_mfma_f32_16x16x32_bf16 v[74:77], v[190:193], v[222:225], v[74:77]
	v_mfma_f32_16x16x32_bf16 v[70:73], v[166:169], v[230:233], v[70:73]
	v_mfma_f32_16x16x32_bf16 v[66:69], v[190:193], v[230:233], v[66:69]
	s_barrier
	s_add_i32 s79, s79, s8
	s_mov_b32 m0, s79
	s_nop 0
	s_setprio 2
	global_load_lds_dwordx4 v148, s[76:77]
	s_add_i32 m0, s79, 0x2000
	s_add_u32 s80, s76, 0x40000
	s_addc_u32 s81, s77, 0
	s_add_i32 s79, s82, s8
	global_load_lds_dwordx4 v152, s[76:77]
	s_mov_b32 m0, s79
	s_nop 0
	global_load_lds_dwordx4 v148, s[80:81]
	s_add_i32 m0, s79, 0x2000
	s_nop 0
	global_load_lds_dwordx4 v152, s[80:81]
	s_mov_b32 m0, s9
	s_nop 0
	global_load_lds_dwordx4 v146, s[20:21]
	s_mov_b32 m0, s28
	s_nop 0
	global_load_lds_dwordx4 v150, s[20:21]
	s_setprio 0
	ds_read_b128 v[194:197], v160 offset:16384
	ds_read_b128 v[198:201], v160 offset:17408
	ds_read_b128 v[202:205], v160 offset:18432
	ds_read_b128 v[206:209], v160 offset:19456
	ds_read_b128 v[218:221], v160 offset:20480
	ds_read_b128 v[222:225], v160 offset:21504
	ds_read_b128 v[226:229], v160 offset:22528
	ds_read_b128 v[230:233], v160 offset:23552
	s_waitcnt vmcnt(8)
	s_waitcnt lgkmcnt(0)
	s_barrier
	s_waitcnt lgkmcnt(0)
	v_mfma_f32_16x16x32_bf16 v[62:65], v[130:133], v[194:197], v[62:65]
	v_mfma_f32_16x16x32_bf16 v[58:61], v[138:141], v[194:197], v[58:61]
	v_mfma_f32_16x16x32_bf16 v[54:57], v[130:133], v[202:205], v[54:57]
	v_mfma_f32_16x16x32_bf16 v[46:49], v[138:141], v[202:205], v[46:49]
	v_mfma_f32_16x16x32_bf16 v[38:41], v[130:133], v[218:221], v[38:41]
	v_mfma_f32_16x16x32_bf16 v[30:33], v[138:141], v[218:221], v[30:33]
	v_mfma_f32_16x16x32_bf16 v[22:25], v[130:133], v[226:229], v[22:25]
	v_mfma_f32_16x16x32_bf16 v[14:17], v[138:141], v[226:229], v[14:17]
	v_mfma_f32_16x16x32_bf16 v[62:65], v[134:137], v[198:201], v[62:65]
	v_mfma_f32_16x16x32_bf16 v[58:61], v[142:145], v[198:201], v[58:61]
	v_mfma_f32_16x16x32_bf16 v[54:57], v[134:137], v[206:209], v[54:57]
	v_mfma_f32_16x16x32_bf16 v[46:49], v[142:145], v[206:209], v[46:49]
	v_mfma_f32_16x16x32_bf16 v[38:41], v[134:137], v[222:225], v[38:41]
	v_mfma_f32_16x16x32_bf16 v[30:33], v[142:145], v[222:225], v[30:33]
	v_mfma_f32_16x16x32_bf16 v[22:25], v[134:137], v[230:233], v[22:25]
	v_mfma_f32_16x16x32_bf16 v[14:17], v[142:145], v[230:233], v[14:17]
	v_mfma_f32_16x16x32_bf16 v[50:53], v[162:165], v[194:197], v[50:53]
	v_mfma_f32_16x16x32_bf16 v[42:45], v[170:173], v[194:197], v[42:45]
	v_mfma_f32_16x16x32_bf16 v[34:37], v[162:165], v[202:205], v[34:37]
	v_mfma_f32_16x16x32_bf16 v[26:29], v[170:173], v[202:205], v[26:29]
	v_mfma_f32_16x16x32_bf16 v[18:21], v[162:165], v[218:221], v[18:21]
	v_mfma_f32_16x16x32_bf16 v[10:13], v[170:173], v[218:221], v[10:13]
	v_mfma_f32_16x16x32_bf16 v[6:9], v[162:165], v[226:229], v[6:9]
	v_mfma_f32_16x16x32_bf16 v[2:5], v[170:173], v[226:229], v[2:5]
	v_mfma_f32_16x16x32_bf16 v[50:53], v[166:169], v[198:201], v[50:53]
	v_mfma_f32_16x16x32_bf16 v[42:45], v[190:193], v[198:201], v[42:45]
	v_mfma_f32_16x16x32_bf16 v[34:37], v[166:169], v[206:209], v[34:37]
	v_mfma_f32_16x16x32_bf16 v[26:29], v[190:193], v[206:209], v[26:29]
	v_mfma_f32_16x16x32_bf16 v[18:21], v[166:169], v[222:225], v[18:21]
	v_mfma_f32_16x16x32_bf16 v[10:13], v[190:193], v[222:225], v[10:13]
	v_mfma_f32_16x16x32_bf16 v[6:9], v[166:169], v[230:233], v[6:9]
	v_mfma_f32_16x16x32_bf16 v[2:5], v[190:193], v[230:233], v[2:5]
	s_barrier
; #define PG8_STAGE(bufoff, gbase, voff) do { _Pragma("unroll") for (int _i = 0; _i < 2; ++_i) \
;         __builtin_amdgcn_global_load_lds((const unsigned*)((const char*)(gbase) + (voff)[_i]), (LAS unsigned*)(lds + (bufoff) + ldsw + _i * 8192), 16, 0, 0); } while (0)
; #define PG8_LDA(dst, b, h) do { _Pragma("unroll") for (int m = 0; m < 4; ++m) _Pragma("unroll") for (int k = 0; k < 2; ++k) dst[m][k] = *(const LAS bf16x8*)(lds + PG8_SA(b, h) + aoff + m * 2048 + k * 1024); } while (0)
; #define PG8_LDB(dst, b, h) do { _Pragma("unroll") for (int n = 0; n < 2; ++n) _Pragma("unroll") for (int k = 0; k < 2; ++k) dst[n][k] = *(const LAS bf16x8*)(lds + PG8_SB(b, h) + boff + n * 2048 + k * 1024); } while (0)
; #define PG8_MMA(ai, bj, At, Bt) do { __builtin_amdgcn_s_setprio(1); _Pragma("unroll") for (int m = 0; m < 4; ++m) _Pragma("unroll") for (int n = 0; n < 2; ++n) _Pragma("unroll") for (int k = 0; k < 2; ++k) \
;         acc[ai][bj][m][n] = __builtin_amdgcn_mfma_f32_16x16x32_bf16(Bt[n][k], At[m][k], acc[ai][bj][m][n], 0, 0, 0); __builtin_amdgcn_s_setprio(0); } while (0)
; #define PG8_WAIT_V(n) asm volatile("s_waitcnt vmcnt(" #n ")" ::: "memory")
; #define PG8_WAIT_L(n) asm volatile("s_waitcnt lgkmcnt(" #n ")" ::: "memory")
; #define PG8_BAR __builtin_amdgcn_s_barrier()
; #define PG8_SCHED __builtin_amdgcn_sched_barrier(0)
; template <class Epi, class Sched>
; __device__ __forceinline__ void gemm_phase(LAS unsigned char* lds, const Gemm g, const Sched& S, const Epi& E) {
;     ...
;             PG8_LDB(B0, 1, 0); PG8_LDB(B1, 1, 1); PG8_SCHED; PG8_LDA(At, 1, 0); PG8_STAGE(PG8_SA(0, 1), a2 + hstepA, voffA);
;             PG8_WAIT_V(8); PG8_WAIT_L(0); PG8_BAR; PG8_MMA(0, 0, At, B0); PG8_MMA(0, 1, At, B1); PG8_BAR; PG8_SCHED;
;             PG8_LDA(At, 1, 1); PG8_STAGE(PG8_SB(1, 0), b3, voffB); PG8_STAGE(PG8_SB(1, 1), b3 + hstepB, voffB); PG8_STAGE(PG8_SA(1, 0), a3, voffA);
;             PG8_WAIT_V(8); PG8_WAIT_L(0); PG8_BAR; PG8_MMA(1, 0, At, B0); PG8_MMA(1, 1, At, B1); PG8_BAR; PG8_SCHED;
;         }
;         if (wr == 0) PG8_BAR;
	s_add_i32 s79, 0, 0x18000
	s_add_i32 s80, 0, 0x1c000
	s_add_u32 s20, s20, 0x40000
	s_addc_u32 s21, s21, 0
	s_mov_b32 m0, s29
	s_nop 0
	s_setprio 2
	global_load_lds_dwordx4 v146, s[20:21]
	s_mov_b32 m0, s30
	s_nop 0
	global_load_lds_dwordx4 v150, s[20:21]
	s_setprio 0
	ds_read_b128 v[130:133], v255 offset:32768
	ds_read_b128 v[134:137], v255 offset:33792
	ds_read_b128 v[138:141], v255 offset:34816
	ds_read_b128 v[142:145], v255 offset:35840
	ds_read_b128 v[162:165], v255 offset:49152
	ds_read_b128 v[166:169], v255 offset:50176
	ds_read_b128 v[170:173], v255 offset:51200
	ds_read_b128 v[190:193], v255 offset:52224
	ds_read_b128 v[194:197], v160 offset:32768
	ds_read_b128 v[198:201], v160 offset:33792
	ds_read_b128 v[202:205], v160 offset:34816
	ds_read_b128 v[206:209], v160 offset:35840
	ds_read_b128 v[218:221], v160 offset:36864
	ds_read_b128 v[222:225], v160 offset:37888
	ds_read_b128 v[226:229], v160 offset:38912
	ds_read_b128 v[230:233], v160 offset:39936
	s_waitcnt vmcnt(8)
	s_waitcnt lgkmcnt(0)
	s_barrier
	s_waitcnt lgkmcnt(0)
	v_mfma_f32_16x16x32_bf16 v[126:129], v[130:133], v[194:197], v[126:129]
	v_mfma_f32_16x16x32_bf16 v[122:125], v[138:141], v[194:197], v[122:125]
	v_mfma_f32_16x16x32_bf16 v[118:121], v[130:133], v[202:205], v[118:121]
	v_mfma_f32_16x16x32_bf16 v[110:113], v[138:141], v[202:205], v[110:113]
	v_mfma_f32_16x16x32_bf16 v[102:105], v[130:133], v[218:221], v[102:105]
	v_mfma_f32_16x16x32_bf16 v[94:97], v[138:141], v[218:221], v[94:97]
	v_mfma_f32_16x16x32_bf16 v[86:89], v[130:133], v[226:229], v[86:89]
	v_mfma_f32_16x16x32_bf16 v[78:81], v[138:141], v[226:229], v[78:81]
	v_mfma_f32_16x16x32_bf16 v[126:129], v[134:137], v[198:201], v[126:129]
	v_mfma_f32_16x16x32_bf16 v[122:125], v[142:145], v[198:201], v[122:125]
	v_mfma_f32_16x16x32_bf16 v[118:121], v[134:137], v[206:209], v[118:121]
	v_mfma_f32_16x16x32_bf16 v[110:113], v[142:145], v[206:209], v[110:113]
	v_mfma_f32_16x16x32_bf16 v[102:105], v[134:137], v[222:225], v[102:105]
	v_mfma_f32_16x16x32_bf16 v[94:97], v[142:145], v[222:225], v[94:97]
	v_mfma_f32_16x16x32_bf16 v[86:89], v[134:137], v[230:233], v[86:89]
	v_mfma_f32_16x16x32_bf16 v[78:81], v[142:145], v[230:233], v[78:81]
	v_mfma_f32_16x16x32_bf16 v[114:117], v[162:165], v[194:197], v[114:117]
	v_mfma_f32_16x16x32_bf16 v[106:109], v[170:173], v[194:197], v[106:109]
	v_mfma_f32_16x16x32_bf16 v[98:101], v[162:165], v[202:205], v[98:101]
	v_mfma_f32_16x16x32_bf16 v[90:93], v[170:173], v[202:205], v[90:93]
	v_mfma_f32_16x16x32_bf16 v[82:85], v[162:165], v[218:221], v[82:85]
	v_mfma_f32_16x16x32_bf16 v[74:77], v[170:173], v[218:221], v[74:77]
	v_mfma_f32_16x16x32_bf16 v[70:73], v[162:165], v[226:229], v[70:73]
	v_mfma_f32_16x16x32_bf16 v[66:69], v[170:173], v[226:229], v[66:69]
	v_mfma_f32_16x16x32_bf16 v[114:117], v[166:169], v[198:201], v[114:117]
	v_mfma_f32_16x16x32_bf16 v[106:109], v[190:193], v[198:201], v[106:109]
	v_mfma_f32_16x16x32_bf16 v[98:101], v[166:169], v[206:209], v[98:101]
	v_mfma_f32_16x16x32_bf16 v[90:93], v[190:193], v[206:209], v[90:93]
	v_mfma_f32_16x16x32_bf16 v[82:85], v[166:169], v[222:225], v[82:85]
	v_mfma_f32_16x16x32_bf16 v[74:77], v[190:193], v[222:225], v[74:77]
	v_mfma_f32_16x16x32_bf16 v[70:73], v[166:169], v[230:233], v[70:73]
	v_mfma_f32_16x16x32_bf16 v[66:69], v[190:193], v[230:233], v[66:69]
	s_barrier
	s_add_i32 s20, s8, 0x18000
	s_add_u32 s80, s76, 0x80
	s_addc_u32 s81, s77, 0
	s_mov_b32 m0, s20
	s_nop 0
	s_setprio 2
	global_load_lds_dwordx4 v148, s[80:81]
	s_add_i32 m0, s20, 0x2000
	s_add_u32 s20, s76, 0x40080
	s_addc_u32 s21, s77, 0
	s_add_i32 s12, s8, 0x1c000
	global_load_lds_dwordx4 v152, s[80:81]
	s_mov_b32 m0, s12
	s_nop 0
	global_load_lds_dwordx4 v148, s[20:21]
	s_add_i32 m0, s12, 0x2000
	s_nop 0
	global_load_lds_dwordx4 v152, s[20:21]
	s_mov_b32 m0, s31
	s_nop 0
	global_load_lds_dwordx4 v146, s[100:101]
	s_mov_b32 m0, s34
	s_nop 0
	global_load_lds_dwordx4 v150, s[100:101]
	s_setprio 0
	ds_read_b128 v[194:197], v160 offset:49152
	ds_read_b128 v[198:201], v160 offset:50176
	ds_read_b128 v[202:205], v160 offset:51200
	ds_read_b128 v[206:209], v160 offset:52224
	ds_read_b128 v[218:221], v160 offset:53248
	ds_read_b128 v[222:225], v160 offset:54272
	ds_read_b128 v[226:229], v160 offset:55296
	ds_read_b128 v[230:233], v160 offset:56320
	s_waitcnt vmcnt(8)
	s_waitcnt lgkmcnt(0)
	s_barrier
	s_waitcnt lgkmcnt(0)
	v_mfma_f32_16x16x32_bf16 v[62:65], v[130:133], v[194:197], v[62:65]
	v_mfma_f32_16x16x32_bf16 v[58:61], v[138:141], v[194:197], v[58:61]
	v_mfma_f32_16x16x32_bf16 v[54:57], v[130:133], v[202:205], v[54:57]
	v_mfma_f32_16x16x32_bf16 v[46:49], v[138:141], v[202:205], v[46:49]
	v_mfma_f32_16x16x32_bf16 v[38:41], v[130:133], v[218:221], v[38:41]
	v_mfma_f32_16x16x32_bf16 v[30:33], v[138:141], v[218:221], v[30:33]
	v_mfma_f32_16x16x32_bf16 v[22:25], v[130:133], v[226:229], v[22:25]
	v_mfma_f32_16x16x32_bf16 v[14:17], v[138:141], v[226:229], v[14:17]
	v_mfma_f32_16x16x32_bf16 v[62:65], v[134:137], v[198:201], v[62:65]
	v_mfma_f32_16x16x32_bf16 v[58:61], v[142:145], v[198:201], v[58:61]
	v_mfma_f32_16x16x32_bf16 v[54:57], v[134:137], v[206:209], v[54:57]
	v_mfma_f32_16x16x32_bf16 v[46:49], v[142:145], v[206:209], v[46:49]
	v_mfma_f32_16x16x32_bf16 v[38:41], v[134:137], v[222:225], v[38:41]
	v_mfma_f32_16x16x32_bf16 v[30:33], v[142:145], v[222:225], v[30:33]
	v_mfma_f32_16x16x32_bf16 v[22:25], v[134:137], v[230:233], v[22:25]
	v_mfma_f32_16x16x32_bf16 v[14:17], v[142:145], v[230:233], v[14:17]
	v_mfma_f32_16x16x32_bf16 v[50:53], v[162:165], v[194:197], v[50:53]
	v_mfma_f32_16x16x32_bf16 v[42:45], v[170:173], v[194:197], v[42:45]
	v_mfma_f32_16x16x32_bf16 v[34:37], v[162:165], v[202:205], v[34:37]
	v_mfma_f32_16x16x32_bf16 v[26:29], v[170:173], v[202:205], v[26:29]
	v_mfma_f32_16x16x32_bf16 v[18:21], v[162:165], v[218:221], v[18:21]
	v_mfma_f32_16x16x32_bf16 v[10:13], v[170:173], v[218:221], v[10:13]
	v_mfma_f32_16x16x32_bf16 v[6:9], v[162:165], v[226:229], v[6:9]
	v_mfma_f32_16x16x32_bf16 v[2:5], v[170:173], v[226:229], v[2:5]
	v_mfma_f32_16x16x32_bf16 v[50:53], v[166:169], v[198:201], v[50:53]
	v_mfma_f32_16x16x32_bf16 v[42:45], v[190:193], v[198:201], v[42:45]
	v_mfma_f32_16x16x32_bf16 v[34:37], v[166:169], v[206:209], v[34:37]
	v_mfma_f32_16x16x32_bf16 v[26:29], v[190:193], v[206:209], v[26:29]
	v_mfma_f32_16x16x32_bf16 v[18:21], v[166:169], v[222:225], v[18:21]
	v_mfma_f32_16x16x32_bf16 v[10:13], v[190:193], v[222:225], v[10:13]
	v_mfma_f32_16x16x32_bf16 v[6:9], v[166:169], v[230:233], v[6:9]
	v_mfma_f32_16x16x32_bf16 v[2:5], v[190:193], v[230:233], v[2:5]
	s_barrier
	s_add_i32 s78, s78, 2
	s_add_u32 s18, s18, 0x100
	s_addc_u32 s19, s19, 0
	s_add_u32 s69, s69, 0x100
	s_addc_u32 s71, s71, 0
	s_cmp_gt_u32 s78, 13
	s_cbranch_scc0 .LBB0_378
	s_and_b64 vcc, exec, s[36:37]
	s_cbranch_vccz .LBB0_381
	s_barrier

; #define PG8_STAGE(bufoff, gbase, voff) do { _Pragma("unroll") for (int _i = 0; _i < 2; ++_i) \
;         __builtin_amdgcn_global_load_lds((const unsigned*)((const char*)(gbase) + (voff)[_i]), (LAS unsigned*)(lds + (bufoff) + ldsw + _i * 8192), 16, 0, 0); } while (0)
; #define PG8_LDA(dst, b, h) do { _Pragma("unroll") for (int m = 0; m < 4; ++m) _Pragma("unroll") for (int k = 0; k < 2; ++k) dst[m][k] = *(const LAS bf16x8*)(lds + PG8_SA(b, h) + aoff + m * 2048 + k * 1024); } while (0)
; #define PG8_LDB(dst, b, h) do { _Pragma("unroll") for (int n = 0; n < 2; ++n) _Pragma("unroll") for (int k = 0; k < 2; ++k) dst[n][k] = *(const LAS bf16x8*)(lds + PG8_SB(b, h) + boff + n * 2048 + k * 1024); } while (0)
; #define PG8_MMA(ai, bj, At, Bt) do { __builtin_amdgcn_s_setprio(1); _Pragma("unroll") for (int m = 0; m < 4; ++m) _Pragma("unroll") for (int n = 0; n < 2; ++n) _Pragma("unroll") for (int k = 0; k < 2; ++k) \
;         acc[ai][bj][m][n] = __builtin_amdgcn_mfma_f32_16x16x32_bf16(Bt[n][k], At[m][k], acc[ai][bj][m][n], 0, 0, 0); __builtin_amdgcn_s_setprio(0); } while (0)
; #define PG8_WAIT_V(n) asm volatile("s_waitcnt vmcnt(" #n ")" ::: "memory")
; #define PG8_WAIT_L(n) asm volatile("s_waitcnt lgkmcnt(" #n ")" ::: "memory")
; #define PG8_BAR __builtin_amdgcn_s_barrier()
; #define PG8_SCHED __builtin_amdgcn_sched_barrier(0)
; template <class Epi, class Sched>
; __device__ __forceinline__ void gemm_phase(LAS unsigned char* lds, const Gemm g, const Sched& S, const Epi& E) {
;     ...
;         for (int t = 0; t < nt; t += 2) {
;             const bool last = (t == nt - 2);
;             const char* a1 = cA + (size_t)(t + 1) * kstep;
;             const char* a2 = last ? nA : cA + (size_t)(t + 2) * kstep; const char* b2 = last ? nB : cB + (size_t)(t + 2) * kstep;
;             const char* a3 = a2 + kstep; const char* b3 = b2 + kstep;
;             PG8_LDB(B0, 0, 0); PG8_LDB(B1, 0, 1); PG8_SCHED; PG8_LDA(At, 0, 0); PG8_STAGE(PG8_SA(1, 1), a1 + hstepA, voffA);
;             PG8_WAIT_V(8); PG8_WAIT_L(0); PG8_BAR; PG8_MMA(0, 0, At, B0); PG8_MMA(0, 1, At, B1); PG8_BAR; PG8_SCHED;
;             PG8_LDA(At, 0, 1); PG8_STAGE(PG8_SB(0, 0), b2, voffB); PG8_STAGE(PG8_SB(0, 1), b2 + hstepB, voffB); PG8_STAGE(PG8_SA(0, 0), a2, voffA);
;             PG8_WAIT_V(8); PG8_WAIT_L(0); PG8_BAR; PG8_MMA(1, 0, At, B0); PG8_MMA(1, 1, At, B1); PG8_BAR; PG8_SCHED;
.LBB0_598:
	s_add_i32 vcc_lo, s20, 2
	s_add_u32 s90, s18, 0x80
	s_addc_u32 s21, s19, 0
	s_add_i32 s92, 0, 0x10000
	s_cmp_eq_u32 s43, s20
	s_cselect_b32 s21, s37, s21
	s_cselect_b32 s20, s36, s90
	s_cselect_b32 s91, s71, s87
	s_cselect_b32 s90, s70, s86
	s_add_i32 s93, 0, 0x14000
	s_add_i32 m0, s35, 0xc000
	s_nop 0
	s_setprio 2
	global_load_lds_dwordx4 v138, s[18:19]
	s_add_i32 m0, s35, 0xe000
	s_nop 0
	global_load_lds_dwordx4 v140, s[18:19]
	s_setprio 0
	ds_read_b128 v[142:145], v255
	ds_read_b128 v[150:153], v255 offset:1024
	ds_read_b128 v[154:157], v255 offset:2048
	ds_read_b128 v[158:161], v255 offset:3072
	ds_read_b128 v[162:165], v255 offset:16384
	ds_read_b128 v[166:169], v255 offset:17408
	ds_read_b128 v[170:173], v255 offset:18432
	ds_read_b128 v[190:193], v255 offset:19456
	ds_read_b128 v[194:197], v148
	ds_read_b128 v[198:201], v148 offset:1024
	ds_read_b128 v[202:205], v148 offset:2048
	ds_read_b128 v[206:209], v148 offset:3072
	ds_read_b128 v[218:221], v148 offset:4096
	ds_read_b128 v[222:225], v148 offset:5120
	ds_read_b128 v[226:229], v148 offset:6144
	ds_read_b128 v[230:233], v148 offset:7168
	s_waitcnt vmcnt(8)
	s_waitcnt lgkmcnt(0)
	s_barrier
	s_waitcnt lgkmcnt(0)
	v_mfma_f32_16x16x32_bf16 v[114:117], v[142:145], v[194:197], v[114:117]
	v_mfma_f32_16x16x32_bf16 v[118:121], v[154:157], v[194:197], v[118:121]
	v_mfma_f32_16x16x32_bf16 v[94:97], v[142:145], v[202:205], v[94:97]
	v_mfma_f32_16x16x32_bf16 v[98:101], v[154:157], v[202:205], v[98:101]
	v_mfma_f32_16x16x32_bf16 v[62:65], v[142:145], v[218:221], v[62:65]
	v_mfma_f32_16x16x32_bf16 v[66:69], v[154:157], v[218:221], v[66:69]
	v_mfma_f32_16x16x32_bf16 v[22:25], v[142:145], v[226:229], v[22:25]
	v_mfma_f32_16x16x32_bf16 v[34:37], v[154:157], v[226:229], v[34:37]
	v_mfma_f32_16x16x32_bf16 v[114:117], v[150:153], v[198:201], v[114:117]
	v_mfma_f32_16x16x32_bf16 v[118:121], v[158:161], v[198:201], v[118:121]
	v_mfma_f32_16x16x32_bf16 v[94:97], v[150:153], v[206:209], v[94:97]
	v_mfma_f32_16x16x32_bf16 v[98:101], v[158:161], v[206:209], v[98:101]
	v_mfma_f32_16x16x32_bf16 v[62:65], v[150:153], v[222:225], v[62:65]
	v_mfma_f32_16x16x32_bf16 v[66:69], v[158:161], v[222:225], v[66:69]
	v_mfma_f32_16x16x32_bf16 v[22:25], v[150:153], v[230:233], v[22:25]
	v_mfma_f32_16x16x32_bf16 v[34:37], v[158:161], v[230:233], v[34:37]
	v_mfma_f32_16x16x32_bf16 v[122:125], v[162:165], v[194:197], v[122:125]
	v_mfma_f32_16x16x32_bf16 v[126:129], v[170:173], v[194:197], v[126:129]
	v_mfma_f32_16x16x32_bf16 v[102:105], v[162:165], v[202:205], v[102:105]
	v_mfma_f32_16x16x32_bf16 v[106:109], v[170:173], v[202:205], v[106:109]
	v_mfma_f32_16x16x32_bf16 v[70:73], v[162:165], v[218:221], v[70:73]
	v_mfma_f32_16x16x32_bf16 v[78:81], v[170:173], v[218:221], v[78:81]
	v_mfma_f32_16x16x32_bf16 v[38:41], v[162:165], v[226:229], v[38:41]
	v_mfma_f32_16x16x32_bf16 v[46:49], v[170:173], v[226:229], v[46:49]
	v_mfma_f32_16x16x32_bf16 v[122:125], v[166:169], v[198:201], v[122:125]
	v_mfma_f32_16x16x32_bf16 v[126:129], v[190:193], v[198:201], v[126:129]
	v_mfma_f32_16x16x32_bf16 v[102:105], v[166:169], v[206:209], v[102:105]
	v_mfma_f32_16x16x32_bf16 v[106:109], v[190:193], v[206:209], v[106:109]
	v_mfma_f32_16x16x32_bf16 v[70:73], v[166:169], v[222:225], v[70:73]
	v_mfma_f32_16x16x32_bf16 v[78:81], v[190:193], v[222:225], v[78:81]
	v_mfma_f32_16x16x32_bf16 v[38:41], v[166:169], v[230:233], v[38:41]
	v_mfma_f32_16x16x32_bf16 v[46:49], v[190:193], v[230:233], v[46:49]
	s_barrier
	s_add_i32 s92, s92, s34
	s_add_u32 s98, s90, 0x80
	s_addc_u32 s99, s91, 0
	s_add_u32 s100, s20, 0x80
	s_addc_u32 s101, s21, 0
	s_mov_b32 m0, s92
	s_nop 0
	s_setprio 2
	global_load_lds_dwordx4 v132, s[90:91]
	s_add_i32 m0, s92, 0x2000
	s_add_i32 s92, s93, s34
	global_load_lds_dwordx4 v136, s[90:91]
	s_add_u32 s90, s90, s29
	s_addc_u32 s91, s91, 0
	s_mov_b32 m0, s92
	s_nop 0
	global_load_lds_dwordx4 v132, s[90:91]
	s_add_i32 m0, s92, 0x2000
	s_nop 0
	global_load_lds_dwordx4 v136, s[90:91]
	s_mov_b32 m0, s35
	s_nop 0
	global_load_lds_dwordx4 v130, s[20:21]
	s_mov_b32 m0, s8
	s_nop 0
	global_load_lds_dwordx4 v134, s[20:21]
	s_setprio 0
	ds_read_b128 v[194:197], v148 offset:16384
	ds_read_b128 v[198:201], v148 offset:17408
	ds_read_b128 v[202:205], v148 offset:18432
	ds_read_b128 v[206:209], v148 offset:19456
	ds_read_b128 v[218:221], v148 offset:20480
	ds_read_b128 v[222:225], v148 offset:21504
	ds_read_b128 v[226:229], v148 offset:22528
	ds_read_b128 v[230:233], v148 offset:23552
	s_waitcnt vmcnt(8)
	s_waitcnt lgkmcnt(0)
	s_barrier
	s_waitcnt lgkmcnt(0)
	v_mfma_f32_16x16x32_bf16 v[14:17], v[142:145], v[194:197], v[14:17]
	v_mfma_f32_16x16x32_bf16 v[26:29], v[154:157], v[194:197], v[26:29]
	v_mfma_f32_16x16x32_bf16 v[74:77], v[142:145], v[202:205], v[74:77]
	v_mfma_f32_16x16x32_bf16 v[82:85], v[154:157], v[202:205], v[82:85]
	v_mfma_f32_16x16x32_bf16 v[42:45], v[142:145], v[218:221], v[42:45]
	v_mfma_f32_16x16x32_bf16 v[50:53], v[154:157], v[218:221], v[50:53]
	v_mfma_f32_16x16x32_bf16 v[2:5], v[142:145], v[226:229], v[2:5]
	v_mfma_f32_16x16x32_bf16 v[6:9], v[154:157], v[226:229], v[6:9]
	v_mfma_f32_16x16x32_bf16 v[14:17], v[150:153], v[198:201], v[14:17]
	v_mfma_f32_16x16x32_bf16 v[26:29], v[158:161], v[198:201], v[26:29]
	v_mfma_f32_16x16x32_bf16 v[74:77], v[150:153], v[206:209], v[74:77]
	v_mfma_f32_16x16x32_bf16 v[82:85], v[158:161], v[206:209], v[82:85]
	v_mfma_f32_16x16x32_bf16 v[42:45], v[150:153], v[222:225], v[42:45]
	v_mfma_f32_16x16x32_bf16 v[50:53], v[158:161], v[222:225], v[50:53]
	v_mfma_f32_16x16x32_bf16 v[2:5], v[150:153], v[230:233], v[2:5]
	v_mfma_f32_16x16x32_bf16 v[6:9], v[158:161], v[230:233], v[6:9]
	v_mfma_f32_16x16x32_bf16 v[30:33], v[162:165], v[194:197], v[30:33]
	v_mfma_f32_16x16x32_bf16 v[110:113], v[170:173], v[194:197], v[110:113]
	v_mfma_f32_16x16x32_bf16 v[86:89], v[162:165], v[202:205], v[86:89]
	v_mfma_f32_16x16x32_bf16 v[90:93], v[170:173], v[202:205], v[90:93]
	v_mfma_f32_16x16x32_bf16 v[54:57], v[162:165], v[218:221], v[54:57]
	v_mfma_f32_16x16x32_bf16 v[58:61], v[170:173], v[218:221], v[58:61]
	v_mfma_f32_16x16x32_bf16 v[10:13], v[162:165], v[226:229], v[10:13]
	v_mfma_f32_16x16x32_bf16 v[18:21], v[170:173], v[226:229], v[18:21]
	v_mfma_f32_16x16x32_bf16 v[30:33], v[166:169], v[198:201], v[30:33]
	v_mfma_f32_16x16x32_bf16 v[110:113], v[190:193], v[198:201], v[110:113]
	v_mfma_f32_16x16x32_bf16 v[86:89], v[166:169], v[206:209], v[86:89]
	v_mfma_f32_16x16x32_bf16 v[90:93], v[190:193], v[206:209], v[90:93]
	v_mfma_f32_16x16x32_bf16 v[54:57], v[166:169], v[222:225], v[54:57]
	v_mfma_f32_16x16x32_bf16 v[58:61], v[190:193], v[222:225], v[58:61]
	v_mfma_f32_16x16x32_bf16 v[10:13], v[166:169], v[230:233], v[10:13]
	v_mfma_f32_16x16x32_bf16 v[18:21], v[190:193], v[230:233], v[18:21]
	s_barrier
; #define PG8_STAGE(bufoff, gbase, voff) do { _Pragma("unroll") for (int _i = 0; _i < 2; ++_i) \
;         __builtin_amdgcn_global_load_lds((const unsigned*)((const char*)(gbase) + (voff)[_i]), (LAS unsigned*)(lds + (bufoff) + ldsw + _i * 8192), 16, 0, 0); } while (0)
; #define PG8_LDA(dst, b, h) do { _Pragma("unroll") for (int m = 0; m < 4; ++m) _Pragma("unroll") for (int k = 0; k < 2; ++k) dst[m][k] = *(const LAS bf16x8*)(lds + PG8_SA(b, h) + aoff + m * 2048 + k * 1024); } while (0)
; #define PG8_LDB(dst, b, h) do { _Pragma("unroll") for (int n = 0; n < 2; ++n) _Pragma("unroll") for (int k = 0; k < 2; ++k) dst[n][k] = *(const LAS bf16x8*)(lds + PG8_SB(b, h) + boff + n * 2048 + k * 1024); } while (0)
; #define PG8_MMA(ai, bj, At, Bt) do { __builtin_amdgcn_s_setprio(1); _Pragma("unroll") for (int m = 0; m < 4; ++m) _Pragma("unroll") for (int n = 0; n < 2; ++n) _Pragma("unroll") for (int k = 0; k < 2; ++k) \
;         acc[ai][bj][m][n] = __builtin_amdgcn_mfma_f32_16x16x32_bf16(Bt[n][k], At[m][k], acc[ai][bj][m][n], 0, 0, 0); __builtin_amdgcn_s_setprio(0); } while (0)
; #define PG8_WAIT_V(n) asm volatile("s_waitcnt vmcnt(" #n ")" ::: "memory")
; #define PG8_WAIT_L(n) asm volatile("s_waitcnt lgkmcnt(" #n ")" ::: "memory")
; #define PG8_BAR __builtin_amdgcn_s_barrier()
; #define PG8_SCHED __builtin_amdgcn_sched_barrier(0)
; template <class Epi, class Sched>
; __device__ __forceinline__ void gemm_phase(LAS unsigned char* lds, const Gemm g, const Sched& S, const Epi& E) {
;     ...
;             PG8_LDB(B0, 1, 0); PG8_LDB(B1, 1, 1); PG8_SCHED; PG8_LDA(At, 1, 0); PG8_STAGE(PG8_SA(0, 1), a2 + hstepA, voffA);
;             PG8_WAIT_V(8); PG8_WAIT_L(0); PG8_BAR; PG8_MMA(0, 0, At, B0); PG8_MMA(0, 1, At, B1); PG8_BAR; PG8_SCHED;
;             PG8_LDA(At, 1, 1); PG8_STAGE(PG8_SB(1, 0), b3, voffB); PG8_STAGE(PG8_SB(1, 1), b3 + hstepB, voffB); PG8_STAGE(PG8_SA(1, 0), a3, voffA);
;             PG8_WAIT_V(8); PG8_WAIT_L(0); PG8_BAR; PG8_MMA(1, 0, At, B0); PG8_MMA(1, 1, At, B1); PG8_BAR; PG8_SCHED;
;         }
;         if (wr == 0) PG8_BAR;
	s_add_u32 s20, s20, s80
	s_addc_u32 s21, s21, 0
	s_mov_b32 m0, s9
	s_nop 0
	s_setprio 2
	global_load_lds_dwordx4 v130, s[20:21]
	s_mov_b32 m0, s40
	s_nop 0
	global_load_lds_dwordx4 v134, s[20:21]
	s_setprio 0
	ds_read_b128 v[142:145], v255 offset:32768
	ds_read_b128 v[150:153], v255 offset:33792
	ds_read_b128 v[154:157], v255 offset:34816
	ds_read_b128 v[158:161], v255 offset:35840
	ds_read_b128 v[162:165], v255 offset:49152
	ds_read_b128 v[166:169], v255 offset:50176
	ds_read_b128 v[170:173], v255 offset:51200
	ds_read_b128 v[190:193], v255 offset:52224
	ds_read_b128 v[194:197], v148 offset:32768
	ds_read_b128 v[198:201], v148 offset:33792
	ds_read_b128 v[202:205], v148 offset:34816
	ds_read_b128 v[206:209], v148 offset:35840
	ds_read_b128 v[218:221], v148 offset:36864
	ds_read_b128 v[222:225], v148 offset:37888
	ds_read_b128 v[226:229], v148 offset:38912
	ds_read_b128 v[230:233], v148 offset:39936
	s_waitcnt vmcnt(8)
	s_waitcnt lgkmcnt(0)
	s_barrier
	s_waitcnt lgkmcnt(0)
	v_mfma_f32_16x16x32_bf16 v[114:117], v[142:145], v[194:197], v[114:117]
	v_mfma_f32_16x16x32_bf16 v[118:121], v[154:157], v[194:197], v[118:121]
	v_mfma_f32_16x16x32_bf16 v[94:97], v[142:145], v[202:205], v[94:97]
	v_mfma_f32_16x16x32_bf16 v[98:101], v[154:157], v[202:205], v[98:101]
	v_mfma_f32_16x16x32_bf16 v[62:65], v[142:145], v[218:221], v[62:65]
	v_mfma_f32_16x16x32_bf16 v[66:69], v[154:157], v[218:221], v[66:69]
	v_mfma_f32_16x16x32_bf16 v[22:25], v[142:145], v[226:229], v[22:25]
	v_mfma_f32_16x16x32_bf16 v[34:37], v[154:157], v[226:229], v[34:37]
	v_mfma_f32_16x16x32_bf16 v[114:117], v[150:153], v[198:201], v[114:117]
	v_mfma_f32_16x16x32_bf16 v[118:121], v[158:161], v[198:201], v[118:121]
	v_mfma_f32_16x16x32_bf16 v[94:97], v[150:153], v[206:209], v[94:97]
	v_mfma_f32_16x16x32_bf16 v[98:101], v[158:161], v[206:209], v[98:101]
	v_mfma_f32_16x16x32_bf16 v[62:65], v[150:153], v[222:225], v[62:65]
	v_mfma_f32_16x16x32_bf16 v[66:69], v[158:161], v[222:225], v[66:69]
	v_mfma_f32_16x16x32_bf16 v[22:25], v[150:153], v[230:233], v[22:25]
	v_mfma_f32_16x16x32_bf16 v[34:37], v[158:161], v[230:233], v[34:37]
	v_mfma_f32_16x16x32_bf16 v[122:125], v[162:165], v[194:197], v[122:125]
	v_mfma_f32_16x16x32_bf16 v[126:129], v[170:173], v[194:197], v[126:129]
	v_mfma_f32_16x16x32_bf16 v[102:105], v[162:165], v[202:205], v[102:105]
	v_mfma_f32_16x16x32_bf16 v[106:109], v[170:173], v[202:205], v[106:109]
	v_mfma_f32_16x16x32_bf16 v[70:73], v[162:165], v[218:221], v[70:73]
	v_mfma_f32_16x16x32_bf16 v[78:81], v[170:173], v[218:221], v[78:81]
	v_mfma_f32_16x16x32_bf16 v[38:41], v[162:165], v[226:229], v[38:41]
	v_mfma_f32_16x16x32_bf16 v[46:49], v[170:173], v[226:229], v[46:49]
	v_mfma_f32_16x16x32_bf16 v[122:125], v[166:169], v[198:201], v[122:125]
	v_mfma_f32_16x16x32_bf16 v[126:129], v[190:193], v[198:201], v[126:129]
	v_mfma_f32_16x16x32_bf16 v[102:105], v[166:169], v[206:209], v[102:105]
	v_mfma_f32_16x16x32_bf16 v[106:109], v[190:193], v[206:209], v[106:109]
	v_mfma_f32_16x16x32_bf16 v[70:73], v[166:169], v[222:225], v[70:73]
	v_mfma_f32_16x16x32_bf16 v[78:81], v[190:193], v[222:225], v[78:81]
	v_mfma_f32_16x16x32_bf16 v[38:41], v[166:169], v[230:233], v[38:41]
	v_mfma_f32_16x16x32_bf16 v[46:49], v[190:193], v[230:233], v[46:49]
	s_barrier
	s_add_i32 s20, s34, 0x18000
	s_mov_b32 m0, s20
	s_nop 0
	s_setprio 2
	global_load_lds_dwordx4 v132, s[98:99]
	s_add_i32 m0, s20, 0x2000
	s_add_i32 s20, s34, 0x1c000
	global_load_lds_dwordx4 v136, s[98:99]
	s_add_u32 s98, s98, s29
	s_addc_u32 s99, s99, 0
	s_mov_b32 m0, s20
	s_nop 0
	global_load_lds_dwordx4 v132, s[98:99]
	s_add_i32 m0, s20, 0x2000
	s_nop 0
	global_load_lds_dwordx4 v136, s[98:99]
	s_mov_b32 m0, s41
	s_nop 0
	global_load_lds_dwordx4 v130, s[100:101]
	s_mov_b32 m0, s42
	s_nop 0
	global_load_lds_dwordx4 v134, s[100:101]
	s_setprio 0
	ds_read_b128 v[194:197], v148 offset:49152
	ds_read_b128 v[198:201], v148 offset:50176
	ds_read_b128 v[202:205], v148 offset:51200
	ds_read_b128 v[206:209], v148 offset:52224
	ds_read_b128 v[218:221], v148 offset:53248
	ds_read_b128 v[222:225], v148 offset:54272
	ds_read_b128 v[226:229], v148 offset:55296
	ds_read_b128 v[230:233], v148 offset:56320
	s_waitcnt vmcnt(8)
	s_waitcnt lgkmcnt(0)
	s_barrier
	s_waitcnt lgkmcnt(0)
	v_mfma_f32_16x16x32_bf16 v[14:17], v[142:145], v[194:197], v[14:17]
	v_mfma_f32_16x16x32_bf16 v[26:29], v[154:157], v[194:197], v[26:29]
	v_mfma_f32_16x16x32_bf16 v[74:77], v[142:145], v[202:205], v[74:77]
	v_mfma_f32_16x16x32_bf16 v[82:85], v[154:157], v[202:205], v[82:85]
	v_mfma_f32_16x16x32_bf16 v[42:45], v[142:145], v[218:221], v[42:45]
	v_mfma_f32_16x16x32_bf16 v[50:53], v[154:157], v[218:221], v[50:53]
	v_mfma_f32_16x16x32_bf16 v[2:5], v[142:145], v[226:229], v[2:5]
	v_mfma_f32_16x16x32_bf16 v[6:9], v[154:157], v[226:229], v[6:9]
	v_mfma_f32_16x16x32_bf16 v[14:17], v[150:153], v[198:201], v[14:17]
	v_mfma_f32_16x16x32_bf16 v[26:29], v[158:161], v[198:201], v[26:29]
	v_mfma_f32_16x16x32_bf16 v[74:77], v[150:153], v[206:209], v[74:77]
	v_mfma_f32_16x16x32_bf16 v[82:85], v[158:161], v[206:209], v[82:85]
	v_mfma_f32_16x16x32_bf16 v[42:45], v[150:153], v[222:225], v[42:45]
	v_mfma_f32_16x16x32_bf16 v[50:53], v[158:161], v[222:225], v[50:53]
	v_mfma_f32_16x16x32_bf16 v[2:5], v[150:153], v[230:233], v[2:5]
	v_mfma_f32_16x16x32_bf16 v[6:9], v[158:161], v[230:233], v[6:9]
	v_mfma_f32_16x16x32_bf16 v[30:33], v[162:165], v[194:197], v[30:33]
	v_mfma_f32_16x16x32_bf16 v[110:113], v[170:173], v[194:197], v[110:113]
	v_mfma_f32_16x16x32_bf16 v[86:89], v[162:165], v[202:205], v[86:89]
	v_mfma_f32_16x16x32_bf16 v[90:93], v[170:173], v[202:205], v[90:93]
	v_mfma_f32_16x16x32_bf16 v[54:57], v[162:165], v[218:221], v[54:57]
	v_mfma_f32_16x16x32_bf16 v[58:61], v[170:173], v[218:221], v[58:61]
	v_mfma_f32_16x16x32_bf16 v[10:13], v[162:165], v[226:229], v[10:13]
	v_mfma_f32_16x16x32_bf16 v[18:21], v[170:173], v[226:229], v[18:21]
	v_mfma_f32_16x16x32_bf16 v[30:33], v[166:169], v[198:201], v[30:33]
	v_mfma_f32_16x16x32_bf16 v[110:113], v[190:193], v[198:201], v[110:113]
	v_mfma_f32_16x16x32_bf16 v[86:89], v[166:169], v[206:209], v[86:89]
	v_mfma_f32_16x16x32_bf16 v[90:93], v[190:193], v[206:209], v[90:93]
	v_mfma_f32_16x16x32_bf16 v[54:57], v[166:169], v[222:225], v[54:57]
	v_mfma_f32_16x16x32_bf16 v[58:61], v[190:193], v[222:225], v[58:61]
	v_mfma_f32_16x16x32_bf16 v[10:13], v[166:169], v[230:233], v[10:13]
	v_mfma_f32_16x16x32_bf16 v[18:21], v[190:193], v[230:233], v[18:21]
	s_barrier
	s_add_u32 s18, s18, 0x100
	s_addc_u32 s19, s19, 0
	s_add_u32 s86, s86, 0x100
	s_addc_u32 s87, s87, 0
	s_cmp_ge_u32 vcc_lo, s48
	s_mov_b32 s20, vcc_lo
	s_cbranch_scc0 .LBB0_598
	s_and_b64 vcc, exec, s[84:85]
	s_cbranch_vccz .LBB0_601
	s_barrier

; #define PG8_STAGE(bufoff, gbase, voff) do { _Pragma("unroll") for (int _i = 0; _i < 2; ++_i) \
;         __builtin_amdgcn_global_load_lds((const unsigned*)((const char*)(gbase) + (voff)[_i]), (LAS unsigned*)(lds + (bufoff) + ldsw + _i * 8192), 16, 0, 0); } while (0)
; #define PG8_LDA(dst, b, h) do { _Pragma("unroll") for (int m = 0; m < 4; ++m) _Pragma("unroll") for (int k = 0; k < 2; ++k) dst[m][k] = *(const LAS bf16x8*)(lds + PG8_SA(b, h) + aoff + m * 2048 + k * 1024); } while (0)
; #define PG8_LDB(dst, b, h) do { _Pragma("unroll") for (int n = 0; n < 2; ++n) _Pragma("unroll") for (int k = 0; k < 2; ++k) dst[n][k] = *(const LAS bf16x8*)(lds + PG8_SB(b, h) + boff + n * 2048 + k * 1024); } while (0)
; #define PG8_MMA(ai, bj, At, Bt) do { __builtin_amdgcn_s_setprio(1); _Pragma("unroll") for (int m = 0; m < 4; ++m) _Pragma("unroll") for (int n = 0; n < 2; ++n) _Pragma("unroll") for (int k = 0; k < 2; ++k) \
;         acc[ai][bj][m][n] = __builtin_amdgcn_mfma_f32_16x16x32_bf16(Bt[n][k], At[m][k], acc[ai][bj][m][n], 0, 0, 0); __builtin_amdgcn_s_setprio(0); } while (0)
; #define PG8_WAIT_V(n) asm volatile("s_waitcnt vmcnt(" #n ")" ::: "memory")
; #define PG8_WAIT_L(n) asm volatile("s_waitcnt lgkmcnt(" #n ")" ::: "memory")
; #define PG8_BAR __builtin_amdgcn_s_barrier()
; #define PG8_SCHED __builtin_amdgcn_sched_barrier(0)
; template <class Epi, class Sched>
; __device__ __forceinline__ void gemm_phase(LAS unsigned char* lds, const Gemm g, const Sched& S, const Epi& E) {
;     ...
;         for (int t = 0; t < nt; t += 2) {
;             const bool last = (t == nt - 2);
;             const char* a1 = cA + (size_t)(t + 1) * kstep;
;             const char* a2 = last ? nA : cA + (size_t)(t + 2) * kstep; const char* b2 = last ? nB : cB + (size_t)(t + 2) * kstep;
;             const char* a3 = a2 + kstep; const char* b3 = b2 + kstep;
;             PG8_LDB(B0, 0, 0); PG8_LDB(B1, 0, 1); PG8_SCHED; PG8_LDA(At, 0, 0); PG8_STAGE(PG8_SA(1, 1), a1 + hstepA, voffA);
;             PG8_WAIT_V(8); PG8_WAIT_L(0); PG8_BAR; PG8_MMA(0, 0, At, B0); PG8_MMA(0, 1, At, B1); PG8_BAR; PG8_SCHED;
;             PG8_LDA(At, 0, 1); PG8_STAGE(PG8_SB(0, 0), b2, voffB); PG8_STAGE(PG8_SB(0, 1), b2 + hstepB, voffB); PG8_STAGE(PG8_SA(0, 0), a2, voffA);
;             PG8_WAIT_V(8); PG8_WAIT_L(0); PG8_BAR; PG8_MMA(1, 0, At, B0); PG8_MMA(1, 1, At, B1); PG8_BAR; PG8_SCHED;
.LBB0_640:
	s_add_i32 s87, s20, 2
	s_add_u32 s88, s18, 0x80
	s_addc_u32 s21, s19, 0
	s_add_i32 s90, 0, 0x10000
	s_cmp_eq_u32 s43, s20
	s_cselect_b32 s21, s69, s21
	s_cselect_b32 s20, s68, s88
	s_cselect_b32 s89, s81, s83
	s_cselect_b32 s88, s80, s82
	s_add_i32 s91, 0, 0x14000
	s_add_i32 m0, s30, 0xc000
	s_nop 0
	s_setprio 2
	global_load_lds_dwordx4 v138, s[18:19]
	s_add_i32 m0, s30, 0xe000
	s_nop 0
	global_load_lds_dwordx4 v140, s[18:19]
	s_setprio 0
	ds_read_b128 v[146:149], v255
	ds_read_b128 v[150:153], v255 offset:1024
	ds_read_b128 v[154:157], v255 offset:2048
	ds_read_b128 v[158:161], v255 offset:3072
	ds_read_b128 v[162:165], v255 offset:16384
	ds_read_b128 v[166:169], v255 offset:17408
	ds_read_b128 v[170:173], v255 offset:18432
	ds_read_b128 v[190:193], v255 offset:19456
	ds_read_b128 v[194:197], v144
	ds_read_b128 v[198:201], v144 offset:1024
	ds_read_b128 v[202:205], v144 offset:2048
	ds_read_b128 v[206:209], v144 offset:3072
	ds_read_b128 v[218:221], v144 offset:4096
	ds_read_b128 v[222:225], v144 offset:5120
	ds_read_b128 v[226:229], v144 offset:6144
	ds_read_b128 v[230:233], v144 offset:7168
	s_waitcnt vmcnt(8)
	s_waitcnt lgkmcnt(0)
	s_barrier
	s_waitcnt lgkmcnt(0)
	v_mfma_f32_16x16x32_bf16 v[2:5], v[146:149], v[194:197], v[2:5]
	v_mfma_f32_16x16x32_bf16 v[6:9], v[154:157], v[194:197], v[6:9]
	v_mfma_f32_16x16x32_bf16 v[10:13], v[146:149], v[202:205], v[10:13]
	v_mfma_f32_16x16x32_bf16 v[14:17], v[154:157], v[202:205], v[14:17]
	v_mfma_f32_16x16x32_bf16 v[26:29], v[146:149], v[218:221], v[26:29]
	v_mfma_f32_16x16x32_bf16 v[30:33], v[154:157], v[218:221], v[30:33]
	v_mfma_f32_16x16x32_bf16 v[42:45], v[146:149], v[226:229], v[42:45]
	v_mfma_f32_16x16x32_bf16 v[46:49], v[154:157], v[226:229], v[46:49]
	v_mfma_f32_16x16x32_bf16 v[2:5], v[150:153], v[198:201], v[2:5]
	v_mfma_f32_16x16x32_bf16 v[6:9], v[158:161], v[198:201], v[6:9]
	v_mfma_f32_16x16x32_bf16 v[10:13], v[150:153], v[206:209], v[10:13]
	v_mfma_f32_16x16x32_bf16 v[14:17], v[158:161], v[206:209], v[14:17]
	v_mfma_f32_16x16x32_bf16 v[26:29], v[150:153], v[222:225], v[26:29]
	v_mfma_f32_16x16x32_bf16 v[30:33], v[158:161], v[222:225], v[30:33]
	v_mfma_f32_16x16x32_bf16 v[42:45], v[150:153], v[230:233], v[42:45]
	v_mfma_f32_16x16x32_bf16 v[46:49], v[158:161], v[230:233], v[46:49]
	v_mfma_f32_16x16x32_bf16 v[18:21], v[162:165], v[194:197], v[18:21]
	v_mfma_f32_16x16x32_bf16 v[22:25], v[170:173], v[194:197], v[22:25]
	v_mfma_f32_16x16x32_bf16 v[34:37], v[162:165], v[202:205], v[34:37]
	v_mfma_f32_16x16x32_bf16 v[38:41], v[170:173], v[202:205], v[38:41]
	v_mfma_f32_16x16x32_bf16 v[50:53], v[162:165], v[218:221], v[50:53]
	v_mfma_f32_16x16x32_bf16 v[54:57], v[170:173], v[218:221], v[54:57]
	v_mfma_f32_16x16x32_bf16 v[58:61], v[162:165], v[226:229], v[58:61]
	v_mfma_f32_16x16x32_bf16 v[66:69], v[170:173], v[226:229], v[66:69]
	v_mfma_f32_16x16x32_bf16 v[18:21], v[166:169], v[198:201], v[18:21]
	v_mfma_f32_16x16x32_bf16 v[22:25], v[190:193], v[198:201], v[22:25]
	v_mfma_f32_16x16x32_bf16 v[34:37], v[166:169], v[206:209], v[34:37]
	v_mfma_f32_16x16x32_bf16 v[38:41], v[190:193], v[206:209], v[38:41]
	v_mfma_f32_16x16x32_bf16 v[50:53], v[166:169], v[222:225], v[50:53]
	v_mfma_f32_16x16x32_bf16 v[54:57], v[190:193], v[222:225], v[54:57]
	v_mfma_f32_16x16x32_bf16 v[58:61], v[166:169], v[230:233], v[58:61]
	v_mfma_f32_16x16x32_bf16 v[66:69], v[190:193], v[230:233], v[66:69]
	s_barrier
	s_add_i32 s90, s90, s29
	s_add_u32 s98, s88, 0x80
	s_addc_u32 s99, s89, 0
	s_add_u32 s100, s20, 0x80
	s_addc_u32 s101, s21, 0
	s_mov_b32 m0, s90
	s_nop 0
	s_setprio 2
	global_load_lds_dwordx4 v132, s[88:89]
	s_add_i32 m0, s90, 0x2000
	s_add_i32 s90, s91, s29
	global_load_lds_dwordx4 v136, s[88:89]
	s_add_u32 s88, s88, s8
	s_addc_u32 s89, s89, 0
	s_mov_b32 m0, s90
	s_nop 0
	global_load_lds_dwordx4 v132, s[88:89]
	s_add_i32 m0, s90, 0x2000
	s_nop 0
	global_load_lds_dwordx4 v136, s[88:89]
	s_mov_b32 m0, s30
	s_nop 0
	global_load_lds_dwordx4 v130, s[20:21]
	s_mov_b32 m0, s31
	s_nop 0
	global_load_lds_dwordx4 v134, s[20:21]
	s_setprio 0
	ds_read_b128 v[194:197], v144 offset:16384
	ds_read_b128 v[198:201], v144 offset:17408
	ds_read_b128 v[202:205], v144 offset:18432
	ds_read_b128 v[206:209], v144 offset:19456
	ds_read_b128 v[218:221], v144 offset:20480
	ds_read_b128 v[222:225], v144 offset:21504
	ds_read_b128 v[226:229], v144 offset:22528
	ds_read_b128 v[230:233], v144 offset:23552
	s_waitcnt vmcnt(8)
	s_waitcnt lgkmcnt(0)
	s_barrier
	s_waitcnt lgkmcnt(0)
	v_mfma_f32_16x16x32_bf16 v[62:65], v[146:149], v[194:197], v[62:65]
	v_mfma_f32_16x16x32_bf16 v[70:73], v[154:157], v[194:197], v[70:73]
	v_mfma_f32_16x16x32_bf16 v[78:81], v[146:149], v[202:205], v[78:81]
	v_mfma_f32_16x16x32_bf16 v[82:85], v[154:157], v[202:205], v[82:85]
	v_mfma_f32_16x16x32_bf16 v[90:93], v[146:149], v[218:221], v[90:93]
	v_mfma_f32_16x16x32_bf16 v[94:97], v[154:157], v[218:221], v[94:97]
	v_mfma_f32_16x16x32_bf16 v[106:109], v[146:149], v[226:229], v[106:109]
	v_mfma_f32_16x16x32_bf16 v[110:113], v[154:157], v[226:229], v[110:113]
	v_mfma_f32_16x16x32_bf16 v[62:65], v[150:153], v[198:201], v[62:65]
	v_mfma_f32_16x16x32_bf16 v[70:73], v[158:161], v[198:201], v[70:73]
	v_mfma_f32_16x16x32_bf16 v[78:81], v[150:153], v[206:209], v[78:81]
	v_mfma_f32_16x16x32_bf16 v[82:85], v[158:161], v[206:209], v[82:85]
	v_mfma_f32_16x16x32_bf16 v[90:93], v[150:153], v[222:225], v[90:93]
	v_mfma_f32_16x16x32_bf16 v[94:97], v[158:161], v[222:225], v[94:97]
	v_mfma_f32_16x16x32_bf16 v[106:109], v[150:153], v[230:233], v[106:109]
	v_mfma_f32_16x16x32_bf16 v[110:113], v[158:161], v[230:233], v[110:113]
	v_mfma_f32_16x16x32_bf16 v[74:77], v[162:165], v[194:197], v[74:77]
	v_mfma_f32_16x16x32_bf16 v[86:89], v[170:173], v[194:197], v[86:89]
	v_mfma_f32_16x16x32_bf16 v[98:101], v[162:165], v[202:205], v[98:101]
	v_mfma_f32_16x16x32_bf16 v[102:105], v[170:173], v[202:205], v[102:105]
	v_mfma_f32_16x16x32_bf16 v[114:117], v[162:165], v[218:221], v[114:117]
	v_mfma_f32_16x16x32_bf16 v[118:121], v[170:173], v[218:221], v[118:121]
	v_mfma_f32_16x16x32_bf16 v[122:125], v[162:165], v[226:229], v[122:125]
	v_mfma_f32_16x16x32_bf16 v[126:129], v[170:173], v[226:229], v[126:129]
	v_mfma_f32_16x16x32_bf16 v[74:77], v[166:169], v[198:201], v[74:77]
	v_mfma_f32_16x16x32_bf16 v[86:89], v[190:193], v[198:201], v[86:89]
	v_mfma_f32_16x16x32_bf16 v[98:101], v[166:169], v[206:209], v[98:101]
	v_mfma_f32_16x16x32_bf16 v[102:105], v[190:193], v[206:209], v[102:105]
	v_mfma_f32_16x16x32_bf16 v[114:117], v[166:169], v[222:225], v[114:117]
	v_mfma_f32_16x16x32_bf16 v[118:121], v[190:193], v[222:225], v[118:121]
	v_mfma_f32_16x16x32_bf16 v[122:125], v[166:169], v[230:233], v[122:125]
	v_mfma_f32_16x16x32_bf16 v[126:129], v[190:193], v[230:233], v[126:129]
	s_barrier
; #define PG8_STAGE(bufoff, gbase, voff) do { _Pragma("unroll") for (int _i = 0; _i < 2; ++_i) \
;         __builtin_amdgcn_global_load_lds((const unsigned*)((const char*)(gbase) + (voff)[_i]), (LAS unsigned*)(lds + (bufoff) + ldsw + _i * 8192), 16, 0, 0); } while (0)
; #define PG8_LDA(dst, b, h) do { _Pragma("unroll") for (int m = 0; m < 4; ++m) _Pragma("unroll") for (int k = 0; k < 2; ++k) dst[m][k] = *(const LAS bf16x8*)(lds + PG8_SA(b, h) + aoff + m * 2048 + k * 1024); } while (0)
; #define PG8_LDB(dst, b, h) do { _Pragma("unroll") for (int n = 0; n < 2; ++n) _Pragma("unroll") for (int k = 0; k < 2; ++k) dst[n][k] = *(const LAS bf16x8*)(lds + PG8_SB(b, h) + boff + n * 2048 + k * 1024); } while (0)
; #define PG8_MMA(ai, bj, At, Bt) do { __builtin_amdgcn_s_setprio(1); _Pragma("unroll") for (int m = 0; m < 4; ++m) _Pragma("unroll") for (int n = 0; n < 2; ++n) _Pragma("unroll") for (int k = 0; k < 2; ++k) \
;         acc[ai][bj][m][n] = __builtin_amdgcn_mfma_f32_16x16x32_bf16(Bt[n][k], At[m][k], acc[ai][bj][m][n], 0, 0, 0); __builtin_amdgcn_s_setprio(0); } while (0)
; #define PG8_WAIT_V(n) asm volatile("s_waitcnt vmcnt(" #n ")" ::: "memory")
; #define PG8_BAR __builtin_amdgcn_s_barrier()
; template <class Epi, class Sched>
; __device__ __forceinline__ void gemm_phase(LAS unsigned char* lds, const Gemm g, const Sched& S, const Epi& E) {
;     ...
;             PG8_LDB(B0, 0, 0); PG8_LDB(B1, 0, 1); PG8_SCHED; PG8_LDA(At, 0, 0); PG8_STAGE(PG8_SA(1, 1), a1 + hstepA, voffA);
;             PG8_WAIT_V(8); PG8_WAIT_L(0); PG8_BAR; PG8_MMA(0, 0, At, B0); PG8_MMA(0, 1, At, B1); PG8_BAR; PG8_SCHED;
;             PG8_LDA(At, 0, 1); PG8_STAGE(PG8_SB(0, 0), b2, voffB); PG8_STAGE(PG8_SB(0, 1), b2 + hstepB, voffB); PG8_STAGE(PG8_SA(0, 0), a2, voffA);
;             PG8_WAIT_V(8); PG8_WAIT_L(0); PG8_BAR; PG8_MMA(1, 0, At, B0); PG8_MMA(1, 1, At, B1); PG8_BAR; PG8_SCHED;
;             PG8_LDB(B0, 1, 0); PG8_LDB(B1, 1, 1); PG8_SCHED; PG8_LDA(At, 1, 0); PG8_STAGE(PG8_SA(0, 1), a2 + hstepA, voffA);
;             PG8_WAIT_V(8); PG8_WAIT_L(0); PG8_BAR; PG8_MMA(0, 0, At, B0); PG8_MMA(0, 1, At, B1); PG8_BAR; PG8_SCHED;
;             PG8_LDA(At, 1, 1); PG8_STAGE(PG8_SB(1, 0), b3, voffB); PG8_STAGE(PG8_SB(1, 1), b3 + hstepB, voffB); PG8_STAGE(PG8_SA(1, 0), a3, voffA);
;             PG8_WAIT_V(8); PG8_WAIT_L(0); PG8_BAR; PG8_MMA(1, 0, At, B0); PG8_MMA(1, 1, At, B1); PG8_BAR; PG8_SCHED;
	s_add_u32 s20, s20, s54
	s_addc_u32 s21, s21, 0
	s_mov_b32 m0, s34
	s_nop 0
	s_setprio 2
	global_load_lds_dwordx4 v130, s[20:21]
	s_mov_b32 m0, s35
	s_nop 0
	global_load_lds_dwordx4 v134, s[20:21]
	s_setprio 0
	ds_read_b128 v[146:149], v255 offset:32768
	ds_read_b128 v[150:153], v255 offset:33792
	ds_read_b128 v[154:157], v255 offset:34816
	ds_read_b128 v[158:161], v255 offset:35840
	ds_read_b128 v[162:165], v255 offset:49152
	ds_read_b128 v[166:169], v255 offset:50176
	ds_read_b128 v[170:173], v255 offset:51200
	ds_read_b128 v[190:193], v255 offset:52224
	ds_read_b128 v[194:197], v144 offset:32768
	ds_read_b128 v[198:201], v144 offset:33792
	ds_read_b128 v[202:205], v144 offset:34816
	ds_read_b128 v[206:209], v144 offset:35840
	ds_read_b128 v[218:221], v144 offset:36864
	ds_read_b128 v[222:225], v144 offset:37888
	ds_read_b128 v[226:229], v144 offset:38912
	ds_read_b128 v[230:233], v144 offset:39936
	s_waitcnt vmcnt(8)
	s_waitcnt lgkmcnt(0)
	s_barrier
	s_waitcnt lgkmcnt(0)
	v_mfma_f32_16x16x32_bf16 v[2:5], v[146:149], v[194:197], v[2:5]
	v_mfma_f32_16x16x32_bf16 v[6:9], v[154:157], v[194:197], v[6:9]
	v_mfma_f32_16x16x32_bf16 v[10:13], v[146:149], v[202:205], v[10:13]
	v_mfma_f32_16x16x32_bf16 v[14:17], v[154:157], v[202:205], v[14:17]
	v_mfma_f32_16x16x32_bf16 v[26:29], v[146:149], v[218:221], v[26:29]
	v_mfma_f32_16x16x32_bf16 v[30:33], v[154:157], v[218:221], v[30:33]
	v_mfma_f32_16x16x32_bf16 v[42:45], v[146:149], v[226:229], v[42:45]
	v_mfma_f32_16x16x32_bf16 v[46:49], v[154:157], v[226:229], v[46:49]
	v_mfma_f32_16x16x32_bf16 v[2:5], v[150:153], v[198:201], v[2:5]
	v_mfma_f32_16x16x32_bf16 v[6:9], v[158:161], v[198:201], v[6:9]
	v_mfma_f32_16x16x32_bf16 v[10:13], v[150:153], v[206:209], v[10:13]
	v_mfma_f32_16x16x32_bf16 v[14:17], v[158:161], v[206:209], v[14:17]
	v_mfma_f32_16x16x32_bf16 v[26:29], v[150:153], v[222:225], v[26:29]
	v_mfma_f32_16x16x32_bf16 v[30:33], v[158:161], v[222:225], v[30:33]
	v_mfma_f32_16x16x32_bf16 v[42:45], v[150:153], v[230:233], v[42:45]
	v_mfma_f32_16x16x32_bf16 v[46:49], v[158:161], v[230:233], v[46:49]
	v_mfma_f32_16x16x32_bf16 v[18:21], v[162:165], v[194:197], v[18:21]
	v_mfma_f32_16x16x32_bf16 v[22:25], v[170:173], v[194:197], v[22:25]
	v_mfma_f32_16x16x32_bf16 v[34:37], v[162:165], v[202:205], v[34:37]
	v_mfma_f32_16x16x32_bf16 v[38:41], v[170:173], v[202:205], v[38:41]
	v_mfma_f32_16x16x32_bf16 v[50:53], v[162:165], v[218:221], v[50:53]
	v_mfma_f32_16x16x32_bf16 v[54:57], v[170:173], v[218:221], v[54:57]
	v_mfma_f32_16x16x32_bf16 v[58:61], v[162:165], v[226:229], v[58:61]
	v_mfma_f32_16x16x32_bf16 v[66:69], v[170:173], v[226:229], v[66:69]
	v_mfma_f32_16x16x32_bf16 v[18:21], v[166:169], v[198:201], v[18:21]
	v_mfma_f32_16x16x32_bf16 v[22:25], v[190:193], v[198:201], v[22:25]
	v_mfma_f32_16x16x32_bf16 v[34:37], v[166:169], v[206:209], v[34:37]
	v_mfma_f32_16x16x32_bf16 v[38:41], v[190:193], v[206:209], v[38:41]
	v_mfma_f32_16x16x32_bf16 v[50:53], v[166:169], v[222:225], v[50:53]
	v_mfma_f32_16x16x32_bf16 v[54:57], v[190:193], v[222:225], v[54:57]
	v_mfma_f32_16x16x32_bf16 v[58:61], v[166:169], v[230:233], v[58:61]
	v_mfma_f32_16x16x32_bf16 v[66:69], v[190:193], v[230:233], v[66:69]
	s_barrier
	s_add_i32 s20, s29, 0x18000
	s_mov_b32 m0, s20
	s_nop 0
	s_setprio 2
	global_load_lds_dwordx4 v132, s[98:99]
	s_add_i32 m0, s20, 0x2000
	s_add_i32 s20, s29, 0x1c000
	global_load_lds_dwordx4 v136, s[98:99]
	s_add_u32 s98, s98, s8
	s_addc_u32 s99, s99, 0
	s_mov_b32 m0, s20
	s_nop 0
	global_load_lds_dwordx4 v132, s[98:99]
	s_add_i32 m0, s20, 0x2000
	s_nop 0
	global_load_lds_dwordx4 v136, s[98:99]
	s_mov_b32 m0, s40
	s_nop 0
	global_load_lds_dwordx4 v130, s[100:101]
	s_mov_b32 m0, s41
	s_nop 0
	global_load_lds_dwordx4 v134, s[100:101]
	s_setprio 0
	ds_read_b128 v[194:197], v144 offset:49152
	ds_read_b128 v[198:201], v144 offset:50176
	ds_read_b128 v[202:205], v144 offset:51200
	ds_read_b128 v[206:209], v144 offset:52224
	ds_read_b128 v[218:221], v144 offset:53248
	ds_read_b128 v[222:225], v144 offset:54272
	ds_read_b128 v[226:229], v144 offset:55296
	ds_read_b128 v[230:233], v144 offset:56320
	s_waitcnt vmcnt(8)
	s_waitcnt lgkmcnt(0)
	s_barrier
	s_waitcnt lgkmcnt(0)
	v_mfma_f32_16x16x32_bf16 v[62:65], v[146:149], v[194:197], v[62:65]
	v_mfma_f32_16x16x32_bf16 v[70:73], v[154:157], v[194:197], v[70:73]
	v_mfma_f32_16x16x32_bf16 v[78:81], v[146:149], v[202:205], v[78:81]
	v_mfma_f32_16x16x32_bf16 v[82:85], v[154:157], v[202:205], v[82:85]
	v_mfma_f32_16x16x32_bf16 v[90:93], v[146:149], v[218:221], v[90:93]
	v_mfma_f32_16x16x32_bf16 v[94:97], v[154:157], v[218:221], v[94:97]
	v_mfma_f32_16x16x32_bf16 v[106:109], v[146:149], v[226:229], v[106:109]
	v_mfma_f32_16x16x32_bf16 v[110:113], v[154:157], v[226:229], v[110:113]
	v_mfma_f32_16x16x32_bf16 v[62:65], v[150:153], v[198:201], v[62:65]
	v_mfma_f32_16x16x32_bf16 v[70:73], v[158:161], v[198:201], v[70:73]
	v_mfma_f32_16x16x32_bf16 v[78:81], v[150:153], v[206:209], v[78:81]
	v_mfma_f32_16x16x32_bf16 v[82:85], v[158:161], v[206:209], v[82:85]
	v_mfma_f32_16x16x32_bf16 v[90:93], v[150:153], v[222:225], v[90:93]
	v_mfma_f32_16x16x32_bf16 v[94:97], v[158:161], v[222:225], v[94:97]
	v_mfma_f32_16x16x32_bf16 v[106:109], v[150:153], v[230:233], v[106:109]
	v_mfma_f32_16x16x32_bf16 v[110:113], v[158:161], v[230:233], v[110:113]
	v_mfma_f32_16x16x32_bf16 v[74:77], v[162:165], v[194:197], v[74:77]
	v_mfma_f32_16x16x32_bf16 v[86:89], v[170:173], v[194:197], v[86:89]
	v_mfma_f32_16x16x32_bf16 v[98:101], v[162:165], v[202:205], v[98:101]
	v_mfma_f32_16x16x32_bf16 v[102:105], v[170:173], v[202:205], v[102:105]
	v_mfma_f32_16x16x32_bf16 v[114:117], v[162:165], v[218:221], v[114:117]
	v_mfma_f32_16x16x32_bf16 v[118:121], v[170:173], v[218:221], v[118:121]
	v_mfma_f32_16x16x32_bf16 v[122:125], v[162:165], v[226:229], v[122:125]
	v_mfma_f32_16x16x32_bf16 v[126:129], v[170:173], v[226:229], v[126:129]
	v_mfma_f32_16x16x32_bf16 v[74:77], v[166:169], v[198:201], v[74:77]
	v_mfma_f32_16x16x32_bf16 v[86:89], v[190:193], v[198:201], v[86:89]
	v_mfma_f32_16x16x32_bf16 v[98:101], v[166:169], v[206:209], v[98:101]
	v_mfma_f32_16x16x32_bf16 v[102:105], v[190:193], v[206:209], v[102:105]
	v_mfma_f32_16x16x32_bf16 v[114:117], v[166:169], v[222:225], v[114:117]
	v_mfma_f32_16x16x32_bf16 v[118:121], v[190:193], v[222:225], v[118:121]
	v_mfma_f32_16x16x32_bf16 v[122:125], v[166:169], v[230:233], v[122:125]
	v_mfma_f32_16x16x32_bf16 v[126:129], v[190:193], v[230:233], v[126:129]
	s_barrier
	s_add_u32 s18, s18, 0x100
	s_addc_u32 s19, s19, 0
	s_add_u32 s82, s82, 0x100
	s_addc_u32 s83, s83, 0
	s_cmp_ge_u32 s87, s42
	s_mov_b32 s20, s87
	s_cbranch_scc0 .LBB0_640
	s_and_b64 vcc, exec, s[70:71]
	s_cbranch_vccz .LBB0_643
	s_barrier
